# GEMM K-loops rewritten: LDS-DMA 3-slot ring + fragment double buffering; hand-written WO/DOWN epilogues with prefetched loads; NSA sel/win vmcnt wait moved to barrier
# speedup vs baseline: 1.0364x; 1.0364x over previous
.LBB0_13:
	s_lshr_b32 s13, s12, 4
	s_and_b32 s13, s13, 24
	s_and_b32 s14, s12, 7
	s_or_b32 s13, s13, s14
	s_lshl_b32 s13, s13, 10
	v_mov_b32 v8, v198
	s_or_b32 s14, s13, s65
	v_ashrrev_i32_e32 v12, 2, v8
	v_add_u32_e32 v0, s14, v12
	v_ashrrev_i32_e32 v1, 31, v0
	v_readlane_b32 s16, v253, 21
	s_lshl_b32 s15, s12, 5
	v_lshlrev_b64 v[0:1], 11, v[0:1]
	v_readlane_b32 s17, v253, 22
	v_lshlrev_b32_e32 v2, 4, v8
	s_and_b32 s13, s15, 0xf00
	v_lshl_add_u64 v[0:1], s[16:17], 0, v[0:1]
	v_and_b32_e32 v152, 48, v2
	v_lshl_add_u64 v[14:15], v[0:1], 0, v[152:153]
	v_add_u32_e32 v0, s13, v12
	v_ashrrev_i32_e32 v1, 31, v0
	v_lshlrev_b64 v[0:1], 11, v[0:1]
	v_lshl_add_u64 v[0:1], s[4:5], 0, v[0:1]
	v_add_co_u32_e32 v54, vcc, s62, v14
	v_lshl_add_u64 v[0:1], v[0:1], 0, v[152:153]
	s_nop 0
	v_addc_co_u32_e32 v55, vcc, 0, v15, vcc
	s_lshl_b32 s16, s11, 11
	s_lshl_b32 s17, s12, 6
	s_and_b32 s18, s10, 7
	v_add_co_u32_e32 v2, vcc, s62, v0
	s_and_b32 s16, s16, 0x780000
	s_and_b32 s19, s17, 0x6000
	s_lshl_b32 s18, s18, 10
	v_lshrrev_b32_e32 v6, 2, v8
	v_addc_co_u32_e32 v3, vcc, 0, v1, vcc
	v_and_b32_e32 v6, 12, v6
	v_ashrrev_i32_e32 v13, 31, v12
	s_movk_i32 s17, 0x1230
	s_add_u32 s16, s7, s16
	v_add_co_u32_e32 v4, vcc, s33, v0
	v_lshrrev_b32_e64 v10, v6, s17
	v_lshlrev_b64 v[6:7], 11, v[12:13]
	s_addc_u32 s17, s8, 0
	s_or_b32 s18, s18, s19
	v_addc_co_u32_e32 v5, vcc, 0, v1, vcc
	v_and_b32_e32 v22, 3, v8
	v_xor_b32_e32 v8, v10, v8
	v_lshl_add_u64 v[156:157], s[16:17], 0, v[6:7]
	s_or_b32 s16, s18, s65
	v_add_co_u32_e32 v20, vcc, s72, v0
	v_lshlrev_b32_e32 v9, 6, v12
	v_lshlrev_b32_e32 v8, 4, v8
	v_add_u32_e32 v12, s16, v12
	v_addc_co_u32_e32 v21, vcc, 0, v1, vcc
	s_nop 0
	v_readfirstlane_b32 s26, v14
	v_readfirstlane_b32 s27, v15
	v_readfirstlane_b32 s28, v0
	v_readfirstlane_b32 s29, v1
	v_lshrrev_b32_e32 v250, 6, v198
	s_nop 0
	v_readfirstlane_b32 s24, v250
	s_lshl_b32 s24, s24, 10
	v_lshrrev_b32_e32 v250, 2, v200
	v_lshrrev_b32_e32 v251, 4, v200
	v_lshlrev_b32_e32 v251, 2, v251
	v_mov_b32_e32 v248, 0x1230
	v_lshrrev_b32_e32 v251, v251, v248
	v_xor_b32_e32 v251, v251, v200
	v_and_b32_e32 v251, 3, v251
	v_lshlrev_b32_e32 v251, 4, v251
	v_lshl_add_u32 v244, v250, 11, v251
	v_add_u32_e32 v245, 0x20000, v244
	v_add_u32_e32 v246, 0x40000, v244
	v_add_u32_e32 v247, 0x60000, v244
	s_mov_b32 s25, 0
	s_add_u32 m0, s25, s24
	s_nop 0
	global_load_lds_dwordx4 v244, s[26:27]
	s_add_u32 m0, m0, 0x1000
	s_nop 0
	global_load_lds_dwordx4 v245, s[26:27]
	s_add_u32 m0, m0, 0x1000
	s_nop 0
	global_load_lds_dwordx4 v244, s[28:29]
	s_add_u32 m0, m0, 0x1000
	s_nop 0
	global_load_lds_dwordx4 v245, s[28:29]
	s_add_u32 m0, m0, 0x1000
	s_nop 0
	global_load_lds_dwordx4 v246, s[28:29]
	s_add_u32 m0, m0, 0x1000
	s_nop 0
	global_load_lds_dwordx4 v247, s[28:29]
	s_add_u32 s26, s26, 64
	s_addc_u32 s27, s27, 0
	s_add_u32 s28, s28, 64
	s_addc_u32 s29, s29, 0
	s_add_u32 s25, s25, 24576
	s_cmp_eq_u32 s25, 73728
	s_cselect_b32 s25, 0, s25
	s_add_u32 m0, s25, s24
	s_nop 0
	global_load_lds_dwordx4 v244, s[26:27]
	s_add_u32 m0, m0, 0x1000
	s_nop 0
	global_load_lds_dwordx4 v245, s[26:27]
	s_add_u32 m0, m0, 0x1000
	s_nop 0
	global_load_lds_dwordx4 v244, s[28:29]
	s_add_u32 m0, m0, 0x1000
	s_nop 0
	global_load_lds_dwordx4 v245, s[28:29]
	s_add_u32 m0, m0, 0x1000
	s_nop 0
	global_load_lds_dwordx4 v246, s[28:29]
	s_add_u32 m0, m0, 0x1000
	s_nop 0
	global_load_lds_dwordx4 v247, s[28:29]
	s_add_u32 s26, s26, 64
	s_addc_u32 s27, s27, 0
	s_add_u32 s28, s28, 64
	s_addc_u32 s29, s29, 0
	s_add_u32 s25, s25, 24576
	s_cmp_eq_u32 s25, 73728
	s_cselect_b32 s25, 0, s25
	s_add_u32 m0, s25, s24
	s_nop 0
	global_load_lds_dwordx4 v244, s[26:27]
	s_add_u32 m0, m0, 0x1000
	s_nop 0
	global_load_lds_dwordx4 v245, s[26:27]
	s_add_u32 m0, m0, 0x1000
	s_nop 0
	global_load_lds_dwordx4 v244, s[28:29]
	s_add_u32 m0, m0, 0x1000
	s_nop 0
	global_load_lds_dwordx4 v245, s[28:29]
	s_add_u32 m0, m0, 0x1000
	s_nop 0
	global_load_lds_dwordx4 v246, s[28:29]
	s_add_u32 m0, m0, 0x1000
	s_nop 0
	global_load_lds_dwordx4 v247, s[28:29]
	s_add_u32 s26, s26, 64
	s_addc_u32 s27, s27, 0
	s_add_u32 s28, s28, 64
	s_addc_u32 s29, s29, 0
	s_add_u32 s25, s25, 24576
	s_cmp_eq_u32 s25, 73728
	s_cselect_b32 s25, 0, s25
	v_mov_b32_e32 v24, 0
	v_mov_b32_e32 v25, v24
	v_mov_b32_e32 v26, v24
	v_mov_b32_e32 v27, v24
	v_mov_b32_e32 v28, v24
	v_mov_b32_e32 v29, v24
	v_mov_b32_e32 v84, v24
	v_mov_b32_e32 v85, v24
	v_mov_b32_e32 v86, v24
	v_mov_b32_e32 v87, v24
	v_mov_b32_e32 v88, v24
	v_mov_b32_e32 v89, v24
	v_mov_b32_e32 v90, v24
	v_mov_b32_e32 v91, v24
	v_mov_b32_e32 v92, v24
	v_mov_b32_e32 v93, v24
	v_mov_b32_e32 v94, v24
	v_mov_b32_e32 v95, v24
	v_mov_b32_e32 v96, v24
	v_mov_b32_e32 v97, v24
	v_mov_b32_e32 v98, v24
	v_mov_b32_e32 v99, v24
	v_mov_b32_e32 v54, v24
	v_mov_b32_e32 v55, v24
	v_mov_b32_e32 v100, v24
	v_mov_b32_e32 v101, v24
	v_mov_b32_e32 v30, v24
	v_mov_b32_e32 v31, v24
	v_mov_b32_e32 v32, v24
	v_mov_b32_e32 v33, v24
	v_mov_b32_e32 v34, v24
	v_mov_b32_e32 v35, v24
	v_mov_b32_e32 v36, v24
	v_mov_b32_e32 v37, v24
	v_mov_b32_e32 v38, v24
	v_mov_b32_e32 v39, v24
	v_mov_b32_e32 v40, v24
	v_mov_b32_e32 v41, v24
	v_mov_b32_e32 v42, v24
	v_mov_b32_e32 v43, v24
	v_mov_b32_e32 v44, v24
	v_mov_b32_e32 v45, v24
	v_mov_b32_e32 v46, v24
	v_mov_b32_e32 v47, v24
	v_mov_b32_e32 v48, v24
	v_mov_b32_e32 v49, v24
	v_mov_b32_e32 v50, v24
	v_mov_b32_e32 v51, v24
	v_mov_b32_e32 v52, v24
	v_mov_b32_e32 v53, v24
	v_mov_b32_e32 v102, v24
	v_mov_b32_e32 v103, v24
	v_mov_b32_e32 v104, v24
	v_mov_b32_e32 v105, v24
	v_mov_b32_e32 v106, v24
	v_mov_b32_e32 v107, v24
	v_mov_b32_e32 v116, v24
	v_mov_b32_e32 v117, v24
	v_mov_b32_e32 v118, v24
	v_mov_b32_e32 v119, v24
	v_mov_b32_e32 v128, v24
	v_mov_b32_e32 v129, v24
	v_mov_b32_e32 v130, v24
	v_mov_b32_e32 v131, v24
	v_mov_b32_e32 v108, v24
	v_mov_b32_e32 v109, v24
	v_mov_b32_e32 v110, v24
	v_mov_b32_e32 v111, v24
	v_mov_b32_e32 v112, v24
	v_mov_b32_e32 v113, v24
	v_mov_b32_e32 v114, v24
	v_mov_b32_e32 v115, v24
	v_mov_b32_e32 v120, v24
	v_mov_b32_e32 v121, v24
	v_mov_b32_e32 v122, v24
	v_mov_b32_e32 v123, v24
	v_mov_b32_e32 v124, v24
	v_mov_b32_e32 v125, v24
	v_mov_b32_e32 v126, v24
	v_mov_b32_e32 v127, v24
	v_mov_b32_e32 v64, v24
	v_mov_b32_e32 v65, v24
	v_mov_b32_e32 v66, v24
	v_mov_b32_e32 v67, v24
	v_mov_b32_e32 v68, v24
	v_mov_b32_e32 v69, v24
	v_mov_b32_e32 v70, v24
	v_mov_b32_e32 v71, v24
	v_mov_b32_e32 v80, v24
	v_mov_b32_e32 v81, v24
	v_mov_b32_e32 v82, v24
	v_mov_b32_e32 v83, v24
	v_mov_b32_e32 v56, v24
	v_mov_b32_e32 v57, v24
	v_mov_b32_e32 v58, v24
	v_mov_b32_e32 v59, v24
	v_mov_b32_e32 v132, v24
	v_mov_b32_e32 v133, v24
	v_mov_b32_e32 v134, v24
	v_mov_b32_e32 v135, v24
	v_mov_b32_e32 v136, v24
	v_mov_b32_e32 v137, v24
	v_mov_b32_e32 v138, v24
	v_mov_b32_e32 v139, v24
	v_mov_b32_e32 v140, v24
	v_mov_b32_e32 v141, v24
	v_mov_b32_e32 v142, v24
	v_mov_b32_e32 v143, v24
	v_mov_b32_e32 v144, v24
	v_mov_b32_e32 v145, v24
	v_mov_b32_e32 v146, v24
	v_mov_b32_e32 v147, v24
	v_mov_b32_e32 v76, v24
	v_mov_b32_e32 v77, v24
	v_mov_b32_e32 v78, v24
	v_mov_b32_e32 v79, v24
	v_mov_b32_e32 v72, v24
	v_mov_b32_e32 v73, v24
	v_mov_b32_e32 v74, v24
	v_mov_b32_e32 v75, v24
	v_mov_b32_e32 v60, v24
	v_mov_b32_e32 v61, v24
	v_mov_b32_e32 v62, v24
	v_mov_b32_e32 v63, v24
	v_mov_b32_e32 v148, v24
	v_mov_b32_e32 v149, v24
	v_mov_b32_e32 v150, v24
	v_mov_b32_e32 v151, v24
	s_waitcnt vmcnt(12)
	s_barrier
	s_mov_b32 s30, 0
	v_add_u32_e32 v248, s30, v155
	v_add_u32_e32 v249, s30, v160
	ds_read_b128 v[186:189], v248
	ds_read_b128 v[212:215], v249 offset:8192
	ds_read_b128 v[190:193], v248 offset:1024
	ds_read_b128 v[216:219], v249 offset:9216
	ds_read_b128 v[194:197], v248 offset:2048
	ds_read_b128 v[220:223], v249 offset:10240
	ds_read_b128 v[208:211], v248 offset:3072
	ds_read_b128 v[224:227], v249 offset:11264
	ds_read_b128 v[228:231], v249 offset:12288
	ds_read_b128 v[232:235], v249 offset:13312
	ds_read_b128 v[236:239], v249 offset:14336
	ds_read_b128 v[240:243], v249 offset:15360
	s_add_u32 s30, s30, 24576
	s_cmp_eq_u32 s30, 73728
	s_cselect_b32 s30, 0, s30
	s_waitcnt vmcnt(6)
	s_waitcnt lgkmcnt(0)
	s_barrier
	s_mov_b32 s31, 14
.Lgm0_loop:
	v_add_u32_e32 v248, s30, v155
	v_add_u32_e32 v249, s30, v160
	v_mfma_f32_16x16x32_bf16 v[128:131], v[212:215], v[186:189], v[128:131]
	ds_read_b128 v[0:3], v248
	v_mfma_f32_16x16x32_bf16 v[96:99], v[212:215], v[190:193], v[96:99]
	ds_read_b128 v[16:19], v249 offset:8192
	v_mfma_f32_16x16x32_bf16 v[108:111], v[212:215], v[194:197], v[108:111]
	ds_read_b128 v[4:7], v248 offset:1024
	v_mfma_f32_16x16x32_bf16 v[132:135], v[212:215], v[208:211], v[132:135]
	ds_read_b128 v[20:23], v249 offset:9216
	v_mfma_f32_16x16x32_bf16 v[116:119], v[216:219], v[186:189], v[116:119]
	ds_read_b128 v[8:11], v248 offset:2048
	v_mfma_f32_16x16x32_bf16 v[92:95], v[216:219], v[190:193], v[92:95]
	ds_read_b128 v[162:165], v249 offset:10240
	v_mfma_f32_16x16x32_bf16 v[112:115], v[216:219], v[194:197], v[112:115]
	ds_read_b128 v[12:15], v248 offset:3072
	v_mfma_f32_16x16x32_bf16 v[136:139], v[216:219], v[208:211], v[136:139]
	ds_read_b128 v[166:169], v249 offset:11264
	v_mfma_f32_16x16x32_bf16 v[104:107], v[220:223], v[186:189], v[104:107]
	ds_read_b128 v[170:173], v249 offset:12288
	v_mfma_f32_16x16x32_bf16 v[88:91], v[220:223], v[190:193], v[88:91]
	ds_read_b128 v[174:177], v249 offset:13312
	v_mfma_f32_16x16x32_bf16 v[120:123], v[220:223], v[194:197], v[120:123]
	ds_read_b128 v[178:181], v249 offset:14336
	v_mfma_f32_16x16x32_bf16 v[140:143], v[220:223], v[208:211], v[140:143]
	ds_read_b128 v[182:185], v249 offset:15360
	s_add_u32 m0, s25, s24
	v_mfma_f32_16x16x32_bf16 v[100:103], v[224:227], v[186:189], v[100:103]
	global_load_lds_dwordx4 v244, s[26:27]
	v_mfma_f32_16x16x32_bf16 v[84:87], v[224:227], v[190:193], v[84:87]
	v_mfma_f32_16x16x32_bf16 v[124:127], v[224:227], v[194:197], v[124:127]
	s_add_u32 m0, m0, 0x1000
	v_mfma_f32_16x16x32_bf16 v[144:147], v[224:227], v[208:211], v[144:147]
	global_load_lds_dwordx4 v245, s[26:27]
	v_mfma_f32_16x16x32_bf16 v[52:55], v[228:231], v[186:189], v[52:55]
	v_mfma_f32_16x16x32_bf16 v[36:39], v[228:231], v[190:193], v[36:39]
	s_add_u32 m0, m0, 0x1000
	v_mfma_f32_16x16x32_bf16 v[64:67], v[228:231], v[194:197], v[64:67]
	global_load_lds_dwordx4 v244, s[28:29]
	v_mfma_f32_16x16x32_bf16 v[76:79], v[228:231], v[208:211], v[76:79]
	v_mfma_f32_16x16x32_bf16 v[48:51], v[232:235], v[186:189], v[48:51]
	s_add_u32 m0, m0, 0x1000
	v_mfma_f32_16x16x32_bf16 v[32:35], v[232:235], v[190:193], v[32:35]
	global_load_lds_dwordx4 v245, s[28:29]
	v_mfma_f32_16x16x32_bf16 v[68:71], v[232:235], v[194:197], v[68:71]
	v_mfma_f32_16x16x32_bf16 v[72:75], v[232:235], v[208:211], v[72:75]
	s_add_u32 m0, m0, 0x1000
	v_mfma_f32_16x16x32_bf16 v[44:47], v[236:239], v[186:189], v[44:47]
	global_load_lds_dwordx4 v246, s[28:29]
	v_mfma_f32_16x16x32_bf16 v[28:31], v[236:239], v[190:193], v[28:31]
	v_mfma_f32_16x16x32_bf16 v[80:83], v[236:239], v[194:197], v[80:83]
	s_add_u32 m0, m0, 0x1000
	v_mfma_f32_16x16x32_bf16 v[60:63], v[236:239], v[208:211], v[60:63]
	global_load_lds_dwordx4 v247, s[28:29]
	v_mfma_f32_16x16x32_bf16 v[40:43], v[240:243], v[186:189], v[40:43]
	v_mfma_f32_16x16x32_bf16 v[24:27], v[240:243], v[190:193], v[24:27]
	v_mfma_f32_16x16x32_bf16 v[56:59], v[240:243], v[194:197], v[56:59]
	v_mfma_f32_16x16x32_bf16 v[148:151], v[240:243], v[208:211], v[148:151]
	s_add_u32 s26, s26, 64
	s_addc_u32 s27, s27, 0
	s_add_u32 s28, s28, 64
	s_addc_u32 s29, s29, 0
	s_add_u32 s25, s25, 24576
	s_cmp_eq_u32 s25, 73728
	s_cselect_b32 s25, 0, s25
	s_add_u32 s30, s30, 24576
	s_cmp_eq_u32 s30, 73728
	s_cselect_b32 s30, 0, s30
	s_waitcnt vmcnt(6)
	s_waitcnt lgkmcnt(0)
	s_barrier
	v_add_u32_e32 v248, s30, v155
	v_add_u32_e32 v249, s30, v160
	v_mfma_f32_16x16x32_bf16 v[128:131], v[16:19], v[0:3], v[128:131]
	ds_read_b128 v[186:189], v248
	v_mfma_f32_16x16x32_bf16 v[96:99], v[16:19], v[4:7], v[96:99]
	ds_read_b128 v[212:215], v249 offset:8192
	v_mfma_f32_16x16x32_bf16 v[108:111], v[16:19], v[8:11], v[108:111]
	ds_read_b128 v[190:193], v248 offset:1024
	v_mfma_f32_16x16x32_bf16 v[132:135], v[16:19], v[12:15], v[132:135]
	ds_read_b128 v[216:219], v249 offset:9216
	v_mfma_f32_16x16x32_bf16 v[116:119], v[20:23], v[0:3], v[116:119]
	ds_read_b128 v[194:197], v248 offset:2048
	v_mfma_f32_16x16x32_bf16 v[92:95], v[20:23], v[4:7], v[92:95]
	ds_read_b128 v[220:223], v249 offset:10240
	v_mfma_f32_16x16x32_bf16 v[112:115], v[20:23], v[8:11], v[112:115]
	ds_read_b128 v[208:211], v248 offset:3072
	v_mfma_f32_16x16x32_bf16 v[136:139], v[20:23], v[12:15], v[136:139]
	ds_read_b128 v[224:227], v249 offset:11264
	v_mfma_f32_16x16x32_bf16 v[104:107], v[162:165], v[0:3], v[104:107]
	ds_read_b128 v[228:231], v249 offset:12288
	v_mfma_f32_16x16x32_bf16 v[88:91], v[162:165], v[4:7], v[88:91]
	ds_read_b128 v[232:235], v249 offset:13312
	v_mfma_f32_16x16x32_bf16 v[120:123], v[162:165], v[8:11], v[120:123]
	ds_read_b128 v[236:239], v249 offset:14336
	v_mfma_f32_16x16x32_bf16 v[140:143], v[162:165], v[12:15], v[140:143]
	ds_read_b128 v[240:243], v249 offset:15360
	s_add_u32 m0, s25, s24
	v_mfma_f32_16x16x32_bf16 v[100:103], v[166:169], v[0:3], v[100:103]
	global_load_lds_dwordx4 v244, s[26:27]
	v_mfma_f32_16x16x32_bf16 v[84:87], v[166:169], v[4:7], v[84:87]
	v_mfma_f32_16x16x32_bf16 v[124:127], v[166:169], v[8:11], v[124:127]
	s_add_u32 m0, m0, 0x1000
	v_mfma_f32_16x16x32_bf16 v[144:147], v[166:169], v[12:15], v[144:147]
	global_load_lds_dwordx4 v245, s[26:27]
	v_mfma_f32_16x16x32_bf16 v[52:55], v[170:173], v[0:3], v[52:55]
	v_mfma_f32_16x16x32_bf16 v[36:39], v[170:173], v[4:7], v[36:39]
	s_add_u32 m0, m0, 0x1000
	v_mfma_f32_16x16x32_bf16 v[64:67], v[170:173], v[8:11], v[64:67]
	global_load_lds_dwordx4 v244, s[28:29]
	v_mfma_f32_16x16x32_bf16 v[76:79], v[170:173], v[12:15], v[76:79]
	v_mfma_f32_16x16x32_bf16 v[48:51], v[174:177], v[0:3], v[48:51]
	s_add_u32 m0, m0, 0x1000
	v_mfma_f32_16x16x32_bf16 v[32:35], v[174:177], v[4:7], v[32:35]
	global_load_lds_dwordx4 v245, s[28:29]
	v_mfma_f32_16x16x32_bf16 v[68:71], v[174:177], v[8:11], v[68:71]
	v_mfma_f32_16x16x32_bf16 v[72:75], v[174:177], v[12:15], v[72:75]
	s_add_u32 m0, m0, 0x1000
	v_mfma_f32_16x16x32_bf16 v[44:47], v[178:181], v[0:3], v[44:47]
	global_load_lds_dwordx4 v246, s[28:29]
	v_mfma_f32_16x16x32_bf16 v[28:31], v[178:181], v[4:7], v[28:31]
	v_mfma_f32_16x16x32_bf16 v[80:83], v[178:181], v[8:11], v[80:83]
	s_add_u32 m0, m0, 0x1000
	v_mfma_f32_16x16x32_bf16 v[60:63], v[178:181], v[12:15], v[60:63]
	global_load_lds_dwordx4 v247, s[28:29]
	v_mfma_f32_16x16x32_bf16 v[40:43], v[182:185], v[0:3], v[40:43]
	v_mfma_f32_16x16x32_bf16 v[24:27], v[182:185], v[4:7], v[24:27]
	v_mfma_f32_16x16x32_bf16 v[56:59], v[182:185], v[8:11], v[56:59]
	v_mfma_f32_16x16x32_bf16 v[148:151], v[182:185], v[12:15], v[148:151]
	s_add_u32 s26, s26, 64
	s_addc_u32 s27, s27, 0
	s_add_u32 s28, s28, 64
	s_addc_u32 s29, s29, 0
	s_add_u32 s25, s25, 24576
	s_cmp_eq_u32 s25, 73728
	s_cselect_b32 s25, 0, s25
	s_add_u32 s30, s30, 24576
	s_cmp_eq_u32 s30, 73728
	s_cselect_b32 s30, 0, s30
	s_waitcnt vmcnt(6)
	s_waitcnt lgkmcnt(0)
	s_barrier
	s_sub_u32 s31, s31, 1
	s_cmp_lg_u32 s31, 0
	s_cbranch_scc1 .Lgm0_loop
	v_add_u32_e32 v248, s30, v155
	v_add_u32_e32 v249, s30, v160
	v_mfma_f32_16x16x32_bf16 v[128:131], v[212:215], v[186:189], v[128:131]
	ds_read_b128 v[0:3], v248
	v_mfma_f32_16x16x32_bf16 v[96:99], v[212:215], v[190:193], v[96:99]
	ds_read_b128 v[16:19], v249 offset:8192
	v_mfma_f32_16x16x32_bf16 v[108:111], v[212:215], v[194:197], v[108:111]
	ds_read_b128 v[4:7], v248 offset:1024
	v_mfma_f32_16x16x32_bf16 v[132:135], v[212:215], v[208:211], v[132:135]
	ds_read_b128 v[20:23], v249 offset:9216
	v_mfma_f32_16x16x32_bf16 v[116:119], v[216:219], v[186:189], v[116:119]
	ds_read_b128 v[8:11], v248 offset:2048
	v_mfma_f32_16x16x32_bf16 v[92:95], v[216:219], v[190:193], v[92:95]
	ds_read_b128 v[162:165], v249 offset:10240
	v_mfma_f32_16x16x32_bf16 v[112:115], v[216:219], v[194:197], v[112:115]
	ds_read_b128 v[12:15], v248 offset:3072
	v_mfma_f32_16x16x32_bf16 v[136:139], v[216:219], v[208:211], v[136:139]
	ds_read_b128 v[166:169], v249 offset:11264
	v_mfma_f32_16x16x32_bf16 v[104:107], v[220:223], v[186:189], v[104:107]
	ds_read_b128 v[170:173], v249 offset:12288
	v_mfma_f32_16x16x32_bf16 v[88:91], v[220:223], v[190:193], v[88:91]
	ds_read_b128 v[174:177], v249 offset:13312
	v_mfma_f32_16x16x32_bf16 v[120:123], v[220:223], v[194:197], v[120:123]
	ds_read_b128 v[178:181], v249 offset:14336
	v_mfma_f32_16x16x32_bf16 v[140:143], v[220:223], v[208:211], v[140:143]
	ds_read_b128 v[182:185], v249 offset:15360
	s_add_u32 m0, s25, s24
	v_mfma_f32_16x16x32_bf16 v[100:103], v[224:227], v[186:189], v[100:103]
	global_load_lds_dwordx4 v244, s[26:27]
	v_mfma_f32_16x16x32_bf16 v[84:87], v[224:227], v[190:193], v[84:87]
	v_mfma_f32_16x16x32_bf16 v[124:127], v[224:227], v[194:197], v[124:127]
	s_add_u32 m0, m0, 0x1000
	v_mfma_f32_16x16x32_bf16 v[144:147], v[224:227], v[208:211], v[144:147]
	global_load_lds_dwordx4 v245, s[26:27]
	v_mfma_f32_16x16x32_bf16 v[52:55], v[228:231], v[186:189], v[52:55]
	v_mfma_f32_16x16x32_bf16 v[36:39], v[228:231], v[190:193], v[36:39]
	s_add_u32 m0, m0, 0x1000
	v_mfma_f32_16x16x32_bf16 v[64:67], v[228:231], v[194:197], v[64:67]
	global_load_lds_dwordx4 v244, s[28:29]
	v_mfma_f32_16x16x32_bf16 v[76:79], v[228:231], v[208:211], v[76:79]
	v_mfma_f32_16x16x32_bf16 v[48:51], v[232:235], v[186:189], v[48:51]
	s_add_u32 m0, m0, 0x1000
	v_mfma_f32_16x16x32_bf16 v[32:35], v[232:235], v[190:193], v[32:35]
	global_load_lds_dwordx4 v245, s[28:29]
	v_mfma_f32_16x16x32_bf16 v[68:71], v[232:235], v[194:197], v[68:71]
	v_mfma_f32_16x16x32_bf16 v[72:75], v[232:235], v[208:211], v[72:75]
	s_add_u32 m0, m0, 0x1000
	v_mfma_f32_16x16x32_bf16 v[44:47], v[236:239], v[186:189], v[44:47]
	global_load_lds_dwordx4 v246, s[28:29]
	v_mfma_f32_16x16x32_bf16 v[28:31], v[236:239], v[190:193], v[28:31]
	v_mfma_f32_16x16x32_bf16 v[80:83], v[236:239], v[194:197], v[80:83]
	s_add_u32 m0, m0, 0x1000
	v_mfma_f32_16x16x32_bf16 v[60:63], v[236:239], v[208:211], v[60:63]
	global_load_lds_dwordx4 v247, s[28:29]
	v_mfma_f32_16x16x32_bf16 v[40:43], v[240:243], v[186:189], v[40:43]
	v_mfma_f32_16x16x32_bf16 v[24:27], v[240:243], v[190:193], v[24:27]
	v_mfma_f32_16x16x32_bf16 v[56:59], v[240:243], v[194:197], v[56:59]
	v_mfma_f32_16x16x32_bf16 v[148:151], v[240:243], v[208:211], v[148:151]
	s_add_u32 s26, s26, 64
	s_addc_u32 s27, s27, 0
	s_add_u32 s28, s28, 64
	s_addc_u32 s29, s29, 0
	s_add_u32 s25, s25, 24576
	s_cmp_eq_u32 s25, 73728
	s_cselect_b32 s25, 0, s25
	s_add_u32 s30, s30, 24576
	s_cmp_eq_u32 s30, 73728
	s_cselect_b32 s30, 0, s30
	s_waitcnt vmcnt(6)
	s_waitcnt lgkmcnt(0)
	s_barrier
	v_mfma_f32_16x16x32_bf16 v[128:131], v[16:19], v[0:3], v[128:131]
	v_mfma_f32_16x16x32_bf16 v[96:99], v[16:19], v[4:7], v[96:99]
	v_mfma_f32_16x16x32_bf16 v[108:111], v[16:19], v[8:11], v[108:111]
	v_mfma_f32_16x16x32_bf16 v[132:135], v[16:19], v[12:15], v[132:135]
	v_mfma_f32_16x16x32_bf16 v[116:119], v[20:23], v[0:3], v[116:119]
	v_mfma_f32_16x16x32_bf16 v[92:95], v[20:23], v[4:7], v[92:95]
	v_mfma_f32_16x16x32_bf16 v[112:115], v[20:23], v[8:11], v[112:115]
	v_mfma_f32_16x16x32_bf16 v[136:139], v[20:23], v[12:15], v[136:139]
	v_mfma_f32_16x16x32_bf16 v[104:107], v[162:165], v[0:3], v[104:107]
	v_mfma_f32_16x16x32_bf16 v[88:91], v[162:165], v[4:7], v[88:91]
	v_mfma_f32_16x16x32_bf16 v[120:123], v[162:165], v[8:11], v[120:123]
	v_mfma_f32_16x16x32_bf16 v[140:143], v[162:165], v[12:15], v[140:143]
	v_mfma_f32_16x16x32_bf16 v[100:103], v[166:169], v[0:3], v[100:103]
	v_mfma_f32_16x16x32_bf16 v[84:87], v[166:169], v[4:7], v[84:87]
	v_mfma_f32_16x16x32_bf16 v[124:127], v[166:169], v[8:11], v[124:127]
	v_mfma_f32_16x16x32_bf16 v[144:147], v[166:169], v[12:15], v[144:147]
	v_mfma_f32_16x16x32_bf16 v[52:55], v[170:173], v[0:3], v[52:55]
	v_mfma_f32_16x16x32_bf16 v[36:39], v[170:173], v[4:7], v[36:39]
	v_mfma_f32_16x16x32_bf16 v[64:67], v[170:173], v[8:11], v[64:67]
	v_mfma_f32_16x16x32_bf16 v[76:79], v[170:173], v[12:15], v[76:79]
	v_mfma_f32_16x16x32_bf16 v[48:51], v[174:177], v[0:3], v[48:51]
	v_mfma_f32_16x16x32_bf16 v[32:35], v[174:177], v[4:7], v[32:35]
	v_mfma_f32_16x16x32_bf16 v[68:71], v[174:177], v[8:11], v[68:71]
	v_mfma_f32_16x16x32_bf16 v[72:75], v[174:177], v[12:15], v[72:75]
	v_mfma_f32_16x16x32_bf16 v[44:47], v[178:181], v[0:3], v[44:47]
	v_mfma_f32_16x16x32_bf16 v[28:31], v[178:181], v[4:7], v[28:31]
	v_mfma_f32_16x16x32_bf16 v[80:83], v[178:181], v[8:11], v[80:83]
	v_mfma_f32_16x16x32_bf16 v[60:63], v[178:181], v[12:15], v[60:63]
	v_mfma_f32_16x16x32_bf16 v[40:43], v[182:185], v[0:3], v[40:43]
	v_mfma_f32_16x16x32_bf16 v[24:27], v[182:185], v[4:7], v[24:27]
	v_mfma_f32_16x16x32_bf16 v[56:59], v[182:185], v[8:11], v[56:59]
	v_mfma_f32_16x16x32_bf16 v[148:151], v[182:185], v[12:15], v[148:151]
	s_waitcnt vmcnt(0)
	s_waitcnt lgkmcnt(0)
	s_barrier
	ds_read_b128 v[156:159], v155
	ds_read_b128 v[162:165], v155 offset:1024
	ds_read_b128 v[166:169], v155 offset:2048
	ds_read_b128 v[170:173], v155 offset:3072
	ds_read_b128 v[174:177], v160 offset:8192
	ds_read_b128 v[178:181], v160 offset:9216
	ds_read_b128 v[182:185], v160 offset:10240
	ds_read_b128 v[186:189], v160 offset:11264
	s_add_i32 s12, s12, s6
	s_waitcnt lgkmcnt(3)
	v_mfma_f32_16x16x32_bf16 v[190:193], v[174:177], v[162:165], v[96:99]
	s_add_i32 s11, s11, s9
	s_add_i32 s10, s10, s6
	s_cmpk_gt_u32 s12, 0x1ff
	s_waitcnt lgkmcnt(0)
	v_mfma_f32_16x16x32_bf16 v[194:197], v[186:189], v[162:165], v[84:87]
	v_mfma_f32_16x16x32_bf16 v[208:211], v[174:177], v[166:169], v[108:111]
	v_mfma_f32_16x16x32_bf16 v[212:215], v[182:185], v[166:169], v[120:123]
	s_nop 0
	ds_read_b128 v[84:87], v160 offset:12288
	ds_read_b128 v[96:99], v160 offset:13312
	ds_read_b128 v[108:111], v160 offset:14336
	ds_read_b128 v[120:123], v160 offset:15360
	s_waitcnt vmcnt(5)
	s_waitcnt vmcnt(3)
	s_waitcnt vmcnt(2)
	s_waitcnt vmcnt(1)
	s_waitcnt vmcnt(0)
	s_waitcnt lgkmcnt(0)
	v_mfma_f32_16x16x32_bf16 v[128:131], v[174:177], v[156:159], v[128:131]
	s_barrier
	v_mfma_f32_16x16x32_bf16 v[116:119], v[178:181], v[156:159], v[116:119]
	v_mfma_f32_16x16x32_bf16 v[104:107], v[182:185], v[156:159], v[104:107]
	v_mfma_f32_16x16x32_bf16 v[100:103], v[186:189], v[156:159], v[100:103]
	v_mfma_f32_16x16x32_bf16 v[92:95], v[178:181], v[162:165], v[92:95]
	v_mfma_f32_16x16x32_bf16 v[88:91], v[182:185], v[162:165], v[88:91]
	v_mfma_f32_16x16x32_bf16 v[112:115], v[178:181], v[166:169], v[112:115]
	v_mfma_f32_16x16x32_bf16 v[216:219], v[186:189], v[166:169], v[124:127]
	v_mfma_f32_16x16x32_bf16 v[132:135], v[174:177], v[170:173], v[132:135]
	v_mfma_f32_16x16x32_bf16 v[136:139], v[178:181], v[170:173], v[136:139]
	v_mfma_f32_16x16x32_bf16 v[140:143], v[182:185], v[170:173], v[140:143]
	v_mfma_f32_16x16x32_bf16 v[144:147], v[186:189], v[170:173], v[144:147]
	v_mfma_f32_16x16x32_bf16 v[174:177], v[84:87], v[156:159], v[52:55]
	v_mfma_f32_16x16x32_bf16 v[48:51], v[96:99], v[156:159], v[48:51]
	v_mfma_f32_16x16x32_bf16 v[178:181], v[108:111], v[156:159], v[44:47]
	v_mfma_f32_16x16x32_bf16 v[40:43], v[120:123], v[156:159], v[40:43]
	v_mfma_f32_16x16x32_bf16 v[156:159], v[84:87], v[162:165], v[36:39]
	v_mfma_f32_16x16x32_bf16 v[182:185], v[96:99], v[162:165], v[32:35]
	v_mfma_f32_16x16x32_bf16 v[28:31], v[108:111], v[162:165], v[28:31]
	v_mfma_f32_16x16x32_bf16 v[24:27], v[120:123], v[162:165], v[24:27]
	v_mfma_f32_16x16x32_bf16 v[162:165], v[84:87], v[166:169], v[64:67]
	v_mfma_f32_16x16x32_bf16 v[186:189], v[96:99], v[166:169], v[68:71]
	v_mfma_f32_16x16x32_bf16 v[220:223], v[108:111], v[166:169], v[80:83]
	v_mfma_f32_16x16x32_bf16 v[166:169], v[120:123], v[166:169], v[56:59]
	v_mfma_f32_16x16x32_bf16 v[224:227], v[84:87], v[170:173], v[76:79]
	v_mfma_f32_16x16x32_bf16 v[228:231], v[96:99], v[170:173], v[72:75]
	v_mfma_f32_16x16x32_bf16 v[232:235], v[108:111], v[170:173], v[60:63]
	v_mfma_f32_16x16x32_bf16 v[148:151], v[120:123], v[170:173], v[148:151]
	ds_read_b128 v[8:11], v155 offset:24576
	ds_read_b128 v[16:19], v155 offset:25600
	ds_read_b128 v[170:173], v155 offset:26624
	ds_read_b128 v[236:239], v155 offset:27648
	ds_read_b128 v[0:3], v160 offset:32768
	ds_read_b128 v[4:7], v160 offset:33792
	ds_read_b128 v[56:59], v160 offset:34816
	ds_read_b128 v[60:63], v160 offset:35840
	s_waitcnt lgkmcnt(3)
	v_mfma_f32_16x16x32_bf16 v[124:127], v[0:3], v[8:11], v[128:131]
	s_waitcnt lgkmcnt(2)
	v_mfma_f32_16x16x32_bf16 v[120:123], v[4:7], v[8:11], v[116:119]
	v_mfma_f32_16x16x32_bf16 v[76:79], v[4:7], v[16:19], v[92:95]
	v_mfma_f32_16x16x32_bf16 v[44:47], v[4:7], v[170:173], v[112:115]
	v_mfma_f32_16x16x32_bf16 v[20:23], v[0:3], v[236:239], v[132:135]
	v_mfma_f32_16x16x32_bf16 v[12:15], v[4:7], v[236:239], v[136:139]
	s_waitcnt lgkmcnt(1)
	v_mfma_f32_16x16x32_bf16 v[4:7], v[56:59], v[236:239], v[140:143]
	ds_read_b128 v[128:131], v160 offset:36864
	ds_read_b128 v[132:135], v160 offset:37888
	ds_read_b128 v[136:139], v160 offset:38912
	ds_read_b128 v[140:143], v160 offset:39936
	s_waitcnt lgkmcnt(0)
	s_barrier
	v_mfma_f32_16x16x32_bf16 v[96:99], v[60:63], v[8:11], v[100:103]
	v_mfma_f32_16x16x32_bf16 v[84:87], v[0:3], v[16:19], v[190:193]
	v_mfma_f32_16x16x32_bf16 v[64:67], v[60:63], v[16:19], v[194:197]
	v_mfma_f32_16x16x32_bf16 v[52:55], v[0:3], v[170:173], v[208:211]
	v_mfma_f32_16x16x32_bf16 v[32:35], v[60:63], v[170:173], v[216:219]
	v_mfma_f32_16x16x32_bf16 v[0:3], v[60:63], v[236:239], v[144:147]
	v_mfma_f32_16x16x32_bf16 v[116:119], v[128:131], v[8:11], v[174:177]
	v_mfma_f32_16x16x32_bf16 v[92:95], v[128:131], v[16:19], v[156:159]
	v_mfma_f32_16x16x32_bf16 v[80:83], v[136:139], v[16:19], v[28:31]
	v_mfma_f32_16x16x32_bf16 v[60:63], v[128:131], v[170:173], v[162:165]
	v_mfma_f32_16x16x32_bf16 v[28:31], v[128:131], v[236:239], v[224:227]
	v_mov_b32 v129, v198
	s_nop 0
	v_lshrrev_b32_e32 v130, 1, v129
	v_and_b32_e32 v128, 15, v129
	v_and_b32_e32 v130, 64, v130
	v_lshlrev_b32_e32 v131, 1, v129
	v_or3_b32 v128, v128, v130, s14
	v_lshrrev_b32_e32 v129, 2, v129
	v_mfma_f32_16x16x32_bf16 v[108:111], v[56:59], v[8:11], v[104:107]
	v_and_b32_e32 v131, 0x80, v131
	v_and_b32_e32 v129, 12, v129
	v_or3_b32 v129, v131, v129, s13
	v_mfma_f32_16x16x32_bf16 v[112:115], v[132:135], v[8:11], v[48:51]
	v_lshlrev_b32_e32 v152, 13, v128
	v_mfma_f32_16x16x32_bf16 v[104:107], v[136:139], v[8:11], v[178:181]
	v_mfma_f32_16x16x32_bf16 v[100:103], v[140:143], v[8:11], v[40:43]
	v_mfma_f32_16x16x32_bf16 v[72:75], v[140:143], v[16:19], v[24:27]
	v_mfma_f32_16x16x32_bf16 v[40:43], v[140:143], v[170:173], v[166:169]
	v_mfma_f32_16x16x32_bf16 v[8:11], v[140:143], v[236:239], v[148:151]
	v_lshlrev_b32_e32 v142, 6, v128
	v_mfma_f32_16x16x32_bf16 v[68:71], v[56:59], v[16:19], v[88:91]
	v_mfma_f32_16x16x32_bf16 v[36:39], v[56:59], v[170:173], v[212:215]
	v_mfma_f32_16x16x32_bf16 v[88:91], v[132:135], v[16:19], v[182:185]
	v_mfma_f32_16x16x32_bf16 v[56:59], v[132:135], v[170:173], v[186:189]
	v_mfma_f32_16x16x32_bf16 v[48:51], v[136:139], v[170:173], v[220:223]
	v_mfma_f32_16x16x32_bf16 v[24:27], v[132:135], v[236:239], v[228:231]
	v_mfma_f32_16x16x32_bf16 v[16:19], v[136:139], v[236:239], v[232:235]
	global_load_dwordx4 v[130:133], v142, s[94:95] offset:32
	global_load_dwordx4 v[134:137], v142, s[94:95] offset:16
	global_load_dwordx4 v[138:141], v142, s[94:95]
	s_nop 0
	global_load_dwordx4 v[142:145], v142, s[94:95] offset:48
	s_waitcnt vmcnt(2)
	v_mov_b32_e32 v148, v135
	s_waitcnt vmcnt(1)
	v_mov_b32_e32 v146, v139
	v_mov_b32_e32 v147, v140
	v_mov_b32_e32 v149, v136
	v_mov_b32_e32 v139, v141
	v_mov_b32_e32 v135, v137
	v_mov_b32_e32 v136, v131
	v_pk_add_f32 v[138:139], v[146:147], v[138:139]
	v_pk_add_f32 v[134:135], v[148:149], v[134:135]
	v_pk_add_f32 v[130:131], v[130:131], v[136:137]
	v_mov_b32_e32 v136, v133
	v_pk_add_f32 v[138:139], v[138:139], v[138:139] op_sel:[0,1] op_sel_hi:[1,0]
	v_pk_add_f32 v[134:135], v[134:135], v[134:135] op_sel:[0,1] op_sel_hi:[1,0]
	v_pk_add_f32 v[132:133], v[132:133], v[136:137]
	s_waitcnt vmcnt(0)
	v_mov_b32_e32 v139, v142
	v_mov_b32_e32 v135, v143
	v_mov_b32_e32 v131, v144
	v_mov_b32_e32 v133, v145
	v_pk_add_f32 v[134:135], v[138:139], v[134:135]
	v_pk_add_f32 v[130:131], v[130:131], v[132:133]
	s_nop 0
	v_pk_add_f32 v[130:131], v[134:135], v[130:131]
	s_nop 0
	v_add_f32_e32 v130, v130, v131
	v_fmamk_f32 v130, v130, 0x3a800000, v199
	v_cmp_gt_f32_e32 vcc, s73, v130
	v_mul_f32_e32 v131, 0x4b800000, v130
	s_nop 0
	v_cndmask_b32_e32 v130, v130, v131, vcc
	v_rsq_f32_e32 v130, v130
	s_nop 0
	v_mul_f32_e32 v131, 0x45800000, v130
	v_cndmask_b32_e32 v132, v130, v131, vcc
	v_mul_f32_e32 v124, v124, v132
	v_mul_f32_e32 v125, v125, v132
	v_mul_f32_e32 v96, v96, v132
	v_mul_f32_e32 v97, v97, v132
	v_max_f32_e32 v124, 0, v124
	v_max_f32_e32 v125, 0, v125
	v_mul_f32_e32 v126, v126, v132
	v_mul_f32_e32 v127, v127, v132
	v_max_f32_e32 v96, 0, v96
	v_max_f32_e32 v97, 0, v97
	v_mul_f32_e32 v98, v98, v132
	v_max_f32_e32 v126, 0, v126
	v_max_f32_e32 v127, 0, v127
	v_mul_f32_e32 v124, v124, v124
	v_mul_f32_e32 v125, v125, v125
	v_max_f32_e32 v98, 0, v98
	v_mul_f32_e32 v99, v99, v132
	v_mul_f32_e32 v96, v96, v96
	v_mul_f32_e32 v97, v97, v97
	v_lshl_add_u64 v[130:131], s[92:93], 0, v[152:153]
	v_cvt_pk_bf16_f32 v124, v124, v125
	v_mul_f32_e32 v125, v126, v126
	v_mul_f32_e32 v126, v127, v127
	v_lshlrev_b32_e32 v152, 1, v129
	v_max_f32_e32 v99, 0, v99
	v_cvt_pk_bf16_f32 v96, v96, v97
	v_mul_f32_e32 v97, v98, v98
	v_cvt_pk_bf16_f32 v125, v125, v126
	v_lshl_add_u64 v[126:127], v[130:131], 0, v[152:153]
	v_mul_f32_e32 v98, v99, v99
	v_cvt_pk_bf16_f32 v97, v97, v98
	global_store_dwordx2 v[126:127], v[96:97], off offset:96
	v_mul_f32_e32 v96, v116, v132
	v_mul_f32_e32 v97, v117, v132
	v_max_f32_e32 v96, 0, v96
	v_max_f32_e32 v97, 0, v97
	v_mul_f32_e32 v98, v118, v132
	v_max_f32_e32 v98, 0, v98
	v_mul_f32_e32 v99, v119, v132
	v_mul_f32_e32 v96, v96, v96
	v_mul_f32_e32 v97, v97, v97
	v_max_f32_e32 v99, 0, v99
	v_cvt_pk_bf16_f32 v96, v96, v97
	v_mul_f32_e32 v97, v98, v98
	v_mul_f32_e32 v98, v99, v99
	v_cvt_pk_bf16_f32 v97, v97, v98
	global_store_dwordx2 v[126:127], v[96:97], off offset:128
	v_mul_f32_e32 v96, v112, v132
	v_mul_f32_e32 v97, v113, v132
	v_max_f32_e32 v96, 0, v96
	v_max_f32_e32 v97, 0, v97
	v_mul_f32_e32 v98, v114, v132
	v_max_f32_e32 v98, 0, v98
	v_mul_f32_e32 v99, v115, v132
	v_mul_f32_e32 v96, v96, v96
	v_mul_f32_e32 v97, v97, v97
	v_max_f32_e32 v99, 0, v99
	v_cvt_pk_bf16_f32 v96, v96, v97
	v_mul_f32_e32 v97, v98, v98
	v_mul_f32_e32 v98, v99, v99
	v_cvt_pk_bf16_f32 v97, v97, v98
	global_store_dwordx2 v[126:127], v[96:97], off offset:160
	v_mul_f32_e32 v96, v104, v132
	v_mul_f32_e32 v97, v105, v132
	v_max_f32_e32 v96, 0, v96
	v_max_f32_e32 v97, 0, v97
	v_mul_f32_e32 v98, v106, v132
	v_max_f32_e32 v98, 0, v98
	v_mul_f32_e32 v99, v107, v132
	v_mul_f32_e32 v96, v96, v96
	v_mul_f32_e32 v97, v97, v97
	v_max_f32_e32 v99, 0, v99
	v_cvt_pk_bf16_f32 v96, v96, v97
	v_mul_f32_e32 v97, v98, v98
	v_mul_f32_e32 v98, v99, v99
	v_cvt_pk_bf16_f32 v97, v97, v98
	v_mul_f32_e32 v120, v120, v132
	v_mul_f32_e32 v121, v121, v132
	v_mul_f32_e32 v108, v108, v132
	v_mul_f32_e32 v109, v109, v132
	global_store_dwordx2 v[126:127], v[96:97], off offset:192
	v_mul_f32_e32 v96, v100, v132
	v_mul_f32_e32 v97, v101, v132
	v_max_f32_e32 v120, 0, v120
	v_max_f32_e32 v121, 0, v121
	v_mul_f32_e32 v122, v122, v132
	v_max_f32_e32 v108, 0, v108
	v_max_f32_e32 v109, 0, v109
	v_mul_f32_e32 v110, v110, v132
	v_max_f32_e32 v96, 0, v96
	v_max_f32_e32 v97, 0, v97
	v_mul_f32_e32 v98, v102, v132
	v_max_f32_e32 v122, 0, v122
	v_mul_f32_e32 v123, v123, v132
	v_mul_f32_e32 v120, v120, v120
	v_mul_f32_e32 v121, v121, v121
	v_max_f32_e32 v110, 0, v110
	v_mul_f32_e32 v111, v111, v132
	v_mul_f32_e32 v108, v108, v108
	v_mul_f32_e32 v109, v109, v109
	v_max_f32_e32 v98, 0, v98
	v_mul_f32_e32 v99, v103, v132
	v_mul_f32_e32 v96, v96, v96
	v_mul_f32_e32 v97, v97, v97
	v_max_f32_e32 v123, 0, v123
	v_cvt_pk_bf16_f32 v120, v120, v121
	v_mul_f32_e32 v121, v122, v122
	v_max_f32_e32 v111, 0, v111
	v_cvt_pk_bf16_f32 v108, v108, v109
	v_mul_f32_e32 v109, v110, v110
	v_max_f32_e32 v99, 0, v99
	v_cvt_pk_bf16_f32 v96, v96, v97
	v_mul_f32_e32 v97, v98, v98
	v_or_b32_e32 v116, 16, v128
	global_store_dwordx2 v[126:127], v[124:125], off
	v_mul_f32_e32 v122, v123, v123
	v_cvt_pk_bf16_f32 v121, v121, v122
	global_store_dwordx2 v[126:127], v[120:121], off offset:32
	v_mul_f32_e32 v110, v111, v111
	v_cvt_pk_bf16_f32 v109, v109, v110
	global_store_dwordx2 v[126:127], v[108:109], off offset:64
	v_mul_f32_e32 v98, v99, v99
	v_cvt_pk_bf16_f32 v97, v97, v98
	global_store_dwordx2 v[126:127], v[96:97], off offset:224
	v_lshlrev_b32_e32 v108, 6, v116
	global_load_dwordx4 v[96:99], v108, s[94:95] offset:32
	global_load_dwordx4 v[100:103], v108, s[94:95] offset:16
	global_load_dwordx4 v[104:107], v108, s[94:95]
	s_nop 0
	global_load_dwordx4 v[108:111], v108, s[94:95] offset:48
	s_waitcnt vmcnt(2)
	v_mov_b32_e32 v114, v101
	s_waitcnt vmcnt(1)
	v_mov_b32_e32 v112, v105
	v_mov_b32_e32 v113, v106
	v_mov_b32_e32 v115, v102
	v_mov_b32_e32 v105, v107
	v_mov_b32_e32 v101, v103
	v_mov_b32_e32 v102, v97
	v_pk_add_f32 v[104:105], v[112:113], v[104:105]
	v_pk_add_f32 v[100:101], v[114:115], v[100:101]
	v_pk_add_f32 v[96:97], v[96:97], v[102:103]
	v_mov_b32_e32 v102, v99
	v_pk_add_f32 v[104:105], v[104:105], v[104:105] op_sel:[0,1] op_sel_hi:[1,0]
	v_pk_add_f32 v[100:101], v[100:101], v[100:101] op_sel:[0,1] op_sel_hi:[1,0]
	v_pk_add_f32 v[98:99], v[98:99], v[102:103]
	s_waitcnt vmcnt(0)
	v_mov_b32_e32 v105, v108
	v_mov_b32_e32 v101, v109
	v_mov_b32_e32 v97, v110
	v_mov_b32_e32 v99, v111
	v_pk_add_f32 v[100:101], v[104:105], v[100:101]
	v_pk_add_f32 v[96:97], v[96:97], v[98:99]
	s_nop 0
	v_pk_add_f32 v[96:97], v[100:101], v[96:97]
	s_nop 0
	v_add_f32_e32 v96, v96, v97
	v_fmamk_f32 v96, v96, 0x3a800000, v199
	v_cmp_gt_f32_e32 vcc, s73, v96
	v_mul_f32_e32 v97, 0x4b800000, v96
	s_nop 0
	v_cndmask_b32_e32 v96, v96, v97, vcc
	v_rsq_f32_e32 v96, v96
	s_nop 0
	v_mul_f32_e32 v97, 0x45800000, v96
	v_cndmask_b32_e32 v98, v96, v97, vcc
	v_mul_f32_e32 v84, v84, v98
	v_mul_f32_e32 v85, v85, v98
	v_mul_f32_e32 v64, v64, v98
	v_mul_f32_e32 v65, v65, v98
	v_max_f32_e32 v84, 0, v84
	v_max_f32_e32 v85, 0, v85
	v_mul_f32_e32 v86, v86, v98
	v_mul_f32_e32 v87, v87, v98
	v_max_f32_e32 v64, 0, v64
	v_max_f32_e32 v65, 0, v65
	v_mul_f32_e32 v66, v66, v98
	v_lshlrev_b32_e32 v96, 13, v116
	v_mov_b32_e32 v97, v153
	v_max_f32_e32 v86, 0, v86
	v_max_f32_e32 v87, 0, v87
	v_mul_f32_e32 v84, v84, v84
	v_mul_f32_e32 v85, v85, v85
	v_max_f32_e32 v66, 0, v66
	v_mul_f32_e32 v67, v67, v98
	v_mul_f32_e32 v64, v64, v64
	v_mul_f32_e32 v65, v65, v65
	v_lshl_add_u64 v[96:97], s[92:93], 0, v[96:97]
	v_cvt_pk_bf16_f32 v84, v84, v85
	v_mul_f32_e32 v85, v86, v86
	v_mul_f32_e32 v86, v87, v87
	v_max_f32_e32 v67, 0, v67
	v_cvt_pk_bf16_f32 v64, v64, v65
	v_mul_f32_e32 v65, v66, v66
	v_cvt_pk_bf16_f32 v85, v85, v86
	v_lshl_add_u64 v[86:87], v[96:97], 0, v[152:153]
	v_mul_f32_e32 v66, v67, v67
	v_cvt_pk_bf16_f32 v65, v65, v66
	global_store_dwordx2 v[86:87], v[64:65], off offset:96
	v_mul_f32_e32 v64, v92, v98
	v_mul_f32_e32 v65, v93, v98
	v_max_f32_e32 v64, 0, v64
	v_max_f32_e32 v65, 0, v65
	v_mul_f32_e32 v66, v94, v98
	v_max_f32_e32 v66, 0, v66
	v_mul_f32_e32 v67, v95, v98
	v_mul_f32_e32 v64, v64, v64
	v_mul_f32_e32 v65, v65, v65
	v_max_f32_e32 v67, 0, v67
	v_cvt_pk_bf16_f32 v64, v64, v65
	v_mul_f32_e32 v65, v66, v66
	v_mul_f32_e32 v66, v67, v67
	v_cvt_pk_bf16_f32 v65, v65, v66
	global_store_dwordx2 v[86:87], v[64:65], off offset:128
	v_mul_f32_e32 v64, v88, v98
	v_mul_f32_e32 v65, v89, v98
	v_max_f32_e32 v64, 0, v64
	v_max_f32_e32 v65, 0, v65
	v_mul_f32_e32 v66, v90, v98
	v_max_f32_e32 v66, 0, v66
	v_mul_f32_e32 v67, v91, v98
	v_mul_f32_e32 v64, v64, v64
	v_mul_f32_e32 v65, v65, v65
	v_max_f32_e32 v67, 0, v67
	v_cvt_pk_bf16_f32 v64, v64, v65
	v_mul_f32_e32 v65, v66, v66
	v_mul_f32_e32 v66, v67, v67
	v_cvt_pk_bf16_f32 v65, v65, v66
	global_store_dwordx2 v[86:87], v[64:65], off offset:160
	v_mul_f32_e32 v64, v80, v98
	v_mul_f32_e32 v65, v81, v98
	v_max_f32_e32 v64, 0, v64
	v_max_f32_e32 v65, 0, v65
	v_mul_f32_e32 v66, v82, v98
	v_max_f32_e32 v66, 0, v66
	v_mul_f32_e32 v67, v83, v98
	v_mul_f32_e32 v64, v64, v64
	v_mul_f32_e32 v65, v65, v65
	v_max_f32_e32 v67, 0, v67
	v_cvt_pk_bf16_f32 v64, v64, v65
	v_mul_f32_e32 v65, v66, v66
	v_mul_f32_e32 v66, v67, v67
	v_cvt_pk_bf16_f32 v65, v65, v66
	v_mul_f32_e32 v76, v76, v98
	v_mul_f32_e32 v77, v77, v98
	v_mul_f32_e32 v68, v68, v98
	v_mul_f32_e32 v69, v69, v98
	global_store_dwordx2 v[86:87], v[64:65], off offset:192
	v_mul_f32_e32 v64, v72, v98
	v_mul_f32_e32 v65, v73, v98
	v_max_f32_e32 v76, 0, v76
	v_max_f32_e32 v77, 0, v77
	v_mul_f32_e32 v78, v78, v98
	v_max_f32_e32 v68, 0, v68
	v_max_f32_e32 v69, 0, v69
	v_mul_f32_e32 v70, v70, v98
	v_max_f32_e32 v64, 0, v64
	v_max_f32_e32 v65, 0, v65
	v_mul_f32_e32 v66, v74, v98
	v_max_f32_e32 v78, 0, v78
	v_mul_f32_e32 v79, v79, v98
	v_mul_f32_e32 v76, v76, v76
	v_mul_f32_e32 v77, v77, v77
	v_max_f32_e32 v70, 0, v70
	v_mul_f32_e32 v71, v71, v98
	v_mul_f32_e32 v68, v68, v68
	v_mul_f32_e32 v69, v69, v69
	v_max_f32_e32 v66, 0, v66
	v_mul_f32_e32 v67, v75, v98
	v_mul_f32_e32 v64, v64, v64
	v_mul_f32_e32 v65, v65, v65
	global_store_dwordx2 v[86:87], v[84:85], off
	v_max_f32_e32 v79, 0, v79
	v_cvt_pk_bf16_f32 v76, v76, v77
	v_mul_f32_e32 v77, v78, v78
	v_max_f32_e32 v71, 0, v71
	v_cvt_pk_bf16_f32 v68, v68, v69
	v_mul_f32_e32 v69, v70, v70
	v_max_f32_e32 v67, 0, v67
	v_cvt_pk_bf16_f32 v64, v64, v65
	v_mul_f32_e32 v65, v66, v66
	v_or_b32_e32 v84, 32, v128
	v_mul_f32_e32 v78, v79, v79
	v_cvt_pk_bf16_f32 v77, v77, v78
	global_store_dwordx2 v[86:87], v[76:77], off offset:32
	v_mul_f32_e32 v70, v71, v71
	v_cvt_pk_bf16_f32 v69, v69, v70
	global_store_dwordx2 v[86:87], v[68:69], off offset:64
	v_mul_f32_e32 v66, v67, v67
	v_cvt_pk_bf16_f32 v65, v65, v66
	global_store_dwordx2 v[86:87], v[64:65], off offset:224
	v_lshlrev_b32_e32 v76, 6, v84
	global_load_dwordx4 v[64:67], v76, s[94:95] offset:32
	global_load_dwordx4 v[68:71], v76, s[94:95] offset:16
	global_load_dwordx4 v[72:75], v76, s[94:95]
	s_nop 0
	global_load_dwordx4 v[76:79], v76, s[94:95] offset:48
	s_waitcnt vmcnt(2)
	v_mov_b32_e32 v82, v69
	s_waitcnt vmcnt(1)
	v_mov_b32_e32 v80, v73
	v_mov_b32_e32 v81, v74
	v_mov_b32_e32 v83, v70
	v_mov_b32_e32 v73, v75
	v_mov_b32_e32 v69, v71
	v_mov_b32_e32 v70, v65
	v_pk_add_f32 v[72:73], v[80:81], v[72:73]
	v_pk_add_f32 v[68:69], v[82:83], v[68:69]
	v_pk_add_f32 v[64:65], v[64:65], v[70:71]
	v_mov_b32_e32 v70, v67
	v_pk_add_f32 v[72:73], v[72:73], v[72:73] op_sel:[0,1] op_sel_hi:[1,0]
	v_pk_add_f32 v[68:69], v[68:69], v[68:69] op_sel:[0,1] op_sel_hi:[1,0]
	v_pk_add_f32 v[66:67], v[66:67], v[70:71]
	s_waitcnt vmcnt(0)
	v_mov_b32_e32 v73, v76
	v_mov_b32_e32 v69, v77
	v_mov_b32_e32 v65, v78
	v_mov_b32_e32 v67, v79
	v_pk_add_f32 v[68:69], v[72:73], v[68:69]
	v_pk_add_f32 v[64:65], v[64:65], v[66:67]
	s_nop 0
	v_pk_add_f32 v[64:65], v[68:69], v[64:65]
	s_nop 0
	v_add_f32_e32 v64, v64, v65
	v_fmamk_f32 v64, v64, 0x3a800000, v199
	v_cmp_gt_f32_e32 vcc, s73, v64
	v_mul_f32_e32 v65, 0x4b800000, v64
	s_nop 0
	v_cndmask_b32_e32 v64, v64, v65, vcc
	v_rsq_f32_e32 v64, v64
	s_nop 0
	v_mul_f32_e32 v65, 0x45800000, v64
	v_cndmask_b32_e32 v66, v64, v65, vcc
	v_mul_f32_e32 v52, v52, v66
	v_mul_f32_e32 v53, v53, v66
	v_mul_f32_e32 v32, v32, v66
	v_mul_f32_e32 v33, v33, v66
	v_max_f32_e32 v52, 0, v52
	v_max_f32_e32 v53, 0, v53
	v_mul_f32_e32 v54, v54, v66
	v_mul_f32_e32 v55, v55, v66
	v_max_f32_e32 v32, 0, v32
	v_max_f32_e32 v33, 0, v33
	v_mul_f32_e32 v34, v34, v66
	v_lshlrev_b32_e32 v64, 13, v84
	v_mov_b32_e32 v65, v153
	v_max_f32_e32 v54, 0, v54
	v_max_f32_e32 v55, 0, v55
	v_mul_f32_e32 v52, v52, v52
	v_mul_f32_e32 v53, v53, v53
	v_max_f32_e32 v34, 0, v34
	v_mul_f32_e32 v35, v35, v66
	v_mul_f32_e32 v32, v32, v32
	v_mul_f32_e32 v33, v33, v33
	v_lshl_add_u64 v[64:65], s[92:93], 0, v[64:65]
	v_cvt_pk_bf16_f32 v52, v52, v53
	v_mul_f32_e32 v53, v54, v54
	v_mul_f32_e32 v54, v55, v55
	v_max_f32_e32 v35, 0, v35
	v_cvt_pk_bf16_f32 v32, v32, v33
	v_mul_f32_e32 v33, v34, v34
	v_cvt_pk_bf16_f32 v53, v53, v54
	v_lshl_add_u64 v[54:55], v[64:65], 0, v[152:153]
	v_mul_f32_e32 v34, v35, v35
	v_cvt_pk_bf16_f32 v33, v33, v34
	global_store_dwordx2 v[54:55], v[32:33], off offset:96
	v_mul_f32_e32 v32, v60, v66
	v_mul_f32_e32 v33, v61, v66
	v_max_f32_e32 v32, 0, v32
	v_max_f32_e32 v33, 0, v33
	v_mul_f32_e32 v34, v62, v66
	v_max_f32_e32 v34, 0, v34
	v_mul_f32_e32 v35, v63, v66
	v_mul_f32_e32 v32, v32, v32
	v_mul_f32_e32 v33, v33, v33
	v_max_f32_e32 v35, 0, v35
	v_cvt_pk_bf16_f32 v32, v32, v33
	v_mul_f32_e32 v33, v34, v34
	v_mul_f32_e32 v34, v35, v35
	v_cvt_pk_bf16_f32 v33, v33, v34
	global_store_dwordx2 v[54:55], v[32:33], off offset:128
	v_mul_f32_e32 v32, v56, v66
	v_mul_f32_e32 v33, v57, v66
	v_max_f32_e32 v32, 0, v32
	v_max_f32_e32 v33, 0, v33
	v_mul_f32_e32 v34, v58, v66
	v_max_f32_e32 v34, 0, v34
	v_mul_f32_e32 v35, v59, v66
	v_mul_f32_e32 v32, v32, v32
	v_mul_f32_e32 v33, v33, v33
	v_max_f32_e32 v35, 0, v35
	v_cvt_pk_bf16_f32 v32, v32, v33
	v_mul_f32_e32 v33, v34, v34
	v_mul_f32_e32 v34, v35, v35
	v_cvt_pk_bf16_f32 v33, v33, v34
	global_store_dwordx2 v[54:55], v[32:33], off offset:160
	v_mul_f32_e32 v32, v48, v66
	v_mul_f32_e32 v33, v49, v66
	v_max_f32_e32 v32, 0, v32
	v_max_f32_e32 v33, 0, v33
	v_mul_f32_e32 v34, v50, v66
	v_max_f32_e32 v34, 0, v34
	v_mul_f32_e32 v35, v51, v66
	v_mul_f32_e32 v32, v32, v32
	v_mul_f32_e32 v33, v33, v33
	v_max_f32_e32 v35, 0, v35
	v_cvt_pk_bf16_f32 v32, v32, v33
	v_mul_f32_e32 v33, v34, v34
	v_mul_f32_e32 v34, v35, v35
	v_cvt_pk_bf16_f32 v33, v33, v34
	v_mul_f32_e32 v44, v44, v66
	v_mul_f32_e32 v45, v45, v66
	v_mul_f32_e32 v36, v36, v66
	v_mul_f32_e32 v37, v37, v66
	global_store_dwordx2 v[54:55], v[32:33], off offset:192
	v_mul_f32_e32 v32, v40, v66
	v_mul_f32_e32 v33, v41, v66
	v_max_f32_e32 v44, 0, v44
	v_max_f32_e32 v45, 0, v45
	v_mul_f32_e32 v46, v46, v66
	v_max_f32_e32 v36, 0, v36
	v_max_f32_e32 v37, 0, v37
	v_mul_f32_e32 v38, v38, v66
	v_max_f32_e32 v32, 0, v32
	v_max_f32_e32 v33, 0, v33
	v_mul_f32_e32 v34, v42, v66
	v_max_f32_e32 v46, 0, v46
	v_mul_f32_e32 v47, v47, v66
	v_mul_f32_e32 v44, v44, v44
	v_mul_f32_e32 v45, v45, v45
	v_max_f32_e32 v38, 0, v38
	v_mul_f32_e32 v39, v39, v66
	v_mul_f32_e32 v36, v36, v36
	v_mul_f32_e32 v37, v37, v37
	v_max_f32_e32 v34, 0, v34
	v_mul_f32_e32 v35, v43, v66
	v_mul_f32_e32 v32, v32, v32
	v_mul_f32_e32 v33, v33, v33
	global_store_dwordx2 v[54:55], v[52:53], off
	v_max_f32_e32 v47, 0, v47
	v_cvt_pk_bf16_f32 v44, v44, v45
	v_mul_f32_e32 v45, v46, v46
	v_max_f32_e32 v39, 0, v39
	v_cvt_pk_bf16_f32 v36, v36, v37
	v_mul_f32_e32 v37, v38, v38
	v_max_f32_e32 v35, 0, v35
	v_cvt_pk_bf16_f32 v32, v32, v33
	v_mul_f32_e32 v33, v34, v34
	v_or_b32_e32 v52, 48, v128
	v_mul_f32_e32 v46, v47, v47
	v_cvt_pk_bf16_f32 v45, v45, v46
	global_store_dwordx2 v[54:55], v[44:45], off offset:32
	v_mul_f32_e32 v38, v39, v39
	v_cvt_pk_bf16_f32 v37, v37, v38
	global_store_dwordx2 v[54:55], v[36:37], off offset:64
	v_mul_f32_e32 v34, v35, v35
	v_cvt_pk_bf16_f32 v33, v33, v34
	global_store_dwordx2 v[54:55], v[32:33], off offset:224
	v_lshlrev_b32_e32 v44, 6, v52
	global_load_dwordx4 v[32:35], v44, s[94:95] offset:32
	global_load_dwordx4 v[36:39], v44, s[94:95] offset:16
	global_load_dwordx4 v[40:43], v44, s[94:95]
	s_nop 0
	global_load_dwordx4 v[44:47], v44, s[94:95] offset:48
	s_waitcnt vmcnt(2)
	v_mov_b32_e32 v50, v37
	s_waitcnt vmcnt(1)
	v_mov_b32_e32 v48, v41
	v_mov_b32_e32 v49, v42
	v_mov_b32_e32 v51, v38
	v_mov_b32_e32 v41, v43
	v_mov_b32_e32 v37, v39
	v_mov_b32_e32 v38, v33
	v_pk_add_f32 v[40:41], v[48:49], v[40:41]
	v_pk_add_f32 v[36:37], v[50:51], v[36:37]
	v_pk_add_f32 v[32:33], v[32:33], v[38:39]
	v_mov_b32_e32 v38, v35
	v_pk_add_f32 v[40:41], v[40:41], v[40:41] op_sel:[0,1] op_sel_hi:[1,0]
	v_pk_add_f32 v[36:37], v[36:37], v[36:37] op_sel:[0,1] op_sel_hi:[1,0]
	v_pk_add_f32 v[34:35], v[34:35], v[38:39]
	s_waitcnt vmcnt(0)
	v_mov_b32_e32 v41, v44
	v_mov_b32_e32 v37, v45
	v_mov_b32_e32 v33, v46
	v_mov_b32_e32 v35, v47
	v_pk_add_f32 v[36:37], v[40:41], v[36:37]
	v_pk_add_f32 v[32:33], v[32:33], v[34:35]
	s_nop 0
	v_pk_add_f32 v[32:33], v[36:37], v[32:33]
	s_nop 0
	v_add_f32_e32 v32, v32, v33
	v_fmamk_f32 v32, v32, 0x3a800000, v199
	v_cmp_gt_f32_e32 vcc, s73, v32
	v_mul_f32_e32 v33, 0x4b800000, v32
	s_nop 0
	v_cndmask_b32_e32 v32, v32, v33, vcc
	v_rsq_f32_e32 v32, v32
	s_nop 0
	v_mul_f32_e32 v33, 0x45800000, v32
	v_cndmask_b32_e32 v34, v32, v33, vcc
	v_mul_f32_e32 v20, v20, v34
	v_mul_f32_e32 v21, v21, v34
	v_mul_f32_e32 v0, v0, v34
	v_mul_f32_e32 v1, v1, v34
	v_max_f32_e32 v20, 0, v20
	v_max_f32_e32 v21, 0, v21
	v_mul_f32_e32 v22, v22, v34
	v_mul_f32_e32 v23, v23, v34
	v_max_f32_e32 v0, 0, v0
	v_max_f32_e32 v1, 0, v1
	v_mul_f32_e32 v2, v2, v34
	v_lshlrev_b32_e32 v32, 13, v52
	v_mov_b32_e32 v33, v153
	v_max_f32_e32 v22, 0, v22
	v_max_f32_e32 v23, 0, v23
	v_mul_f32_e32 v20, v20, v20
	v_mul_f32_e32 v21, v21, v21
	v_max_f32_e32 v2, 0, v2
	v_mul_f32_e32 v3, v3, v34
	v_mul_f32_e32 v0, v0, v0
	v_mul_f32_e32 v1, v1, v1
	v_lshl_add_u64 v[32:33], s[92:93], 0, v[32:33]
	v_cvt_pk_bf16_f32 v20, v20, v21
	v_mul_f32_e32 v21, v22, v22
	v_mul_f32_e32 v22, v23, v23
	v_max_f32_e32 v3, 0, v3
	v_cvt_pk_bf16_f32 v0, v0, v1
	v_mul_f32_e32 v1, v2, v2
	v_cvt_pk_bf16_f32 v21, v21, v22
	v_lshl_add_u64 v[22:23], v[32:33], 0, v[152:153]
	v_mul_f32_e32 v2, v3, v3
	v_cvt_pk_bf16_f32 v1, v1, v2
	global_store_dwordx2 v[22:23], v[0:1], off offset:96
	v_mul_f32_e32 v0, v28, v34
	v_mul_f32_e32 v1, v29, v34
	v_max_f32_e32 v0, 0, v0
	v_max_f32_e32 v1, 0, v1
	v_mul_f32_e32 v2, v30, v34
	v_max_f32_e32 v2, 0, v2
	v_mul_f32_e32 v3, v31, v34
	v_mul_f32_e32 v0, v0, v0
	v_mul_f32_e32 v1, v1, v1
	v_max_f32_e32 v3, 0, v3
	v_cvt_pk_bf16_f32 v0, v0, v1
	v_mul_f32_e32 v1, v2, v2
	v_mul_f32_e32 v2, v3, v3
	v_cvt_pk_bf16_f32 v1, v1, v2
	global_store_dwordx2 v[22:23], v[0:1], off offset:128
	v_mul_f32_e32 v0, v24, v34
	v_mul_f32_e32 v1, v25, v34
	v_max_f32_e32 v0, 0, v0
	v_max_f32_e32 v1, 0, v1
	v_mul_f32_e32 v2, v26, v34
	v_max_f32_e32 v2, 0, v2
	v_mul_f32_e32 v3, v27, v34
	v_mul_f32_e32 v0, v0, v0
	v_mul_f32_e32 v1, v1, v1
	v_max_f32_e32 v3, 0, v3
	v_cvt_pk_bf16_f32 v0, v0, v1
	v_mul_f32_e32 v1, v2, v2
	v_mul_f32_e32 v2, v3, v3
	v_cvt_pk_bf16_f32 v1, v1, v2
	global_store_dwordx2 v[22:23], v[0:1], off offset:160
	v_mul_f32_e32 v0, v16, v34
	v_mul_f32_e32 v1, v17, v34
	v_max_f32_e32 v0, 0, v0
	v_max_f32_e32 v1, 0, v1
	v_mul_f32_e32 v2, v18, v34
	v_max_f32_e32 v2, 0, v2
	v_mul_f32_e32 v3, v19, v34
	v_mul_f32_e32 v0, v0, v0
	v_mul_f32_e32 v1, v1, v1
	v_max_f32_e32 v3, 0, v3
	v_cvt_pk_bf16_f32 v0, v0, v1
	v_mul_f32_e32 v1, v2, v2
	v_mul_f32_e32 v2, v3, v3
	v_cvt_pk_bf16_f32 v1, v1, v2
	v_mul_f32_e32 v12, v12, v34
	v_mul_f32_e32 v13, v13, v34
	v_mul_f32_e32 v4, v4, v34
	v_mul_f32_e32 v5, v5, v34
	global_store_dwordx2 v[22:23], v[0:1], off offset:192
	v_mul_f32_e32 v0, v8, v34
	v_mul_f32_e32 v1, v9, v34
	v_max_f32_e32 v12, 0, v12
	v_max_f32_e32 v13, 0, v13
	v_mul_f32_e32 v14, v14, v34
	v_max_f32_e32 v4, 0, v4
	v_max_f32_e32 v5, 0, v5
	v_mul_f32_e32 v6, v6, v34
	v_max_f32_e32 v0, 0, v0
	v_max_f32_e32 v1, 0, v1
	v_mul_f32_e32 v2, v10, v34
	v_max_f32_e32 v14, 0, v14
	v_mul_f32_e32 v15, v15, v34
	v_mul_f32_e32 v12, v12, v12
	v_mul_f32_e32 v13, v13, v13
	v_max_f32_e32 v6, 0, v6
	v_mul_f32_e32 v7, v7, v34
	v_mul_f32_e32 v4, v4, v4
	v_mul_f32_e32 v5, v5, v5
	v_max_f32_e32 v2, 0, v2
	v_mul_f32_e32 v3, v11, v34
	v_mul_f32_e32 v0, v0, v0
	v_mul_f32_e32 v1, v1, v1
	v_max_f32_e32 v15, 0, v15
	v_cvt_pk_bf16_f32 v12, v12, v13
	v_mul_f32_e32 v13, v14, v14
	v_max_f32_e32 v7, 0, v7
	v_cvt_pk_bf16_f32 v4, v4, v5
	v_mul_f32_e32 v5, v6, v6
	v_max_f32_e32 v3, 0, v3
	v_cvt_pk_bf16_f32 v0, v0, v1
	v_mul_f32_e32 v1, v2, v2
	global_store_dwordx2 v[22:23], v[20:21], off
	v_mul_f32_e32 v14, v15, v15
	v_cvt_pk_bf16_f32 v13, v13, v14
	global_store_dwordx2 v[22:23], v[12:13], off offset:32
	v_mul_f32_e32 v6, v7, v7
	v_cvt_pk_bf16_f32 v5, v5, v6
	global_store_dwordx2 v[22:23], v[4:5], off offset:64
	v_mul_f32_e32 v2, v3, v3
	v_cvt_pk_bf16_f32 v1, v1, v2
	global_store_dwordx2 v[22:23], v[0:1], off offset:224
	s_cbranch_scc0 .LBB0_13

.LBB0_24:
	s_lshr_b32 s10, s18, 2
	s_and_b32 s10, s10, 24
	s_and_b32 s11, s18, 7
	s_or_b32 s10, s10, s11
	s_lshl_b32 s10, s10, 10
	v_mov_b32 v8, v198
	s_or_b32 s10, s10, s65
	v_ashrrev_i32_e32 v12, 2, v8
	v_add_u32_e32 v0, s10, v12
	s_waitcnt lgkmcnt(0)
	v_ashrrev_i32_e32 v1, 31, v0
	s_lshl_b32 s11, s18, 5
	v_lshlrev_b64 v[0:1], 11, v[0:1]
	v_lshlrev_b32_e32 v2, 4, v8
	s_and_b32 s11, s11, 0x300
	v_lshl_add_u64 v[0:1], s[96:97], 0, v[0:1]
	v_and_b32_e32 v152, 48, v2
	v_lshl_add_u64 v[14:15], v[0:1], 0, v[152:153]
	v_add_u32_e32 v0, s11, v12
	v_ashrrev_i32_e32 v1, 31, v0
	v_lshlrev_b64 v[0:1], 11, v[0:1]
	v_lshl_add_u64 v[0:1], s[4:5], 0, v[0:1]
	v_add_co_u32_e32 v54, vcc, s62, v14
	v_lshl_add_u64 v[0:1], v[0:1], 0, v[152:153]
	s_nop 0
	v_addc_co_u32_e32 v55, vcc, 0, v15, vcc
	s_lshl_b32 s20, s17, 11
	s_lshl_b32 s21, s18, 8
	s_and_b32 s22, s16, 7
	v_add_co_u32_e32 v2, vcc, s62, v0
	s_and_b32 s20, s20, 0x180000
	s_and_b32 s23, s21, 0x6000
	s_lshl_b32 s22, s22, 10
	v_lshrrev_b32_e32 v6, 2, v8
	v_addc_co_u32_e32 v3, vcc, 0, v1, vcc
	v_and_b32_e32 v6, 12, v6
	v_ashrrev_i32_e32 v13, 31, v12
	s_movk_i32 s21, 0x1230
	s_add_u32 s20, s13, s20
	v_add_co_u32_e32 v4, vcc, s33, v0
	v_lshrrev_b32_e64 v10, v6, s21
	v_lshlrev_b64 v[6:7], 11, v[12:13]
	s_addc_u32 s21, s14, 0
	s_or_b32 s22, s22, s23
	v_addc_co_u32_e32 v5, vcc, 0, v1, vcc
	v_and_b32_e32 v22, 3, v8
	v_xor_b32_e32 v8, v10, v8
	v_lshl_add_u64 v[156:157], s[20:21], 0, v[6:7]
	s_or_b32 s20, s22, s65
	v_add_co_u32_e32 v20, vcc, s72, v0
	v_lshlrev_b32_e32 v9, 6, v12
	v_lshlrev_b32_e32 v8, 4, v8
	v_add_u32_e32 v12, s20, v12
	v_addc_co_u32_e32 v21, vcc, 0, v1, vcc
	s_nop 0
	v_readfirstlane_b32 s26, v14
	v_readfirstlane_b32 s27, v15
	v_readfirstlane_b32 s28, v0
	v_readfirstlane_b32 s29, v1
	v_lshrrev_b32_e32 v250, 6, v198
	s_nop 0
	v_readfirstlane_b32 s24, v250
	s_lshl_b32 s24, s24, 10
	v_lshrrev_b32_e32 v250, 2, v200
	v_lshrrev_b32_e32 v251, 4, v200
	v_lshlrev_b32_e32 v251, 2, v251
	v_mov_b32_e32 v248, 0x1230
	v_lshrrev_b32_e32 v251, v251, v248
	v_xor_b32_e32 v251, v251, v200
	v_and_b32_e32 v251, 3, v251
	v_lshlrev_b32_e32 v251, 4, v251
	v_lshl_add_u32 v244, v250, 11, v251
	v_add_u32_e32 v245, 0x20000, v244
	v_add_u32_e32 v246, 0x40000, v244
	v_add_u32_e32 v247, 0x60000, v244
	s_mov_b32 s25, 0
	s_add_u32 m0, s25, s24
	s_nop 0
	global_load_lds_dwordx4 v244, s[26:27]
	s_add_u32 m0, m0, 0x1000
	s_nop 0
	global_load_lds_dwordx4 v245, s[26:27]
	s_add_u32 m0, m0, 0x1000
	s_nop 0
	global_load_lds_dwordx4 v244, s[28:29]
	s_add_u32 m0, m0, 0x1000
	s_nop 0
	global_load_lds_dwordx4 v245, s[28:29]
	s_add_u32 m0, m0, 0x1000
	s_nop 0
	global_load_lds_dwordx4 v246, s[28:29]
	s_add_u32 m0, m0, 0x1000
	s_nop 0
	global_load_lds_dwordx4 v247, s[28:29]
	s_add_u32 s26, s26, 64
	s_addc_u32 s27, s27, 0
	s_add_u32 s28, s28, 64
	s_addc_u32 s29, s29, 0
	s_add_u32 s25, s25, 24576
	s_cmp_eq_u32 s25, 73728
	s_cselect_b32 s25, 0, s25
	s_add_u32 m0, s25, s24
	s_nop 0
	global_load_lds_dwordx4 v244, s[26:27]
	s_add_u32 m0, m0, 0x1000
	s_nop 0
	global_load_lds_dwordx4 v245, s[26:27]
	s_add_u32 m0, m0, 0x1000
	s_nop 0
	global_load_lds_dwordx4 v244, s[28:29]
	s_add_u32 m0, m0, 0x1000
	s_nop 0
	global_load_lds_dwordx4 v245, s[28:29]
	s_add_u32 m0, m0, 0x1000
	s_nop 0
	global_load_lds_dwordx4 v246, s[28:29]
	s_add_u32 m0, m0, 0x1000
	s_nop 0
	global_load_lds_dwordx4 v247, s[28:29]
	s_add_u32 s26, s26, 64
	s_addc_u32 s27, s27, 0
	s_add_u32 s28, s28, 64
	s_addc_u32 s29, s29, 0
	s_add_u32 s25, s25, 24576
	s_cmp_eq_u32 s25, 73728
	s_cselect_b32 s25, 0, s25
	s_add_u32 m0, s25, s24
	s_nop 0
	global_load_lds_dwordx4 v244, s[26:27]
	s_add_u32 m0, m0, 0x1000
	s_nop 0
	global_load_lds_dwordx4 v245, s[26:27]
	s_add_u32 m0, m0, 0x1000
	s_nop 0
	global_load_lds_dwordx4 v244, s[28:29]
	s_add_u32 m0, m0, 0x1000
	s_nop 0
	global_load_lds_dwordx4 v245, s[28:29]
	s_add_u32 m0, m0, 0x1000
	s_nop 0
	global_load_lds_dwordx4 v246, s[28:29]
	s_add_u32 m0, m0, 0x1000
	s_nop 0
	global_load_lds_dwordx4 v247, s[28:29]
	s_add_u32 s26, s26, 64
	s_addc_u32 s27, s27, 0
	s_add_u32 s28, s28, 64
	s_addc_u32 s29, s29, 0
	s_add_u32 s25, s25, 24576
	s_cmp_eq_u32 s25, 73728
	s_cselect_b32 s25, 0, s25
	v_mov_b32_e32 v24, 0
	v_mov_b32_e32 v25, v24
	v_mov_b32_e32 v26, v24
	v_mov_b32_e32 v27, v24
	v_mov_b32_e32 v28, v24
	v_mov_b32_e32 v29, v24
	v_mov_b32_e32 v60, v24
	v_mov_b32_e32 v61, v24
	v_mov_b32_e32 v62, v24
	v_mov_b32_e32 v63, v24
	v_mov_b32_e32 v64, v24
	v_mov_b32_e32 v65, v24
	v_mov_b32_e32 v66, v24
	v_mov_b32_e32 v67, v24
	v_mov_b32_e32 v72, v24
	v_mov_b32_e32 v73, v24
	v_mov_b32_e32 v74, v24
	v_mov_b32_e32 v75, v24
	v_mov_b32_e32 v80, v24
	v_mov_b32_e32 v81, v24
	v_mov_b32_e32 v82, v24
	v_mov_b32_e32 v83, v24
	v_mov_b32_e32 v56, v24
	v_mov_b32_e32 v57, v24
	v_mov_b32_e32 v58, v24
	v_mov_b32_e32 v59, v24
	v_mov_b32_e32 v68, v24
	v_mov_b32_e32 v69, v24
	v_mov_b32_e32 v30, v24
	v_mov_b32_e32 v31, v24
	v_mov_b32_e32 v32, v24
	v_mov_b32_e32 v33, v24
	v_mov_b32_e32 v34, v24
	v_mov_b32_e32 v35, v24
	v_mov_b32_e32 v36, v24
	v_mov_b32_e32 v37, v24
	v_mov_b32_e32 v38, v24
	v_mov_b32_e32 v39, v24
	v_mov_b32_e32 v40, v24
	v_mov_b32_e32 v41, v24
	v_mov_b32_e32 v42, v24
	v_mov_b32_e32 v43, v24
	v_mov_b32_e32 v48, v24
	v_mov_b32_e32 v49, v24
	v_mov_b32_e32 v50, v24
	v_mov_b32_e32 v51, v24
	v_mov_b32_e32 v70, v24
	v_mov_b32_e32 v71, v24
	v_mov_b32_e32 v100, v24
	v_mov_b32_e32 v101, v24
	v_mov_b32_e32 v102, v24
	v_mov_b32_e32 v103, v24
	v_mov_b32_e32 v104, v24
	v_mov_b32_e32 v105, v24
	v_mov_b32_e32 v106, v24
	v_mov_b32_e32 v107, v24
	v_mov_b32_e32 v120, v24
	v_mov_b32_e32 v121, v24
	v_mov_b32_e32 v122, v24
	v_mov_b32_e32 v123, v24
	v_mov_b32_e32 v128, v24
	v_mov_b32_e32 v129, v24
	v_mov_b32_e32 v130, v24
	v_mov_b32_e32 v131, v24
	v_mov_b32_e32 v108, v24
	v_mov_b32_e32 v109, v24
	v_mov_b32_e32 v110, v24
	v_mov_b32_e32 v111, v24
	v_mov_b32_e32 v112, v24
	v_mov_b32_e32 v113, v24
	v_mov_b32_e32 v114, v24
	v_mov_b32_e32 v115, v24
	v_mov_b32_e32 v116, v24
	v_mov_b32_e32 v117, v24
	v_mov_b32_e32 v118, v24
	v_mov_b32_e32 v119, v24
	v_mov_b32_e32 v124, v24
	v_mov_b32_e32 v125, v24
	v_mov_b32_e32 v126, v24
	v_mov_b32_e32 v127, v24
	v_mov_b32_e32 v88, v24
	v_mov_b32_e32 v89, v24
	v_mov_b32_e32 v90, v24
	v_mov_b32_e32 v91, v24
	v_mov_b32_e32 v92, v24
	v_mov_b32_e32 v93, v24
	v_mov_b32_e32 v94, v24
	v_mov_b32_e32 v95, v24
	v_mov_b32_e32 v96, v24
	v_mov_b32_e32 v97, v24
	v_mov_b32_e32 v98, v24
	v_mov_b32_e32 v99, v24
	v_mov_b32_e32 v84, v24
	v_mov_b32_e32 v85, v24
	v_mov_b32_e32 v86, v24
	v_mov_b32_e32 v87, v24
	v_mov_b32_e32 v132, v24
	v_mov_b32_e32 v133, v24
	v_mov_b32_e32 v134, v24
	v_mov_b32_e32 v135, v24
	v_mov_b32_e32 v136, v24
	v_mov_b32_e32 v137, v24
	v_mov_b32_e32 v138, v24
	v_mov_b32_e32 v139, v24
	v_mov_b32_e32 v140, v24
	v_mov_b32_e32 v141, v24
	v_mov_b32_e32 v142, v24
	v_mov_b32_e32 v143, v24
	v_mov_b32_e32 v144, v24
	v_mov_b32_e32 v145, v24
	v_mov_b32_e32 v146, v24
	v_mov_b32_e32 v147, v24
	v_mov_b32_e32 v76, v24
	v_mov_b32_e32 v77, v24
	v_mov_b32_e32 v78, v24
	v_mov_b32_e32 v79, v24
	v_mov_b32_e32 v52, v24
	v_mov_b32_e32 v53, v24
	v_mov_b32_e32 v54, v24
	v_mov_b32_e32 v55, v24
	v_mov_b32_e32 v44, v24
	v_mov_b32_e32 v45, v24
	v_mov_b32_e32 v46, v24
	v_mov_b32_e32 v47, v24
	v_mov_b32_e32 v148, v24
	v_mov_b32_e32 v149, v24
	v_mov_b32_e32 v150, v24
	v_mov_b32_e32 v151, v24
	s_waitcnt vmcnt(12)
	s_barrier
	s_mov_b32 s30, 0
	v_add_u32_e32 v248, s30, v155
	v_add_u32_e32 v249, s30, v160
	ds_read_b128 v[186:189], v248
	ds_read_b128 v[212:215], v249 offset:8192
	ds_read_b128 v[190:193], v248 offset:1024
	ds_read_b128 v[216:219], v249 offset:9216
	ds_read_b128 v[194:197], v248 offset:2048
	ds_read_b128 v[220:223], v249 offset:10240
	ds_read_b128 v[208:211], v248 offset:3072
	ds_read_b128 v[224:227], v249 offset:11264
	ds_read_b128 v[228:231], v249 offset:12288
	ds_read_b128 v[232:235], v249 offset:13312
	ds_read_b128 v[236:239], v249 offset:14336
	ds_read_b128 v[240:243], v249 offset:15360
	s_add_u32 s30, s30, 24576
	s_cmp_eq_u32 s30, 73728
	s_cselect_b32 s30, 0, s30
	s_waitcnt vmcnt(6)
	s_waitcnt lgkmcnt(0)
	s_barrier
	s_mov_b32 s31, 14
.Lgm1_loop:
	v_add_u32_e32 v248, s30, v155
	v_add_u32_e32 v249, s30, v160
	v_mfma_f32_16x16x32_bf16 v[128:131], v[212:215], v[186:189], v[128:131]
	ds_read_b128 v[0:3], v248
	v_mfma_f32_16x16x32_bf16 v[80:83], v[212:215], v[190:193], v[80:83]
	ds_read_b128 v[16:19], v249 offset:8192
	v_mfma_f32_16x16x32_bf16 v[108:111], v[212:215], v[194:197], v[108:111]
	ds_read_b128 v[4:7], v248 offset:1024
	v_mfma_f32_16x16x32_bf16 v[132:135], v[212:215], v[208:211], v[132:135]
	ds_read_b128 v[20:23], v249 offset:9216
	v_mfma_f32_16x16x32_bf16 v[120:123], v[216:219], v[186:189], v[120:123]
	ds_read_b128 v[8:11], v248 offset:2048
	v_mfma_f32_16x16x32_bf16 v[72:75], v[216:219], v[190:193], v[72:75]
	ds_read_b128 v[162:165], v249 offset:10240
	v_mfma_f32_16x16x32_bf16 v[112:115], v[216:219], v[194:197], v[112:115]
	ds_read_b128 v[12:15], v248 offset:3072
	v_mfma_f32_16x16x32_bf16 v[136:139], v[216:219], v[208:211], v[136:139]
	ds_read_b128 v[166:169], v249 offset:11264
	v_mfma_f32_16x16x32_bf16 v[104:107], v[220:223], v[186:189], v[104:107]
	ds_read_b128 v[170:173], v249 offset:12288
	v_mfma_f32_16x16x32_bf16 v[64:67], v[220:223], v[190:193], v[64:67]
	ds_read_b128 v[174:177], v249 offset:13312
	v_mfma_f32_16x16x32_bf16 v[116:119], v[220:223], v[194:197], v[116:119]
	ds_read_b128 v[178:181], v249 offset:14336
	v_mfma_f32_16x16x32_bf16 v[140:143], v[220:223], v[208:211], v[140:143]
	ds_read_b128 v[182:185], v249 offset:15360
	s_add_u32 m0, s25, s24
	v_mfma_f32_16x16x32_bf16 v[100:103], v[224:227], v[186:189], v[100:103]
	global_load_lds_dwordx4 v244, s[26:27]
	v_mfma_f32_16x16x32_bf16 v[60:63], v[224:227], v[190:193], v[60:63]
	v_mfma_f32_16x16x32_bf16 v[124:127], v[224:227], v[194:197], v[124:127]
	s_add_u32 m0, m0, 0x1000
	v_mfma_f32_16x16x32_bf16 v[144:147], v[224:227], v[208:211], v[144:147]
	global_load_lds_dwordx4 v245, s[26:27]
	v_mfma_f32_16x16x32_bf16 v[68:71], v[228:231], v[186:189], v[68:71]
	v_mfma_f32_16x16x32_bf16 v[36:39], v[228:231], v[190:193], v[36:39]
	s_add_u32 m0, m0, 0x1000
	v_mfma_f32_16x16x32_bf16 v[88:91], v[228:231], v[194:197], v[88:91]
	global_load_lds_dwordx4 v244, s[28:29]
	v_mfma_f32_16x16x32_bf16 v[76:79], v[228:231], v[208:211], v[76:79]
	v_mfma_f32_16x16x32_bf16 v[56:59], v[232:235], v[186:189], v[56:59]
	s_add_u32 m0, m0, 0x1000
	v_mfma_f32_16x16x32_bf16 v[32:35], v[232:235], v[190:193], v[32:35]
	global_load_lds_dwordx4 v245, s[28:29]
	v_mfma_f32_16x16x32_bf16 v[92:95], v[232:235], v[194:197], v[92:95]
	v_mfma_f32_16x16x32_bf16 v[52:55], v[232:235], v[208:211], v[52:55]
	s_add_u32 m0, m0, 0x1000
	v_mfma_f32_16x16x32_bf16 v[48:51], v[236:239], v[186:189], v[48:51]
	global_load_lds_dwordx4 v246, s[28:29]
	v_mfma_f32_16x16x32_bf16 v[28:31], v[236:239], v[190:193], v[28:31]
	v_mfma_f32_16x16x32_bf16 v[96:99], v[236:239], v[194:197], v[96:99]
	s_add_u32 m0, m0, 0x1000
	v_mfma_f32_16x16x32_bf16 v[44:47], v[236:239], v[208:211], v[44:47]
	global_load_lds_dwordx4 v247, s[28:29]
	v_mfma_f32_16x16x32_bf16 v[40:43], v[240:243], v[186:189], v[40:43]
	v_mfma_f32_16x16x32_bf16 v[24:27], v[240:243], v[190:193], v[24:27]
	v_mfma_f32_16x16x32_bf16 v[84:87], v[240:243], v[194:197], v[84:87]
	v_mfma_f32_16x16x32_bf16 v[148:151], v[240:243], v[208:211], v[148:151]
	s_add_u32 s26, s26, 64
	s_addc_u32 s27, s27, 0
	s_add_u32 s28, s28, 64
	s_addc_u32 s29, s29, 0
	s_add_u32 s25, s25, 24576
	s_cmp_eq_u32 s25, 73728
	s_cselect_b32 s25, 0, s25
	s_add_u32 s30, s30, 24576
	s_cmp_eq_u32 s30, 73728
	s_cselect_b32 s30, 0, s30
	s_waitcnt vmcnt(6)
	s_waitcnt lgkmcnt(0)
	s_barrier
	v_add_u32_e32 v248, s30, v155
	v_add_u32_e32 v249, s30, v160
	v_mfma_f32_16x16x32_bf16 v[128:131], v[16:19], v[0:3], v[128:131]
	ds_read_b128 v[186:189], v248
	v_mfma_f32_16x16x32_bf16 v[80:83], v[16:19], v[4:7], v[80:83]
	ds_read_b128 v[212:215], v249 offset:8192
	v_mfma_f32_16x16x32_bf16 v[108:111], v[16:19], v[8:11], v[108:111]
	ds_read_b128 v[190:193], v248 offset:1024
	v_mfma_f32_16x16x32_bf16 v[132:135], v[16:19], v[12:15], v[132:135]
	ds_read_b128 v[216:219], v249 offset:9216
	v_mfma_f32_16x16x32_bf16 v[120:123], v[20:23], v[0:3], v[120:123]
	ds_read_b128 v[194:197], v248 offset:2048
	v_mfma_f32_16x16x32_bf16 v[72:75], v[20:23], v[4:7], v[72:75]
	ds_read_b128 v[220:223], v249 offset:10240
	v_mfma_f32_16x16x32_bf16 v[112:115], v[20:23], v[8:11], v[112:115]
	ds_read_b128 v[208:211], v248 offset:3072
	v_mfma_f32_16x16x32_bf16 v[136:139], v[20:23], v[12:15], v[136:139]
	ds_read_b128 v[224:227], v249 offset:11264
	v_mfma_f32_16x16x32_bf16 v[104:107], v[162:165], v[0:3], v[104:107]
	ds_read_b128 v[228:231], v249 offset:12288
	v_mfma_f32_16x16x32_bf16 v[64:67], v[162:165], v[4:7], v[64:67]
	ds_read_b128 v[232:235], v249 offset:13312
	v_mfma_f32_16x16x32_bf16 v[116:119], v[162:165], v[8:11], v[116:119]
	ds_read_b128 v[236:239], v249 offset:14336
	v_mfma_f32_16x16x32_bf16 v[140:143], v[162:165], v[12:15], v[140:143]
	ds_read_b128 v[240:243], v249 offset:15360
	s_add_u32 m0, s25, s24
	v_mfma_f32_16x16x32_bf16 v[100:103], v[166:169], v[0:3], v[100:103]
	global_load_lds_dwordx4 v244, s[26:27]
	v_mfma_f32_16x16x32_bf16 v[60:63], v[166:169], v[4:7], v[60:63]
	v_mfma_f32_16x16x32_bf16 v[124:127], v[166:169], v[8:11], v[124:127]
	s_add_u32 m0, m0, 0x1000
	v_mfma_f32_16x16x32_bf16 v[144:147], v[166:169], v[12:15], v[144:147]
	global_load_lds_dwordx4 v245, s[26:27]
	v_mfma_f32_16x16x32_bf16 v[68:71], v[170:173], v[0:3], v[68:71]
	v_mfma_f32_16x16x32_bf16 v[36:39], v[170:173], v[4:7], v[36:39]
	s_add_u32 m0, m0, 0x1000
	v_mfma_f32_16x16x32_bf16 v[88:91], v[170:173], v[8:11], v[88:91]
	global_load_lds_dwordx4 v244, s[28:29]
	v_mfma_f32_16x16x32_bf16 v[76:79], v[170:173], v[12:15], v[76:79]
	v_mfma_f32_16x16x32_bf16 v[56:59], v[174:177], v[0:3], v[56:59]
	s_add_u32 m0, m0, 0x1000
	v_mfma_f32_16x16x32_bf16 v[32:35], v[174:177], v[4:7], v[32:35]
	global_load_lds_dwordx4 v245, s[28:29]
	v_mfma_f32_16x16x32_bf16 v[92:95], v[174:177], v[8:11], v[92:95]
	v_mfma_f32_16x16x32_bf16 v[52:55], v[174:177], v[12:15], v[52:55]
	s_add_u32 m0, m0, 0x1000
	v_mfma_f32_16x16x32_bf16 v[48:51], v[178:181], v[0:3], v[48:51]
	global_load_lds_dwordx4 v246, s[28:29]
	v_mfma_f32_16x16x32_bf16 v[28:31], v[178:181], v[4:7], v[28:31]
	v_mfma_f32_16x16x32_bf16 v[96:99], v[178:181], v[8:11], v[96:99]
	s_add_u32 m0, m0, 0x1000
	v_mfma_f32_16x16x32_bf16 v[44:47], v[178:181], v[12:15], v[44:47]
	global_load_lds_dwordx4 v247, s[28:29]
	v_mfma_f32_16x16x32_bf16 v[40:43], v[182:185], v[0:3], v[40:43]
	v_mfma_f32_16x16x32_bf16 v[24:27], v[182:185], v[4:7], v[24:27]
	v_mfma_f32_16x16x32_bf16 v[84:87], v[182:185], v[8:11], v[84:87]
	v_mfma_f32_16x16x32_bf16 v[148:151], v[182:185], v[12:15], v[148:151]
	s_add_u32 s26, s26, 64
	s_addc_u32 s27, s27, 0
	s_add_u32 s28, s28, 64
	s_addc_u32 s29, s29, 0
	s_add_u32 s25, s25, 24576
	s_cmp_eq_u32 s25, 73728
	s_cselect_b32 s25, 0, s25
	s_add_u32 s30, s30, 24576
	s_cmp_eq_u32 s30, 73728
	s_cselect_b32 s30, 0, s30
	s_waitcnt vmcnt(6)
	s_waitcnt lgkmcnt(0)
	s_barrier
	s_sub_u32 s31, s31, 1
	s_cmp_lg_u32 s31, 0
	s_cbranch_scc1 .Lgm1_loop
	v_add_u32_e32 v248, s30, v155
	v_add_u32_e32 v249, s30, v160
	v_mfma_f32_16x16x32_bf16 v[128:131], v[212:215], v[186:189], v[128:131]
	ds_read_b128 v[0:3], v248
	v_mfma_f32_16x16x32_bf16 v[80:83], v[212:215], v[190:193], v[80:83]
	ds_read_b128 v[16:19], v249 offset:8192
	v_mfma_f32_16x16x32_bf16 v[108:111], v[212:215], v[194:197], v[108:111]
	ds_read_b128 v[4:7], v248 offset:1024
	v_mfma_f32_16x16x32_bf16 v[132:135], v[212:215], v[208:211], v[132:135]
	ds_read_b128 v[20:23], v249 offset:9216
	v_mfma_f32_16x16x32_bf16 v[120:123], v[216:219], v[186:189], v[120:123]
	ds_read_b128 v[8:11], v248 offset:2048
	v_mfma_f32_16x16x32_bf16 v[72:75], v[216:219], v[190:193], v[72:75]
	ds_read_b128 v[162:165], v249 offset:10240
	v_mfma_f32_16x16x32_bf16 v[112:115], v[216:219], v[194:197], v[112:115]
	ds_read_b128 v[12:15], v248 offset:3072
	v_mfma_f32_16x16x32_bf16 v[136:139], v[216:219], v[208:211], v[136:139]
	ds_read_b128 v[166:169], v249 offset:11264
	v_mfma_f32_16x16x32_bf16 v[104:107], v[220:223], v[186:189], v[104:107]
	ds_read_b128 v[170:173], v249 offset:12288
	v_mfma_f32_16x16x32_bf16 v[64:67], v[220:223], v[190:193], v[64:67]
	ds_read_b128 v[174:177], v249 offset:13312
	v_mfma_f32_16x16x32_bf16 v[116:119], v[220:223], v[194:197], v[116:119]
	ds_read_b128 v[178:181], v249 offset:14336
	v_mfma_f32_16x16x32_bf16 v[140:143], v[220:223], v[208:211], v[140:143]
	ds_read_b128 v[182:185], v249 offset:15360
	s_add_u32 m0, s25, s24
	v_mfma_f32_16x16x32_bf16 v[100:103], v[224:227], v[186:189], v[100:103]
	global_load_lds_dwordx4 v244, s[26:27]
	v_mfma_f32_16x16x32_bf16 v[60:63], v[224:227], v[190:193], v[60:63]
	v_mfma_f32_16x16x32_bf16 v[124:127], v[224:227], v[194:197], v[124:127]
	s_add_u32 m0, m0, 0x1000
	v_mfma_f32_16x16x32_bf16 v[144:147], v[224:227], v[208:211], v[144:147]
	global_load_lds_dwordx4 v245, s[26:27]
	v_mfma_f32_16x16x32_bf16 v[68:71], v[228:231], v[186:189], v[68:71]
	v_mfma_f32_16x16x32_bf16 v[36:39], v[228:231], v[190:193], v[36:39]
	s_add_u32 m0, m0, 0x1000
	v_mfma_f32_16x16x32_bf16 v[88:91], v[228:231], v[194:197], v[88:91]
	global_load_lds_dwordx4 v244, s[28:29]
	v_mfma_f32_16x16x32_bf16 v[76:79], v[228:231], v[208:211], v[76:79]
	v_mfma_f32_16x16x32_bf16 v[56:59], v[232:235], v[186:189], v[56:59]
	s_add_u32 m0, m0, 0x1000
	v_mfma_f32_16x16x32_bf16 v[32:35], v[232:235], v[190:193], v[32:35]
	global_load_lds_dwordx4 v245, s[28:29]
	v_mfma_f32_16x16x32_bf16 v[92:95], v[232:235], v[194:197], v[92:95]
	v_mfma_f32_16x16x32_bf16 v[52:55], v[232:235], v[208:211], v[52:55]
	s_add_u32 m0, m0, 0x1000
	v_mfma_f32_16x16x32_bf16 v[48:51], v[236:239], v[186:189], v[48:51]
	global_load_lds_dwordx4 v246, s[28:29]
	v_mfma_f32_16x16x32_bf16 v[28:31], v[236:239], v[190:193], v[28:31]
	v_mfma_f32_16x16x32_bf16 v[96:99], v[236:239], v[194:197], v[96:99]
	s_add_u32 m0, m0, 0x1000
	v_mfma_f32_16x16x32_bf16 v[44:47], v[236:239], v[208:211], v[44:47]
	global_load_lds_dwordx4 v247, s[28:29]
	v_mfma_f32_16x16x32_bf16 v[40:43], v[240:243], v[186:189], v[40:43]
	v_mfma_f32_16x16x32_bf16 v[24:27], v[240:243], v[190:193], v[24:27]
	v_mfma_f32_16x16x32_bf16 v[84:87], v[240:243], v[194:197], v[84:87]
	v_mfma_f32_16x16x32_bf16 v[148:151], v[240:243], v[208:211], v[148:151]
	s_add_u32 s26, s26, 64
	s_addc_u32 s27, s27, 0
	s_add_u32 s28, s28, 64
	s_addc_u32 s29, s29, 0
	s_add_u32 s25, s25, 24576
	s_cmp_eq_u32 s25, 73728
	s_cselect_b32 s25, 0, s25
	s_add_u32 s30, s30, 24576
	s_cmp_eq_u32 s30, 73728
	s_cselect_b32 s30, 0, s30
	s_waitcnt vmcnt(6)
	s_waitcnt lgkmcnt(0)
	s_barrier
	v_add_u32_e32 v248, s30, v155
	v_add_u32_e32 v249, s30, v160
	v_mfma_f32_16x16x32_bf16 v[128:131], v[16:19], v[0:3], v[128:131]
	ds_read_b128 v[186:189], v248
	v_mfma_f32_16x16x32_bf16 v[80:83], v[16:19], v[4:7], v[80:83]
	ds_read_b128 v[212:215], v249 offset:8192
	v_mfma_f32_16x16x32_bf16 v[108:111], v[16:19], v[8:11], v[108:111]
	ds_read_b128 v[190:193], v248 offset:1024
	v_mfma_f32_16x16x32_bf16 v[132:135], v[16:19], v[12:15], v[132:135]
	ds_read_b128 v[216:219], v249 offset:9216
	v_mfma_f32_16x16x32_bf16 v[120:123], v[20:23], v[0:3], v[120:123]
	ds_read_b128 v[194:197], v248 offset:2048
	v_mfma_f32_16x16x32_bf16 v[72:75], v[20:23], v[4:7], v[72:75]
	ds_read_b128 v[220:223], v249 offset:10240
	v_mfma_f32_16x16x32_bf16 v[112:115], v[20:23], v[8:11], v[112:115]
	ds_read_b128 v[208:211], v248 offset:3072
	v_mfma_f32_16x16x32_bf16 v[136:139], v[20:23], v[12:15], v[136:139]
	ds_read_b128 v[224:227], v249 offset:11264
	v_mfma_f32_16x16x32_bf16 v[104:107], v[162:165], v[0:3], v[104:107]
	ds_read_b128 v[228:231], v249 offset:12288
	v_mfma_f32_16x16x32_bf16 v[64:67], v[162:165], v[4:7], v[64:67]
	ds_read_b128 v[232:235], v249 offset:13312
	v_mfma_f32_16x16x32_bf16 v[116:119], v[162:165], v[8:11], v[116:119]
	ds_read_b128 v[236:239], v249 offset:14336
	v_mfma_f32_16x16x32_bf16 v[140:143], v[162:165], v[12:15], v[140:143]
	ds_read_b128 v[240:243], v249 offset:15360
	v_mfma_f32_16x16x32_bf16 v[100:103], v[166:169], v[0:3], v[100:103]
	v_mfma_f32_16x16x32_bf16 v[60:63], v[166:169], v[4:7], v[60:63]
	v_mfma_f32_16x16x32_bf16 v[124:127], v[166:169], v[8:11], v[124:127]
	v_mfma_f32_16x16x32_bf16 v[144:147], v[166:169], v[12:15], v[144:147]
	v_mfma_f32_16x16x32_bf16 v[68:71], v[170:173], v[0:3], v[68:71]
	v_mfma_f32_16x16x32_bf16 v[36:39], v[170:173], v[4:7], v[36:39]
	v_mfma_f32_16x16x32_bf16 v[88:91], v[170:173], v[8:11], v[88:91]
	v_mfma_f32_16x16x32_bf16 v[76:79], v[170:173], v[12:15], v[76:79]
	v_mfma_f32_16x16x32_bf16 v[56:59], v[174:177], v[0:3], v[56:59]
	v_mfma_f32_16x16x32_bf16 v[32:35], v[174:177], v[4:7], v[32:35]
	v_mfma_f32_16x16x32_bf16 v[92:95], v[174:177], v[8:11], v[92:95]
	v_mfma_f32_16x16x32_bf16 v[52:55], v[174:177], v[12:15], v[52:55]
	v_mfma_f32_16x16x32_bf16 v[48:51], v[178:181], v[0:3], v[48:51]
	v_mfma_f32_16x16x32_bf16 v[28:31], v[178:181], v[4:7], v[28:31]
	v_mfma_f32_16x16x32_bf16 v[96:99], v[178:181], v[8:11], v[96:99]
	v_mfma_f32_16x16x32_bf16 v[44:47], v[178:181], v[12:15], v[44:47]
	v_mfma_f32_16x16x32_bf16 v[40:43], v[182:185], v[0:3], v[40:43]
	v_mfma_f32_16x16x32_bf16 v[24:27], v[182:185], v[4:7], v[24:27]
	v_mfma_f32_16x16x32_bf16 v[84:87], v[182:185], v[8:11], v[84:87]
	v_mfma_f32_16x16x32_bf16 v[148:151], v[182:185], v[12:15], v[148:151]
	s_add_u32 s30, s30, 24576
	s_cmp_eq_u32 s30, 73728
	s_cselect_b32 s30, 0, s30
	s_waitcnt vmcnt(0)
	s_waitcnt lgkmcnt(0)
	s_barrier
	v_add_u32_e32 v248, s30, v155
	v_add_u32_e32 v249, s30, v160
	v_mfma_f32_16x16x32_bf16 v[128:131], v[212:215], v[186:189], v[128:131]
	ds_read_b128 v[0:3], v248
	v_mfma_f32_16x16x32_bf16 v[80:83], v[212:215], v[190:193], v[80:83]
	ds_read_b128 v[16:19], v249 offset:8192
	v_mfma_f32_16x16x32_bf16 v[108:111], v[212:215], v[194:197], v[108:111]
	ds_read_b128 v[4:7], v248 offset:1024
	v_mfma_f32_16x16x32_bf16 v[132:135], v[212:215], v[208:211], v[132:135]
	ds_read_b128 v[20:23], v249 offset:9216
	v_mfma_f32_16x16x32_bf16 v[120:123], v[216:219], v[186:189], v[120:123]
	ds_read_b128 v[8:11], v248 offset:2048
	v_mfma_f32_16x16x32_bf16 v[72:75], v[216:219], v[190:193], v[72:75]
	ds_read_b128 v[162:165], v249 offset:10240
	v_mfma_f32_16x16x32_bf16 v[112:115], v[216:219], v[194:197], v[112:115]
	ds_read_b128 v[12:15], v248 offset:3072
	v_mfma_f32_16x16x32_bf16 v[136:139], v[216:219], v[208:211], v[136:139]
	ds_read_b128 v[166:169], v249 offset:11264
	v_mfma_f32_16x16x32_bf16 v[104:107], v[220:223], v[186:189], v[104:107]
	ds_read_b128 v[170:173], v249 offset:12288
	v_mfma_f32_16x16x32_bf16 v[64:67], v[220:223], v[190:193], v[64:67]
	ds_read_b128 v[174:177], v249 offset:13312
	v_mfma_f32_16x16x32_bf16 v[116:119], v[220:223], v[194:197], v[116:119]
	ds_read_b128 v[178:181], v249 offset:14336
	v_mfma_f32_16x16x32_bf16 v[140:143], v[220:223], v[208:211], v[140:143]
	ds_read_b128 v[182:185], v249 offset:15360
	v_mfma_f32_16x16x32_bf16 v[100:103], v[224:227], v[186:189], v[100:103]
	v_mfma_f32_16x16x32_bf16 v[60:63], v[224:227], v[190:193], v[60:63]
	v_mfma_f32_16x16x32_bf16 v[124:127], v[224:227], v[194:197], v[124:127]
	v_mfma_f32_16x16x32_bf16 v[144:147], v[224:227], v[208:211], v[144:147]
	v_mfma_f32_16x16x32_bf16 v[68:71], v[228:231], v[186:189], v[68:71]
	v_mfma_f32_16x16x32_bf16 v[36:39], v[228:231], v[190:193], v[36:39]
	v_mfma_f32_16x16x32_bf16 v[88:91], v[228:231], v[194:197], v[88:91]
	v_mfma_f32_16x16x32_bf16 v[76:79], v[228:231], v[208:211], v[76:79]
	v_mfma_f32_16x16x32_bf16 v[56:59], v[232:235], v[186:189], v[56:59]
	v_mfma_f32_16x16x32_bf16 v[32:35], v[232:235], v[190:193], v[32:35]
	v_mfma_f32_16x16x32_bf16 v[92:95], v[232:235], v[194:197], v[92:95]
	v_mfma_f32_16x16x32_bf16 v[52:55], v[232:235], v[208:211], v[52:55]
	v_mfma_f32_16x16x32_bf16 v[48:51], v[236:239], v[186:189], v[48:51]
	v_mfma_f32_16x16x32_bf16 v[28:31], v[236:239], v[190:193], v[28:31]
	v_mfma_f32_16x16x32_bf16 v[96:99], v[236:239], v[194:197], v[96:99]
	v_mfma_f32_16x16x32_bf16 v[44:47], v[236:239], v[208:211], v[44:47]
	v_mfma_f32_16x16x32_bf16 v[40:43], v[240:243], v[186:189], v[40:43]
	v_mfma_f32_16x16x32_bf16 v[24:27], v[240:243], v[190:193], v[24:27]
	v_mfma_f32_16x16x32_bf16 v[84:87], v[240:243], v[194:197], v[84:87]
	v_mfma_f32_16x16x32_bf16 v[148:151], v[240:243], v[208:211], v[148:151]
	s_add_u32 s30, s30, 24576
	s_cmp_eq_u32 s30, 73728
	s_cselect_b32 s30, 0, s30
	s_waitcnt lgkmcnt(0)
	s_barrier
	v_mfma_f32_16x16x32_bf16 v[128:131], v[16:19], v[0:3], v[128:131]
	v_mfma_f32_16x16x32_bf16 v[80:83], v[16:19], v[4:7], v[80:83]
	v_mfma_f32_16x16x32_bf16 v[108:111], v[16:19], v[8:11], v[108:111]
	v_mfma_f32_16x16x32_bf16 v[132:135], v[16:19], v[12:15], v[132:135]
	v_mfma_f32_16x16x32_bf16 v[120:123], v[20:23], v[0:3], v[120:123]
	v_mfma_f32_16x16x32_bf16 v[72:75], v[20:23], v[4:7], v[72:75]
	v_mfma_f32_16x16x32_bf16 v[112:115], v[20:23], v[8:11], v[112:115]
	v_mfma_f32_16x16x32_bf16 v[136:139], v[20:23], v[12:15], v[136:139]
	v_mfma_f32_16x16x32_bf16 v[104:107], v[162:165], v[0:3], v[104:107]
	v_mfma_f32_16x16x32_bf16 v[64:67], v[162:165], v[4:7], v[64:67]
	v_mfma_f32_16x16x32_bf16 v[116:119], v[162:165], v[8:11], v[116:119]
	v_mfma_f32_16x16x32_bf16 v[140:143], v[162:165], v[12:15], v[140:143]
	v_mfma_f32_16x16x32_bf16 v[100:103], v[166:169], v[0:3], v[100:103]
	v_mfma_f32_16x16x32_bf16 v[60:63], v[166:169], v[4:7], v[60:63]
	v_mfma_f32_16x16x32_bf16 v[124:127], v[166:169], v[8:11], v[124:127]
	v_mfma_f32_16x16x32_bf16 v[144:147], v[166:169], v[12:15], v[144:147]
	v_mfma_f32_16x16x32_bf16 v[68:71], v[170:173], v[0:3], v[68:71]
	v_mfma_f32_16x16x32_bf16 v[36:39], v[170:173], v[4:7], v[36:39]
	v_mfma_f32_16x16x32_bf16 v[88:91], v[170:173], v[8:11], v[88:91]
	v_mfma_f32_16x16x32_bf16 v[76:79], v[170:173], v[12:15], v[76:79]
	v_mfma_f32_16x16x32_bf16 v[56:59], v[174:177], v[0:3], v[56:59]
	v_mfma_f32_16x16x32_bf16 v[32:35], v[174:177], v[4:7], v[32:35]
	v_mfma_f32_16x16x32_bf16 v[92:95], v[174:177], v[8:11], v[92:95]
	v_mfma_f32_16x16x32_bf16 v[52:55], v[174:177], v[12:15], v[52:55]
	v_mfma_f32_16x16x32_bf16 v[48:51], v[178:181], v[0:3], v[48:51]
	v_mfma_f32_16x16x32_bf16 v[28:31], v[178:181], v[4:7], v[28:31]
	v_mfma_f32_16x16x32_bf16 v[96:99], v[178:181], v[8:11], v[96:99]
	v_mfma_f32_16x16x32_bf16 v[44:47], v[178:181], v[12:15], v[44:47]
	v_mfma_f32_16x16x32_bf16 v[40:43], v[182:185], v[0:3], v[40:43]
	v_mfma_f32_16x16x32_bf16 v[24:27], v[182:185], v[4:7], v[24:27]
	v_mfma_f32_16x16x32_bf16 v[84:87], v[182:185], v[8:11], v[84:87]
	v_mfma_f32_16x16x32_bf16 v[148:151], v[182:185], v[12:15], v[148:151]
	v_mov_b32 v250, v198
	s_nop 0
	v_and_b32_e32 v251, 15, v250
	v_bfe_u32 v156, v250, 4, 2
	v_bfe_u32 v157, v250, 6, 1
	v_bfe_u32 v158, v250, 7, 1
	v_lshl_add_u32 v158, v158, 6, s10
	v_add_u32_e32 v158, v158, v251
	v_lshl_add_u32 v157, v157, 7, s11
	v_lshl_add_u32 v159, v156, 2, v157
	v_lshlrev_b32_e32 v246, 2, v159
	v_lshl_add_u32 v244, v158, 12, v246
	v_lshlrev_b32_e32 v161, 1, v159
	v_lshl_add_u32 v245, v158, 11, v161
	v_lshrrev_b32_e32 v161, 6, v157
	v_lshlrev_b32_e32 v161, 2, v161
	v_lshl_add_u32 v247, v158, 6, v161
	v_xor_b32_e32 v248, 16, v200
	v_lshlrev_b32_e32 v248, 2, v248
	v_xor_b32_e32 v249, 32, v200
	v_lshlrev_b32_e32 v249, 2, v249
	s_mov_b32 s24, s6
	s_mov_b32 s25, s7
	s_mov_b32 s26, s78
	s_mov_b32 s27, s79
	v_readlane_b32 s28, v253, 21
	v_readlane_b32 s29, v253, 22
	s_mov_b32 s30, s94
	s_mov_b32 s31, s95
	global_load_dwordx4 v[208:211], v246, s[8:9]
	global_load_dwordx4 v[212:215], v246, s[8:9] offset:64
	global_load_dwordx4 v[216:219], v246, s[8:9] offset:128
	global_load_dwordx4 v[220:223], v246, s[8:9] offset:192
	global_load_dwordx4 v[224:227], v246, s[8:9] offset:256
	global_load_dwordx4 v[228:231], v246, s[8:9] offset:320
	global_load_dwordx4 v[232:235], v246, s[8:9] offset:384
	global_load_dwordx4 v[236:239], v246, s[8:9] offset:448
	global_load_dwordx4 v[0:3], v244, s[24:25]
	global_load_dwordx4 v[4:7], v244, s[24:25] offset:64
	global_load_dwordx4 v[8:11], v244, s[24:25] offset:128
	global_load_dwordx4 v[12:15], v244, s[24:25] offset:192
	global_load_dwordx4 v[16:19], v244, s[24:25] offset:256
	global_load_dwordx4 v[20:23], v244, s[24:25] offset:320
	global_load_dwordx4 v[162:165], v244, s[24:25] offset:384
	global_load_dwordx4 v[166:169], v244, s[24:25] offset:448
	s_add_u32 s24, s24, 0x10000
	s_addc_u32 s25, s25, 0
	global_load_dwordx4 v[170:173], v244, s[24:25]
	global_load_dwordx4 v[174:177], v244, s[24:25] offset:64
	global_load_dwordx4 v[178:181], v244, s[24:25] offset:128
	global_load_dwordx4 v[182:185], v244, s[24:25] offset:192
	global_load_dwordx4 v[186:189], v244, s[24:25] offset:256
	global_load_dwordx4 v[190:193], v244, s[24:25] offset:320
	global_load_dwordx4 v[194:197], v244, s[24:25] offset:384
	global_load_dwordx4 v[240:243], v244, s[24:25] offset:448
	s_add_u32 s24, s24, 0x10000
	s_addc_u32 s25, s25, 0
	s_waitcnt vmcnt(12)
	v_add_f32_e32 v0, v128, v0
	v_add_f32_e32 v1, v129, v1
	v_add_f32_e32 v2, v130, v2
	v_add_f32_e32 v3, v131, v3
	global_store_dwordx4 v244, v[0:3], s[26:27]
	v_mul_f32_e32 v156, v0, v208
	v_mul_f32_e32 v157, v1, v209
	v_mul_f32_e32 v158, v2, v210
	v_mul_f32_e32 v159, v3, v211
	v_cvt_pk_bf16_f32 v156, v156, v157
	v_cvt_pk_bf16_f32 v157, v158, v159
	global_store_dwordx2 v245, v[156:157], s[28:29]
	v_mul_f32_e32 v158, v0, v0
	v_mul_f32_e32 v159, v1, v1
	v_mul_f32_e32 v250, v2, v2
	v_mul_f32_e32 v251, v3, v3
	v_add_f32_e32 v158, v158, v159
	v_add_f32_e32 v250, v250, v251
	v_add_f32_e32 v161, v158, v250
	v_add_f32_e32 v4, v120, v4
	v_add_f32_e32 v5, v121, v5
	v_add_f32_e32 v6, v122, v6
	v_add_f32_e32 v7, v123, v7
	global_store_dwordx4 v244, v[4:7], s[26:27] offset:64
	v_mul_f32_e32 v156, v4, v212
	v_mul_f32_e32 v157, v5, v213
	v_mul_f32_e32 v158, v6, v214
	v_mul_f32_e32 v159, v7, v215
	v_cvt_pk_bf16_f32 v156, v156, v157
	v_cvt_pk_bf16_f32 v157, v158, v159
	global_store_dwordx2 v245, v[156:157], s[28:29] offset:32
	v_mul_f32_e32 v158, v4, v4
	v_mul_f32_e32 v159, v5, v5
	v_mul_f32_e32 v250, v6, v6
	v_mul_f32_e32 v251, v7, v7
	v_add_f32_e32 v158, v158, v159
	v_add_f32_e32 v250, v250, v251
	v_add_f32_e32 v158, v158, v250
	v_add_f32_e32 v161, v161, v158
	v_add_f32_e32 v8, v104, v8
	v_add_f32_e32 v9, v105, v9
	v_add_f32_e32 v10, v106, v10
	v_add_f32_e32 v11, v107, v11
	global_store_dwordx4 v244, v[8:11], s[26:27] offset:128
	v_mul_f32_e32 v156, v8, v216
	v_mul_f32_e32 v157, v9, v217
	v_mul_f32_e32 v158, v10, v218
	v_mul_f32_e32 v159, v11, v219
	v_cvt_pk_bf16_f32 v156, v156, v157
	v_cvt_pk_bf16_f32 v157, v158, v159
	global_store_dwordx2 v245, v[156:157], s[28:29] offset:64
	v_mul_f32_e32 v158, v8, v8
	v_mul_f32_e32 v159, v9, v9
	v_mul_f32_e32 v250, v10, v10
	v_mul_f32_e32 v251, v11, v11
	v_add_f32_e32 v158, v158, v159
	v_add_f32_e32 v250, v250, v251
	v_add_f32_e32 v158, v158, v250
	v_add_f32_e32 v161, v161, v158
	v_add_f32_e32 v12, v100, v12
	v_add_f32_e32 v13, v101, v13
	v_add_f32_e32 v14, v102, v14
	v_add_f32_e32 v15, v103, v15
	global_store_dwordx4 v244, v[12:15], s[26:27] offset:192
	v_mul_f32_e32 v156, v12, v220
	v_mul_f32_e32 v157, v13, v221
	v_mul_f32_e32 v158, v14, v222
	v_mul_f32_e32 v159, v15, v223
	v_cvt_pk_bf16_f32 v156, v156, v157
	v_cvt_pk_bf16_f32 v157, v158, v159
	global_store_dwordx2 v245, v[156:157], s[28:29] offset:96
	v_mul_f32_e32 v158, v12, v12
	v_mul_f32_e32 v159, v13, v13
	v_mul_f32_e32 v250, v14, v14
	v_mul_f32_e32 v251, v15, v15
	v_add_f32_e32 v158, v158, v159
	v_add_f32_e32 v250, v250, v251
	v_add_f32_e32 v158, v158, v250
	v_add_f32_e32 v161, v161, v158
	ds_bpermute_b32 v158, v248, v161
	s_waitcnt lgkmcnt(0)
	v_add_f32_e32 v161, v161, v158
	ds_bpermute_b32 v158, v249, v161
	s_waitcnt lgkmcnt(0)
	v_add_f32_e32 v161, v161, v158
	global_store_dword v247, v161, s[30:31]
	global_load_dwordx4 v[0:3], v244, s[24:25]
	global_load_dwordx4 v[4:7], v244, s[24:25] offset:64
	global_load_dwordx4 v[8:11], v244, s[24:25] offset:128
	global_load_dwordx4 v[12:15], v244, s[24:25] offset:192
	s_waitcnt vmcnt(21)
	v_add_f32_e32 v16, v68, v16
	v_add_f32_e32 v17, v69, v17
	v_add_f32_e32 v18, v70, v18
	v_add_f32_e32 v19, v71, v19
	global_store_dwordx4 v244, v[16:19], s[26:27] offset:256
	v_mul_f32_e32 v156, v16, v224
	v_mul_f32_e32 v157, v17, v225
	v_mul_f32_e32 v158, v18, v226
	v_mul_f32_e32 v159, v19, v227
	v_cvt_pk_bf16_f32 v156, v156, v157
	v_cvt_pk_bf16_f32 v157, v158, v159
	global_store_dwordx2 v245, v[156:157], s[28:29] offset:128
	v_mul_f32_e32 v158, v16, v16
	v_mul_f32_e32 v159, v17, v17
	v_mul_f32_e32 v250, v18, v18
	v_mul_f32_e32 v251, v19, v19
	v_add_f32_e32 v158, v158, v159
	v_add_f32_e32 v250, v250, v251
	v_add_f32_e32 v161, v158, v250
	v_add_f32_e32 v20, v56, v20
	v_add_f32_e32 v21, v57, v21
	v_add_f32_e32 v22, v58, v22
	v_add_f32_e32 v23, v59, v23
	global_store_dwordx4 v244, v[20:23], s[26:27] offset:320
	v_mul_f32_e32 v156, v20, v228
	v_mul_f32_e32 v157, v21, v229
	v_mul_f32_e32 v158, v22, v230
	v_mul_f32_e32 v159, v23, v231
	v_cvt_pk_bf16_f32 v156, v156, v157
	v_cvt_pk_bf16_f32 v157, v158, v159
	global_store_dwordx2 v245, v[156:157], s[28:29] offset:160
	v_mul_f32_e32 v158, v20, v20
	v_mul_f32_e32 v159, v21, v21
	v_mul_f32_e32 v250, v22, v22
	v_mul_f32_e32 v251, v23, v23
	v_add_f32_e32 v158, v158, v159
	v_add_f32_e32 v250, v250, v251
	v_add_f32_e32 v158, v158, v250
	v_add_f32_e32 v161, v161, v158
	v_add_f32_e32 v162, v48, v162
	v_add_f32_e32 v163, v49, v163
	v_add_f32_e32 v164, v50, v164
	v_add_f32_e32 v165, v51, v165
	global_store_dwordx4 v244, v[162:165], s[26:27] offset:384
	v_mul_f32_e32 v156, v162, v232
	v_mul_f32_e32 v157, v163, v233
	v_mul_f32_e32 v158, v164, v234
	v_mul_f32_e32 v159, v165, v235
	v_cvt_pk_bf16_f32 v156, v156, v157
	v_cvt_pk_bf16_f32 v157, v158, v159
	global_store_dwordx2 v245, v[156:157], s[28:29] offset:192
	v_mul_f32_e32 v158, v162, v162
	v_mul_f32_e32 v159, v163, v163
	v_mul_f32_e32 v250, v164, v164
	v_mul_f32_e32 v251, v165, v165
	v_add_f32_e32 v158, v158, v159
	v_add_f32_e32 v250, v250, v251
	v_add_f32_e32 v158, v158, v250
	v_add_f32_e32 v161, v161, v158
	v_add_f32_e32 v166, v40, v166
	v_add_f32_e32 v167, v41, v167
	v_add_f32_e32 v168, v42, v168
	v_add_f32_e32 v169, v43, v169
	global_store_dwordx4 v244, v[166:169], s[26:27] offset:448
	v_mul_f32_e32 v156, v166, v236
	v_mul_f32_e32 v157, v167, v237
	v_mul_f32_e32 v158, v168, v238
	v_mul_f32_e32 v159, v169, v239
	v_cvt_pk_bf16_f32 v156, v156, v157
	v_cvt_pk_bf16_f32 v157, v158, v159
	global_store_dwordx2 v245, v[156:157], s[28:29] offset:224
	v_mul_f32_e32 v158, v166, v166
	v_mul_f32_e32 v159, v167, v167
	v_mul_f32_e32 v250, v168, v168
	v_mul_f32_e32 v251, v169, v169
	v_add_f32_e32 v158, v158, v159
	v_add_f32_e32 v250, v250, v251
	v_add_f32_e32 v158, v158, v250
	v_add_f32_e32 v161, v161, v158
	ds_bpermute_b32 v158, v248, v161
	s_waitcnt lgkmcnt(0)
	v_add_f32_e32 v161, v161, v158
	ds_bpermute_b32 v158, v249, v161
	s_waitcnt lgkmcnt(0)
	v_add_f32_e32 v161, v161, v158
	global_store_dword v247, v161, s[30:31] offset:4
	s_add_u32 s26, s26, 0x10000
	s_addc_u32 s27, s27, 0
	s_add_u32 s28, s28, 0x8000
	s_addc_u32 s29, s29, 0
	s_add_u32 s30, s30, 0x400
	s_addc_u32 s31, s31, 0
	global_load_dwordx4 v[16:19], v244, s[24:25] offset:256
	global_load_dwordx4 v[20:23], v244, s[24:25] offset:320
	global_load_dwordx4 v[162:165], v244, s[24:25] offset:384
	global_load_dwordx4 v[166:169], v244, s[24:25] offset:448
	s_add_u32 s24, s24, 0x10000
	s_addc_u32 s25, s25, 0
	s_waitcnt vmcnt(30)
	v_add_f32_e32 v170, v80, v170
	v_add_f32_e32 v171, v81, v171
	v_add_f32_e32 v172, v82, v172
	v_add_f32_e32 v173, v83, v173
	global_store_dwordx4 v244, v[170:173], s[26:27]
	v_mul_f32_e32 v156, v170, v208
	v_mul_f32_e32 v157, v171, v209
	v_mul_f32_e32 v158, v172, v210
	v_mul_f32_e32 v159, v173, v211
	v_cvt_pk_bf16_f32 v156, v156, v157
	v_cvt_pk_bf16_f32 v157, v158, v159
	global_store_dwordx2 v245, v[156:157], s[28:29]
	v_mul_f32_e32 v158, v170, v170
	v_mul_f32_e32 v159, v171, v171
	v_mul_f32_e32 v250, v172, v172
	v_mul_f32_e32 v251, v173, v173
	v_add_f32_e32 v158, v158, v159
	v_add_f32_e32 v250, v250, v251
	v_add_f32_e32 v161, v158, v250
	v_add_f32_e32 v174, v72, v174
	v_add_f32_e32 v175, v73, v175
	v_add_f32_e32 v176, v74, v176
	v_add_f32_e32 v177, v75, v177
	global_store_dwordx4 v244, v[174:177], s[26:27] offset:64
	v_mul_f32_e32 v156, v174, v212
	v_mul_f32_e32 v157, v175, v213
	v_mul_f32_e32 v158, v176, v214
	v_mul_f32_e32 v159, v177, v215
	v_cvt_pk_bf16_f32 v156, v156, v157
	v_cvt_pk_bf16_f32 v157, v158, v159
	global_store_dwordx2 v245, v[156:157], s[28:29] offset:32
	v_mul_f32_e32 v158, v174, v174
	v_mul_f32_e32 v159, v175, v175
	v_mul_f32_e32 v250, v176, v176
	v_mul_f32_e32 v251, v177, v177
	v_add_f32_e32 v158, v158, v159
	v_add_f32_e32 v250, v250, v251
	v_add_f32_e32 v158, v158, v250
	v_add_f32_e32 v161, v161, v158
	v_add_f32_e32 v178, v64, v178
	v_add_f32_e32 v179, v65, v179
	v_add_f32_e32 v180, v66, v180
	v_add_f32_e32 v181, v67, v181
	global_store_dwordx4 v244, v[178:181], s[26:27] offset:128
	v_mul_f32_e32 v156, v178, v216
	v_mul_f32_e32 v157, v179, v217
	v_mul_f32_e32 v158, v180, v218
	v_mul_f32_e32 v159, v181, v219
	v_cvt_pk_bf16_f32 v156, v156, v157
	v_cvt_pk_bf16_f32 v157, v158, v159
	global_store_dwordx2 v245, v[156:157], s[28:29] offset:64
	v_mul_f32_e32 v158, v178, v178
	v_mul_f32_e32 v159, v179, v179
	v_mul_f32_e32 v250, v180, v180
	v_mul_f32_e32 v251, v181, v181
	v_add_f32_e32 v158, v158, v159
	v_add_f32_e32 v250, v250, v251
	v_add_f32_e32 v158, v158, v250
	v_add_f32_e32 v161, v161, v158
	v_add_f32_e32 v182, v60, v182
	v_add_f32_e32 v183, v61, v183
	v_add_f32_e32 v184, v62, v184
	v_add_f32_e32 v185, v63, v185
	global_store_dwordx4 v244, v[182:185], s[26:27] offset:192
	v_mul_f32_e32 v156, v182, v220
	v_mul_f32_e32 v157, v183, v221
	v_mul_f32_e32 v158, v184, v222
	v_mul_f32_e32 v159, v185, v223
	v_cvt_pk_bf16_f32 v156, v156, v157
	v_cvt_pk_bf16_f32 v157, v158, v159
	global_store_dwordx2 v245, v[156:157], s[28:29] offset:96
	v_mul_f32_e32 v158, v182, v182
	v_mul_f32_e32 v159, v183, v183
	v_mul_f32_e32 v250, v184, v184
	v_mul_f32_e32 v251, v185, v185
	v_add_f32_e32 v158, v158, v159
	v_add_f32_e32 v250, v250, v251
	v_add_f32_e32 v158, v158, v250
	v_add_f32_e32 v161, v161, v158
	ds_bpermute_b32 v158, v248, v161
	s_waitcnt lgkmcnt(0)
	v_add_f32_e32 v161, v161, v158
	ds_bpermute_b32 v158, v249, v161
	s_waitcnt lgkmcnt(0)
	v_add_f32_e32 v161, v161, v158
	global_store_dword v247, v161, s[30:31]
	global_load_dwordx4 v[170:173], v244, s[24:25]
	global_load_dwordx4 v[174:177], v244, s[24:25] offset:64
	global_load_dwordx4 v[178:181], v244, s[24:25] offset:128
	global_load_dwordx4 v[182:185], v244, s[24:25] offset:192
	s_waitcnt vmcnt(39)
	v_add_f32_e32 v186, v36, v186
	v_add_f32_e32 v187, v37, v187
	v_add_f32_e32 v188, v38, v188
	v_add_f32_e32 v189, v39, v189
	global_store_dwordx4 v244, v[186:189], s[26:27] offset:256
	v_mul_f32_e32 v156, v186, v224
	v_mul_f32_e32 v157, v187, v225
	v_mul_f32_e32 v158, v188, v226
	v_mul_f32_e32 v159, v189, v227
	v_cvt_pk_bf16_f32 v156, v156, v157
	v_cvt_pk_bf16_f32 v157, v158, v159
	global_store_dwordx2 v245, v[156:157], s[28:29] offset:128
	v_mul_f32_e32 v158, v186, v186
	v_mul_f32_e32 v159, v187, v187
	v_mul_f32_e32 v250, v188, v188
	v_mul_f32_e32 v251, v189, v189
	v_add_f32_e32 v158, v158, v159
	v_add_f32_e32 v250, v250, v251
	v_add_f32_e32 v161, v158, v250
	v_add_f32_e32 v190, v32, v190
	v_add_f32_e32 v191, v33, v191
	v_add_f32_e32 v192, v34, v192
	v_add_f32_e32 v193, v35, v193
	global_store_dwordx4 v244, v[190:193], s[26:27] offset:320
	v_mul_f32_e32 v156, v190, v228
	v_mul_f32_e32 v157, v191, v229
	v_mul_f32_e32 v158, v192, v230
	v_mul_f32_e32 v159, v193, v231
	v_cvt_pk_bf16_f32 v156, v156, v157
	v_cvt_pk_bf16_f32 v157, v158, v159
	global_store_dwordx2 v245, v[156:157], s[28:29] offset:160
	v_mul_f32_e32 v158, v190, v190
	v_mul_f32_e32 v159, v191, v191
	v_mul_f32_e32 v250, v192, v192
	v_mul_f32_e32 v251, v193, v193
	v_add_f32_e32 v158, v158, v159
	v_add_f32_e32 v250, v250, v251
	v_add_f32_e32 v158, v158, v250
	v_add_f32_e32 v161, v161, v158
	v_add_f32_e32 v194, v28, v194
	v_add_f32_e32 v195, v29, v195
	v_add_f32_e32 v196, v30, v196
	v_add_f32_e32 v197, v31, v197
	global_store_dwordx4 v244, v[194:197], s[26:27] offset:384
	v_mul_f32_e32 v156, v194, v232
	v_mul_f32_e32 v157, v195, v233
	v_mul_f32_e32 v158, v196, v234
	v_mul_f32_e32 v159, v197, v235
	v_cvt_pk_bf16_f32 v156, v156, v157
	v_cvt_pk_bf16_f32 v157, v158, v159
	global_store_dwordx2 v245, v[156:157], s[28:29] offset:192
	v_mul_f32_e32 v158, v194, v194
	v_mul_f32_e32 v159, v195, v195
	v_mul_f32_e32 v250, v196, v196
	v_mul_f32_e32 v251, v197, v197
	v_add_f32_e32 v158, v158, v159
	v_add_f32_e32 v250, v250, v251
	v_add_f32_e32 v158, v158, v250
	v_add_f32_e32 v161, v161, v158
	v_add_f32_e32 v240, v24, v240
	v_add_f32_e32 v241, v25, v241
	v_add_f32_e32 v242, v26, v242
	v_add_f32_e32 v243, v27, v243
	global_store_dwordx4 v244, v[240:243], s[26:27] offset:448
	v_mul_f32_e32 v156, v240, v236
	v_mul_f32_e32 v157, v241, v237
	v_mul_f32_e32 v158, v242, v238
	v_mul_f32_e32 v159, v243, v239
	v_cvt_pk_bf16_f32 v156, v156, v157
	v_cvt_pk_bf16_f32 v157, v158, v159
	global_store_dwordx2 v245, v[156:157], s[28:29] offset:224
	v_mul_f32_e32 v158, v240, v240
	v_mul_f32_e32 v159, v241, v241
	v_mul_f32_e32 v250, v242, v242
	v_mul_f32_e32 v251, v243, v243
	v_add_f32_e32 v158, v158, v159
	v_add_f32_e32 v250, v250, v251
	v_add_f32_e32 v158, v158, v250
	v_add_f32_e32 v161, v161, v158
	ds_bpermute_b32 v158, v248, v161
	s_waitcnt lgkmcnt(0)
	v_add_f32_e32 v161, v161, v158
	ds_bpermute_b32 v158, v249, v161
	s_waitcnt lgkmcnt(0)
	v_add_f32_e32 v161, v161, v158
	global_store_dword v247, v161, s[30:31] offset:4
	s_add_u32 s26, s26, 0x10000
	s_addc_u32 s27, s27, 0
	s_add_u32 s28, s28, 0x8000
	s_addc_u32 s29, s29, 0
	s_add_u32 s30, s30, 0x400
	s_addc_u32 s31, s31, 0
	global_load_dwordx4 v[186:189], v244, s[24:25] offset:256
	global_load_dwordx4 v[190:193], v244, s[24:25] offset:320
	global_load_dwordx4 v[194:197], v244, s[24:25] offset:384
	global_load_dwordx4 v[240:243], v244, s[24:25] offset:448
	s_add_u32 s24, s24, 0x10000
	s_addc_u32 s25, s25, 0
	s_waitcnt vmcnt(39)
	v_add_f32_e32 v0, v108, v0
	v_add_f32_e32 v1, v109, v1
	v_add_f32_e32 v2, v110, v2
	v_add_f32_e32 v3, v111, v3
	global_store_dwordx4 v244, v[0:3], s[26:27]
	v_mul_f32_e32 v156, v0, v208
	v_mul_f32_e32 v157, v1, v209
	v_mul_f32_e32 v158, v2, v210
	v_mul_f32_e32 v159, v3, v211
	v_cvt_pk_bf16_f32 v156, v156, v157
	v_cvt_pk_bf16_f32 v157, v158, v159
	global_store_dwordx2 v245, v[156:157], s[28:29]
	v_mul_f32_e32 v158, v0, v0
	v_mul_f32_e32 v159, v1, v1
	v_mul_f32_e32 v250, v2, v2
	v_mul_f32_e32 v251, v3, v3
	v_add_f32_e32 v158, v158, v159
	v_add_f32_e32 v250, v250, v251
	v_add_f32_e32 v161, v158, v250
	v_add_f32_e32 v4, v112, v4
	v_add_f32_e32 v5, v113, v5
	v_add_f32_e32 v6, v114, v6
	v_add_f32_e32 v7, v115, v7
	global_store_dwordx4 v244, v[4:7], s[26:27] offset:64
	v_mul_f32_e32 v156, v4, v212
	v_mul_f32_e32 v157, v5, v213
	v_mul_f32_e32 v158, v6, v214
	v_mul_f32_e32 v159, v7, v215
	v_cvt_pk_bf16_f32 v156, v156, v157
	v_cvt_pk_bf16_f32 v157, v158, v159
	global_store_dwordx2 v245, v[156:157], s[28:29] offset:32
	v_mul_f32_e32 v158, v4, v4
	v_mul_f32_e32 v159, v5, v5
	v_mul_f32_e32 v250, v6, v6
	v_mul_f32_e32 v251, v7, v7
	v_add_f32_e32 v158, v158, v159
	v_add_f32_e32 v250, v250, v251
	v_add_f32_e32 v158, v158, v250
	v_add_f32_e32 v161, v161, v158
	v_add_f32_e32 v8, v116, v8
	v_add_f32_e32 v9, v117, v9
	v_add_f32_e32 v10, v118, v10
	v_add_f32_e32 v11, v119, v11
	global_store_dwordx4 v244, v[8:11], s[26:27] offset:128
	v_mul_f32_e32 v156, v8, v216
	v_mul_f32_e32 v157, v9, v217
	v_mul_f32_e32 v158, v10, v218
	v_mul_f32_e32 v159, v11, v219
	v_cvt_pk_bf16_f32 v156, v156, v157
	v_cvt_pk_bf16_f32 v157, v158, v159
	global_store_dwordx2 v245, v[156:157], s[28:29] offset:64
	v_mul_f32_e32 v158, v8, v8
	v_mul_f32_e32 v159, v9, v9
	v_mul_f32_e32 v250, v10, v10
	v_mul_f32_e32 v251, v11, v11
	v_add_f32_e32 v158, v158, v159
	v_add_f32_e32 v250, v250, v251
	v_add_f32_e32 v158, v158, v250
	v_add_f32_e32 v161, v161, v158
	v_add_f32_e32 v12, v124, v12
	v_add_f32_e32 v13, v125, v13
	v_add_f32_e32 v14, v126, v14
	v_add_f32_e32 v15, v127, v15
	global_store_dwordx4 v244, v[12:15], s[26:27] offset:192
	v_mul_f32_e32 v156, v12, v220
	v_mul_f32_e32 v157, v13, v221
	v_mul_f32_e32 v158, v14, v222
	v_mul_f32_e32 v159, v15, v223
	v_cvt_pk_bf16_f32 v156, v156, v157
	v_cvt_pk_bf16_f32 v157, v158, v159
	global_store_dwordx2 v245, v[156:157], s[28:29] offset:96
	v_mul_f32_e32 v158, v12, v12
	v_mul_f32_e32 v159, v13, v13
	v_mul_f32_e32 v250, v14, v14
	v_mul_f32_e32 v251, v15, v15
	v_add_f32_e32 v158, v158, v159
	v_add_f32_e32 v250, v250, v251
	v_add_f32_e32 v158, v158, v250
	v_add_f32_e32 v161, v161, v158
	ds_bpermute_b32 v158, v248, v161
	s_waitcnt lgkmcnt(0)
	v_add_f32_e32 v161, v161, v158
	ds_bpermute_b32 v158, v249, v161
	s_waitcnt lgkmcnt(0)
	v_add_f32_e32 v161, v161, v158
	global_store_dword v247, v161, s[30:31]
	s_waitcnt vmcnt(35)
	v_add_f32_e32 v16, v88, v16
	v_add_f32_e32 v17, v89, v17
	v_add_f32_e32 v18, v90, v18
	v_add_f32_e32 v19, v91, v19
	global_store_dwordx4 v244, v[16:19], s[26:27] offset:256
	v_mul_f32_e32 v156, v16, v224
	v_mul_f32_e32 v157, v17, v225
	v_mul_f32_e32 v158, v18, v226
	v_mul_f32_e32 v159, v19, v227
	v_cvt_pk_bf16_f32 v156, v156, v157
	v_cvt_pk_bf16_f32 v157, v158, v159
	global_store_dwordx2 v245, v[156:157], s[28:29] offset:128
	v_mul_f32_e32 v158, v16, v16
	v_mul_f32_e32 v159, v17, v17
	v_mul_f32_e32 v250, v18, v18
	v_mul_f32_e32 v251, v19, v19
	v_add_f32_e32 v158, v158, v159
	v_add_f32_e32 v250, v250, v251
	v_add_f32_e32 v161, v158, v250
	v_add_f32_e32 v20, v92, v20
	v_add_f32_e32 v21, v93, v21
	v_add_f32_e32 v22, v94, v22
	v_add_f32_e32 v23, v95, v23
	global_store_dwordx4 v244, v[20:23], s[26:27] offset:320
	v_mul_f32_e32 v156, v20, v228
	v_mul_f32_e32 v157, v21, v229
	v_mul_f32_e32 v158, v22, v230
	v_mul_f32_e32 v159, v23, v231
	v_cvt_pk_bf16_f32 v156, v156, v157
	v_cvt_pk_bf16_f32 v157, v158, v159
	global_store_dwordx2 v245, v[156:157], s[28:29] offset:160
	v_mul_f32_e32 v158, v20, v20
	v_mul_f32_e32 v159, v21, v21
	v_mul_f32_e32 v250, v22, v22
	v_mul_f32_e32 v251, v23, v23
	v_add_f32_e32 v158, v158, v159
	v_add_f32_e32 v250, v250, v251
	v_add_f32_e32 v158, v158, v250
	v_add_f32_e32 v161, v161, v158
	v_add_f32_e32 v162, v96, v162
	v_add_f32_e32 v163, v97, v163
	v_add_f32_e32 v164, v98, v164
	v_add_f32_e32 v165, v99, v165
	global_store_dwordx4 v244, v[162:165], s[26:27] offset:384
	v_mul_f32_e32 v156, v162, v232
	v_mul_f32_e32 v157, v163, v233
	v_mul_f32_e32 v158, v164, v234
	v_mul_f32_e32 v159, v165, v235
	v_cvt_pk_bf16_f32 v156, v156, v157
	v_cvt_pk_bf16_f32 v157, v158, v159
	global_store_dwordx2 v245, v[156:157], s[28:29] offset:192
	v_mul_f32_e32 v158, v162, v162
	v_mul_f32_e32 v159, v163, v163
	v_mul_f32_e32 v250, v164, v164
	v_mul_f32_e32 v251, v165, v165
	v_add_f32_e32 v158, v158, v159
	v_add_f32_e32 v250, v250, v251
	v_add_f32_e32 v158, v158, v250
	v_add_f32_e32 v161, v161, v158
	v_add_f32_e32 v166, v84, v166
	v_add_f32_e32 v167, v85, v167
	v_add_f32_e32 v168, v86, v168
	v_add_f32_e32 v169, v87, v169
	global_store_dwordx4 v244, v[166:169], s[26:27] offset:448
	v_mul_f32_e32 v156, v166, v236
	v_mul_f32_e32 v157, v167, v237
	v_mul_f32_e32 v158, v168, v238
	v_mul_f32_e32 v159, v169, v239
	v_cvt_pk_bf16_f32 v156, v156, v157
	v_cvt_pk_bf16_f32 v157, v158, v159
	global_store_dwordx2 v245, v[156:157], s[28:29] offset:224
	v_mul_f32_e32 v158, v166, v166
	v_mul_f32_e32 v159, v167, v167
	v_mul_f32_e32 v250, v168, v168
	v_mul_f32_e32 v251, v169, v169
	v_add_f32_e32 v158, v158, v159
	v_add_f32_e32 v250, v250, v251
	v_add_f32_e32 v158, v158, v250
	v_add_f32_e32 v161, v161, v158
	ds_bpermute_b32 v158, v248, v161
	s_waitcnt lgkmcnt(0)
	v_add_f32_e32 v161, v161, v158
	ds_bpermute_b32 v158, v249, v161
	s_waitcnt lgkmcnt(0)
	v_add_f32_e32 v161, v161, v158
	global_store_dword v247, v161, s[30:31] offset:4
	s_add_u32 s26, s26, 0x10000
	s_addc_u32 s27, s27, 0
	s_add_u32 s28, s28, 0x8000
	s_addc_u32 s29, s29, 0
	s_add_u32 s30, s30, 0x400
	s_addc_u32 s31, s31, 0
	s_waitcnt vmcnt(31)
	v_add_f32_e32 v170, v132, v170
	v_add_f32_e32 v171, v133, v171
	v_add_f32_e32 v172, v134, v172
	v_add_f32_e32 v173, v135, v173
	global_store_dwordx4 v244, v[170:173], s[26:27]
	v_mul_f32_e32 v156, v170, v208
	v_mul_f32_e32 v157, v171, v209
	v_mul_f32_e32 v158, v172, v210
	v_mul_f32_e32 v159, v173, v211
	v_cvt_pk_bf16_f32 v156, v156, v157
	v_cvt_pk_bf16_f32 v157, v158, v159
	global_store_dwordx2 v245, v[156:157], s[28:29]
	v_mul_f32_e32 v158, v170, v170
	v_mul_f32_e32 v159, v171, v171
	v_mul_f32_e32 v250, v172, v172
	v_mul_f32_e32 v251, v173, v173
	v_add_f32_e32 v158, v158, v159
	v_add_f32_e32 v250, v250, v251
	v_add_f32_e32 v161, v158, v250
	v_add_f32_e32 v174, v136, v174
	v_add_f32_e32 v175, v137, v175
	v_add_f32_e32 v176, v138, v176
	v_add_f32_e32 v177, v139, v177
	global_store_dwordx4 v244, v[174:177], s[26:27] offset:64
	v_mul_f32_e32 v156, v174, v212
	v_mul_f32_e32 v157, v175, v213
	v_mul_f32_e32 v158, v176, v214
	v_mul_f32_e32 v159, v177, v215
	v_cvt_pk_bf16_f32 v156, v156, v157
	v_cvt_pk_bf16_f32 v157, v158, v159
	global_store_dwordx2 v245, v[156:157], s[28:29] offset:32
	v_mul_f32_e32 v158, v174, v174
	v_mul_f32_e32 v159, v175, v175
	v_mul_f32_e32 v250, v176, v176
	v_mul_f32_e32 v251, v177, v177
	v_add_f32_e32 v158, v158, v159
	v_add_f32_e32 v250, v250, v251
	v_add_f32_e32 v158, v158, v250
	v_add_f32_e32 v161, v161, v158
	v_add_f32_e32 v178, v140, v178
	v_add_f32_e32 v179, v141, v179
	v_add_f32_e32 v180, v142, v180
	v_add_f32_e32 v181, v143, v181
	global_store_dwordx4 v244, v[178:181], s[26:27] offset:128
	v_mul_f32_e32 v156, v178, v216
	v_mul_f32_e32 v157, v179, v217
	v_mul_f32_e32 v158, v180, v218
	v_mul_f32_e32 v159, v181, v219
	v_cvt_pk_bf16_f32 v156, v156, v157
	v_cvt_pk_bf16_f32 v157, v158, v159
	global_store_dwordx2 v245, v[156:157], s[28:29] offset:64
	v_mul_f32_e32 v158, v178, v178
	v_mul_f32_e32 v159, v179, v179
	v_mul_f32_e32 v250, v180, v180
	v_mul_f32_e32 v251, v181, v181
	v_add_f32_e32 v158, v158, v159
	v_add_f32_e32 v250, v250, v251
	v_add_f32_e32 v158, v158, v250
	v_add_f32_e32 v161, v161, v158
	v_add_f32_e32 v182, v144, v182
	v_add_f32_e32 v183, v145, v183
	v_add_f32_e32 v184, v146, v184
	v_add_f32_e32 v185, v147, v185
	global_store_dwordx4 v244, v[182:185], s[26:27] offset:192
	v_mul_f32_e32 v156, v182, v220
	v_mul_f32_e32 v157, v183, v221
	v_mul_f32_e32 v158, v184, v222
	v_mul_f32_e32 v159, v185, v223
	v_cvt_pk_bf16_f32 v156, v156, v157
	v_cvt_pk_bf16_f32 v157, v158, v159
	global_store_dwordx2 v245, v[156:157], s[28:29] offset:96
	v_mul_f32_e32 v158, v182, v182
	v_mul_f32_e32 v159, v183, v183
	v_mul_f32_e32 v250, v184, v184
	v_mul_f32_e32 v251, v185, v185
	v_add_f32_e32 v158, v158, v159
	v_add_f32_e32 v250, v250, v251
	v_add_f32_e32 v158, v158, v250
	v_add_f32_e32 v161, v161, v158
	ds_bpermute_b32 v158, v248, v161
	s_waitcnt lgkmcnt(0)
	v_add_f32_e32 v161, v161, v158
	ds_bpermute_b32 v158, v249, v161
	s_waitcnt lgkmcnt(0)
	v_add_f32_e32 v161, v161, v158
	global_store_dword v247, v161, s[30:31]
	s_waitcnt vmcnt(27)
	v_add_f32_e32 v186, v76, v186
	v_add_f32_e32 v187, v77, v187
	v_add_f32_e32 v188, v78, v188
	v_add_f32_e32 v189, v79, v189
	global_store_dwordx4 v244, v[186:189], s[26:27] offset:256
	v_mul_f32_e32 v156, v186, v224
	v_mul_f32_e32 v157, v187, v225
	v_mul_f32_e32 v158, v188, v226
	v_mul_f32_e32 v159, v189, v227
	v_cvt_pk_bf16_f32 v156, v156, v157
	v_cvt_pk_bf16_f32 v157, v158, v159
	global_store_dwordx2 v245, v[156:157], s[28:29] offset:128
	v_mul_f32_e32 v158, v186, v186
	v_mul_f32_e32 v159, v187, v187
	v_mul_f32_e32 v250, v188, v188
	v_mul_f32_e32 v251, v189, v189
	v_add_f32_e32 v158, v158, v159
	v_add_f32_e32 v250, v250, v251
	v_add_f32_e32 v161, v158, v250
	v_add_f32_e32 v190, v52, v190
	v_add_f32_e32 v191, v53, v191
	v_add_f32_e32 v192, v54, v192
	v_add_f32_e32 v193, v55, v193
	global_store_dwordx4 v244, v[190:193], s[26:27] offset:320
	v_mul_f32_e32 v156, v190, v228
	v_mul_f32_e32 v157, v191, v229
	v_mul_f32_e32 v158, v192, v230
	v_mul_f32_e32 v159, v193, v231
	v_cvt_pk_bf16_f32 v156, v156, v157
	v_cvt_pk_bf16_f32 v157, v158, v159
	global_store_dwordx2 v245, v[156:157], s[28:29] offset:160
	v_mul_f32_e32 v158, v190, v190
	v_mul_f32_e32 v159, v191, v191
	v_mul_f32_e32 v250, v192, v192
	v_mul_f32_e32 v251, v193, v193
	v_add_f32_e32 v158, v158, v159
	v_add_f32_e32 v250, v250, v251
	v_add_f32_e32 v158, v158, v250
	v_add_f32_e32 v161, v161, v158
	v_add_f32_e32 v194, v44, v194
	v_add_f32_e32 v195, v45, v195
	v_add_f32_e32 v196, v46, v196
	v_add_f32_e32 v197, v47, v197
	global_store_dwordx4 v244, v[194:197], s[26:27] offset:384
	v_mul_f32_e32 v156, v194, v232
	v_mul_f32_e32 v157, v195, v233
	v_mul_f32_e32 v158, v196, v234
	v_mul_f32_e32 v159, v197, v235
	v_cvt_pk_bf16_f32 v156, v156, v157
	v_cvt_pk_bf16_f32 v157, v158, v159
	global_store_dwordx2 v245, v[156:157], s[28:29] offset:192
	v_mul_f32_e32 v158, v194, v194
	v_mul_f32_e32 v159, v195, v195
	v_mul_f32_e32 v250, v196, v196
	v_mul_f32_e32 v251, v197, v197
	v_add_f32_e32 v158, v158, v159
	v_add_f32_e32 v250, v250, v251
	v_add_f32_e32 v158, v158, v250
	v_add_f32_e32 v161, v161, v158
	v_add_f32_e32 v240, v148, v240
	v_add_f32_e32 v241, v149, v241
	v_add_f32_e32 v242, v150, v242
	v_add_f32_e32 v243, v151, v243
	global_store_dwordx4 v244, v[240:243], s[26:27] offset:448
	v_mul_f32_e32 v156, v240, v236
	v_mul_f32_e32 v157, v241, v237
	v_mul_f32_e32 v158, v242, v238
	v_mul_f32_e32 v159, v243, v239
	v_cvt_pk_bf16_f32 v156, v156, v157
	v_cvt_pk_bf16_f32 v157, v158, v159
	global_store_dwordx2 v245, v[156:157], s[28:29] offset:224
	v_mul_f32_e32 v158, v240, v240
	v_mul_f32_e32 v159, v241, v241
	v_mul_f32_e32 v250, v242, v242
	v_mul_f32_e32 v251, v243, v243
	v_add_f32_e32 v158, v158, v159
	v_add_f32_e32 v250, v250, v251
	v_add_f32_e32 v158, v158, v250
	v_add_f32_e32 v161, v161, v158
	ds_bpermute_b32 v158, v248, v161
	s_waitcnt lgkmcnt(0)
	v_add_f32_e32 v161, v161, v158
	ds_bpermute_b32 v158, v249, v161
	s_waitcnt lgkmcnt(0)
	v_add_f32_e32 v161, v161, v158
	global_store_dword v247, v161, s[30:31] offset:4
	s_add_u32 s26, s26, 0x10000
	s_addc_u32 s27, s27, 0
	s_add_u32 s28, s28, 0x8000
	s_addc_u32 s29, s29, 0
	s_add_u32 s30, s30, 0x400
	s_addc_u32 s31, s31, 0
	s_branch .LBB0_23

.LBB0_105:
	v_add_u32_e32 v94, s10, v208
	v_add_u32_e32 v151, v94, v149
	ds_read_b128 v[76:79], v151
	v_add_u32_e32 v192, v147, v149
	ds_read_b128 v[64:67], v192 offset:32768
	ds_read_b128 v[84:87], v151 offset:2048
	v_add_u32_e32 v196, v94, v155
	v_add_u32_e32 v193, v147, v155
	ds_read_b128 v[72:75], v192 offset:40960
	ds_read_b128 v[132:135], v196
	ds_read_b128 v[128:131], v196 offset:2048
	ds_read_b128 v[80:83], v193 offset:32768
	ds_read_b128 v[68:71], v193 offset:40960
	s_waitcnt lgkmcnt(0)
	v_mfma_f32_16x16x32_bf16 v[96:99], v[76:79], v[64:67], 0
	v_lshl_or_b32 v194, v88, 6, v145
	v_lshrrev_b64 v[88:89], v88, v[172:173]
	v_and_b32_e32 v88, 1, v88
	v_mfma_f32_16x16x32_bf16 v[104:107], v[84:87], v[64:67], 0
	v_mov_b32_e32 v89, v153
	v_cmp_gt_i32_e64 s[8:9], v194, v144
	v_cmp_eq_u64_e32 vcc, 0, v[88:89]
	v_mfma_f32_16x16x32_bf16 v[96:99], v[132:135], v[80:83], v[96:99]
	s_or_b64 s[22:23], vcc, s[8:9]
	v_or_b32_e32 v95, 2, v194
	v_cmp_lt_i32_e64 s[20:21], v194, v144
	v_mfma_f32_16x16x32_bf16 v[104:107], v[128:131], v[80:83], v[104:107]
	v_cmp_gt_i32_e64 s[8:9], v95, v144
	s_nop 2
	v_cndmask_b32_e64 v89, v96, v204, s[22:23]
	v_or_b32_e32 v96, 3, v194
	v_cndmask_b32_e64 v92, v204, v97, s[20:21]
	s_or_b64 s[24:25], vcc, s[8:9]
	v_cmp_gt_i32_e64 s[8:9], v96, v144
	v_or_b32_e32 v97, 16, v194
	v_cndmask_b32_e64 v95, v98, v204, s[24:25]
	s_or_b64 s[26:27], vcc, s[8:9]
	v_cmp_gt_i32_e64 s[8:9], v97, v144
	v_or_b32_e32 v98, 17, v194
	v_cndmask_b32_e64 v96, v99, v204, s[26:27]
	s_or_b64 s[28:29], vcc, s[8:9]
	v_cmp_gt_i32_e64 s[8:9], v98, v144
	v_or_b32_e32 v99, 18, v194
	v_cndmask_b32_e32 v88, v92, v204, vcc
	v_cndmask_b32_e64 v97, v104, v204, s[28:29]
	s_or_b64 s[30:31], vcc, s[8:9]
	v_cmp_gt_i32_e64 s[8:9], v99, v144
	v_or_b32_e32 v104, 19, v194
	v_max3_f32 v92, v89, s75, v88
	s_or_b64 s[34:35], vcc, s[8:9]
	v_cmp_gt_i32_e64 s[8:9], v104, v144
	v_max3_f32 v92, v92, v95, v96
	v_cndmask_b32_e64 v98, v105, v204, s[30:31]
	s_or_b64 s[36:37], vcc, s[8:9]
	v_max3_f32 v92, v92, v97, v98
	v_cndmask_b32_e64 v99, v106, v204, s[34:35]
	v_cndmask_b32_e64 v116, v107, v204, s[36:37]
	v_add_u32_e32 v91, v94, v211
	v_max3_f32 v92, v92, v99, v116
	ds_read2st64_b64 v[100:103], v91 offset0:16 offset1:20
	ds_bpermute_b32 v104, v157, v92
	v_add_u32_e32 v93, s10, v209
	v_add_u32_e32 v90, v94, v210
	v_add_u32_e32 v105, v93, v210
	s_waitcnt lgkmcnt(1)
	v_mov_b32_e32 v122, v100
	s_waitcnt lgkmcnt(0)
	v_max_f32_e32 v100, v104, v104
	v_max_f32_e32 v92, v92, v100
	ds_bpermute_b32 v104, v159, v92
	v_add_u32_e32 v106, v93, v211
	ds_read2st64_b64 v[108:111], v90 offset0:16 offset1:20
	v_mov_b32_e32 v123, v101
	v_add_u32_e32 v225, v94, v213
	s_waitcnt lgkmcnt(1)
	v_max3_f32 v197, v223, v92, v104
	v_sub_f32_e32 v89, v89, v197
	v_exp_f32_e32 v89, v89
	v_sub_f32_e32 v88, v88, v197
	v_exp_f32_e32 v88, v88
	ds_read_b64 v[112:113], v90 offset:12288
	ds_read_b64 v[114:115], v91 offset:12288
	ds_read_b64 v[104:105], v105 offset:8192
	ds_read_b64 v[106:107], v106 offset:8192
	v_add_f32_e32 v91, 0, v89
	v_sub_f32_e32 v90, v223, v197
	v_add_f32_e32 v189, v88, v91
	v_sub_f32_e32 v91, v95, v197
	v_exp_f32_e32 v117, v91
	v_sub_f32_e32 v91, v96, v197
	v_exp_f32_e32 v190, v90
	v_exp_f32_e32 v119, v91
	v_sub_f32_e32 v91, v97, v197
	v_exp_f32_e32 v125, v91
	v_sub_f32_e32 v91, v98, v197
	v_exp_f32_e32 v127, v91
	v_sub_f32_e32 v91, v99, v197
	v_sub_f32_e32 v90, v116, v197
	s_waitcnt lgkmcnt(4)
	v_mov_b32_e32 v121, v109
	v_mov_b32_e32 v101, v111
	v_exp_f32_e32 v109, v91
	v_exp_f32_e32 v111, v90
	v_cvt_pk_bf16_f32 v92, v89, v88
	v_pk_mul_f32 v[90:91], v[58:59], v[190:191] op_sel_hi:[1,0]
	v_pk_mul_f32 v[88:89], v[56:57], v[190:191] op_sel_hi:[1,0]
	v_pk_mul_f32 v[58:59], v[50:51], v[190:191] op_sel_hi:[1,0]
	v_pk_mul_f32 v[56:57], v[48:49], v[190:191] op_sel_hi:[1,0]
	v_mfma_f32_16x16x32_bf16 v[48:51], v[76:79], v[72:75], 0
	v_mul_f32_e64 v98, v62, v190
	v_mul_f32_e64 v99, v63, v190
	v_pk_mul_f32 v[96:97], v[60:61], v[190:191] op_sel_hi:[1,0]
	v_pk_mul_f32 v[62:63], v[54:55], v[190:191] op_sel_hi:[1,0]
	v_pk_mul_f32 v[60:61], v[52:53], v[190:191] op_sel_hi:[1,0]
	v_mfma_f32_16x16x32_bf16 v[52:55], v[84:87], v[72:75], 0
	v_add_u32_e32 v223, v94, v212
	v_mov_b32_e32 v120, v108
	v_mov_b32_e32 v100, v110
	v_mfma_f32_16x16x32_bf16 v[48:51], v[132:135], v[68:71], v[48:51]
	v_add_u32_e32 v227, v93, v212
	v_add_u32_e32 v228, v93, v213
	v_or_b32_e32 v93, 32, v194
	v_mfma_f32_16x16x32_bf16 v[52:55], v[128:131], v[68:71], v[52:55]
	v_cmp_gt_i32_e64 s[10:11], v93, v144
	s_nop 2
	v_cndmask_b32_e64 v49, v204, v49, s[20:21]
	v_cndmask_b32_e64 v48, v48, v204, s[22:23]
	v_cndmask_b32_e32 v49, v49, v204, vcc
	v_max3_f32 v94, v48, s75, v49
	v_cndmask_b32_e64 v50, v50, v204, s[24:25]
	v_cndmask_b32_e64 v51, v51, v204, s[26:27]
	v_max3_f32 v94, v94, v50, v51
	v_cndmask_b32_e64 v108, v52, v204, s[28:29]
	v_cndmask_b32_e64 v110, v53, v204, s[30:31]
	v_max3_f32 v52, v94, v108, v110
	v_cndmask_b32_e64 v226, v54, v204, s[34:35]
	v_cndmask_b32_e64 v229, v55, v204, s[36:37]
	v_max3_f32 v52, v52, v226, v229
	ds_bpermute_b32 v53, v157, v52
	v_or_b32_e32 v93, 33, v194
	v_cmp_gt_i32_e64 s[8:9], v93, v144
	v_or_b32_e32 v93, 34, v194
	v_or_b32_e32 v54, 48, v194
	s_waitcnt lgkmcnt(0)
	v_max_f32_e32 v53, v53, v53
	v_max_f32_e32 v52, v52, v53
	ds_bpermute_b32 v53, v159, v52
	v_cmp_gt_i32_e64 s[12:13], v93, v144
	v_or_b32_e32 v93, 35, v194
	v_cmp_gt_i32_e64 s[14:15], v54, v144
	v_or_b32_e32 v54, 49, v194
	s_waitcnt lgkmcnt(0)
	v_max3_f32 v224, v222, v52, v53
	v_sub_f32_e32 v48, v48, v224
	v_exp_f32_e32 v232, v48
	v_sub_f32_e32 v48, v49, v224
	v_exp_f32_e32 v233, v48
	v_sub_f32_e32 v48, v50, v224
	v_exp_f32_e32 v116, v48
	v_add_f32_e32 v48, 0, v232
	v_add_f32_e32 v188, v233, v48
	v_sub_f32_e32 v48, v51, v224
	v_exp_f32_e32 v118, v48
	v_sub_f32_e32 v48, v108, v224
	v_exp_f32_e32 v124, v48
	v_pk_add_f32 v[52:53], v[116:117], v[188:189]
	v_cmp_gt_i32_e64 s[16:17], v93, v144
	v_cmp_gt_i32_e64 s[18:19], v54, v144
	v_cvt_pk_bf16_f32 v93, v117, v119
	v_cvt_pk_bf16_f32 v94, v125, v127
	v_cvt_pk_bf16_f32 v95, v109, v111
	v_sub_f32_e32 v54, v110, v224
	v_mfma_f32_16x16x32_bf16 v[48:51], v[120:123], v[92:95], v[96:99]
	v_exp_f32_e32 v126, v54
	v_or_b32_e32 v195, 50, v194
	v_cmp_gt_i32_e64 s[38:39], v195, v144
	v_pk_add_f32 v[96:97], v[118:119], v[52:53]
	v_mfma_f32_16x16x32_bf16 v[52:55], v[100:103], v[92:95], v[88:91]
	v_mov_b32_e32 v189, v190
	s_or_b64 s[10:11], vcc, s[10:11]
	s_or_b64 s[8:9], vcc, s[8:9]
	v_pk_add_f32 v[88:89], v[124:125], v[96:97]
	v_sub_f32_e32 v96, v226, v224
	v_exp_f32_e32 v108, v96
	ds_read_b128 v[96:99], v192 offset:49152
	v_pk_add_f32 v[230:231], v[126:127], v[88:89]
	v_mfma_f32_16x16x32_bf16 v[88:91], v[112:115], v[92:95], v[60:63]
	s_or_b64 s[12:13], vcc, s[12:13]
	s_or_b64 s[16:17], vcc, s[16:17]
	s_or_b64 s[14:15], vcc, s[14:15]
	v_sub_f32_e32 v60, v229, v224
	v_mfma_f32_16x16x32_bf16 v[92:95], v[104:107], v[92:95], v[56:59]
	v_cvt_pk_bf16_f32 v58, v124, v126
	ds_read_b128 v[124:127], v193 offset:49152
	v_exp_f32_e32 v110, v60
	v_cvt_pk_bf16_f32 v57, v116, v118
	v_pk_add_f32 v[60:61], v[108:109], v[230:231]
	v_sub_f32_e32 v56, v222, v224
	v_exp_f32_e32 v188, v56
	v_cvt_pk_bf16_f32 v56, v232, v233
	ds_read_b128 v[116:119], v192 offset:57344
	s_waitcnt lgkmcnt(2)
	v_mfma_f32_16x16x32_bf16 v[230:233], v[76:79], v[96:99], 0
	v_cvt_pk_bf16_f32 v59, v108, v110
	v_add_f32_e64 v60, v110, v60
	v_add_f32_e64 v61, v111, v61
	v_or_b32_e32 v222, 51, v194
	v_mfma_f32_16x16x32_bf16 v[234:237], v[84:87], v[96:99], 0
	ds_read_b128 v[108:111], v193 offset:57344
	v_pk_mul_f32 v[46:47], v[46:47], v[188:189] op_sel_hi:[1,0]
	v_pk_mul_f32 v[44:45], v[44:45], v[188:189] op_sel_hi:[1,0]
	s_waitcnt lgkmcnt(2)
	v_mfma_f32_16x16x32_bf16 v[192:195], v[132:135], v[124:127], v[230:233]
	v_mul_f32_e64 v30, v30, v188
	v_mul_f32_e64 v31, v31, v188
	v_pk_mul_f32 v[28:29], v[28:29], v[188:189] op_sel_hi:[1,0]
	v_pk_mul_f32 v[34:35], v[34:35], v[188:189] op_sel_hi:[1,0]
	v_mfma_f32_16x16x32_bf16 v[230:233], v[128:131], v[124:127], v[234:237]
	v_mul_f32_e64 v32, v32, v188
	v_mul_f32_e64 v33, v33, v188
	s_nop 0
	v_cndmask_b32_e64 v190, v192, v204, s[22:23]
	v_cndmask_b32_e64 v192, v204, v193, s[20:21]
	v_cndmask_b32_e32 v192, v192, v204, vcc
	v_max3_f32 v193, v190, s75, v192
	v_cndmask_b32_e64 v194, v194, v204, s[24:25]
	v_cndmask_b32_e64 v195, v195, v204, s[26:27]
	v_max3_f32 v193, v193, v194, v195
	v_cndmask_b32_e64 v226, v230, v204, s[28:29]
	v_cndmask_b32_e64 v230, v231, v204, s[30:31]
	v_max3_f32 v193, v193, v226, v230
	v_cndmask_b32_e64 v232, v232, v204, s[34:35]
	v_cndmask_b32_e64 v233, v233, v204, s[36:37]
	v_max3_f32 v193, v193, v232, v233
	ds_bpermute_b32 v229, v157, v193
	s_waitcnt lgkmcnt(2)
	v_mfma_f32_16x16x32_bf16 v[76:79], v[76:79], v[116:119], 0
	v_mul_f32_e64 v26, v26, v188
	v_mul_f32_e64 v27, v27, v188
	v_pk_mul_f32 v[24:25], v[24:25], v[188:189] op_sel_hi:[1,0]
	ds_bpermute_b32 v63, v157, v61
	s_waitcnt lgkmcnt(1)
	v_max_f32_e32 v229, v229, v229
	v_max_f32_e32 v193, v193, v229
	ds_bpermute_b32 v229, v159, v193
	v_mfma_f32_16x16x32_bf16 v[44:47], v[120:123], v[56:59], v[44:47]
	ds_bpermute_b32 v62, v157, v60
	s_or_b64 s[18:19], vcc, s[18:19]
	s_waitcnt lgkmcnt(1)
	v_max3_f32 v229, v191, v193, v229
	v_mfma_f32_16x16x32_bf16 v[28:31], v[100:103], v[56:59], v[28:31]
	v_sub_f32_e32 v190, v190, v229
	v_exp_f32_e32 v190, v190
	v_sub_f32_e32 v192, v192, v229
	v_mfma_f32_16x16x32_bf16 v[32:35], v[112:115], v[56:59], v[32:35]
	v_exp_f32_e32 v192, v192
	s_waitcnt lgkmcnt(0)
	v_pk_add_f32 v[60:61], v[60:61], v[62:63]
	ds_bpermute_b32 v63, v159, v61
	v_mfma_f32_16x16x32_bf16 v[24:27], v[104:107], v[56:59], v[24:27]
	v_sub_f32_e32 v58, v195, v229
	v_exp_f32_e32 v59, v58
	v_sub_f32_e32 v58, v226, v229
	v_mfma_f32_16x16x32_bf16 v[84:87], v[84:87], v[116:119], 0
	v_sub_f32_e32 v56, v191, v229
	v_exp_f32_e32 v191, v58
	v_sub_f32_e32 v58, v230, v229
	v_mfma_f32_16x16x32_bf16 v[76:79], v[132:135], v[108:111], v[76:79]
	v_exp_f32_e32 v193, v58
	v_sub_f32_e32 v58, v232, v229
	v_exp_f32_e32 v195, v58
	v_sub_f32_e32 v58, v233, v229
	v_mfma_f32_16x16x32_bf16 v[84:87], v[128:131], v[108:111], v[84:87]
	v_exp_f32_e32 v233, v58
	s_nop 1
	v_cndmask_b32_e64 v58, v204, v77, s[20:21]
	v_exp_f32_e32 v234, v56
	v_cndmask_b32_e64 v56, v76, v204, s[22:23]
	v_cndmask_b32_e32 v58, v58, v204, vcc
	v_max3_f32 v76, v56, s75, v58
	v_cndmask_b32_e64 v128, v78, v204, s[24:25]
	v_cndmask_b32_e64 v129, v79, v204, s[26:27]
	v_add_f32_e32 v57, 0, v190
	v_max3_f32 v76, v76, v128, v129
	v_cndmask_b32_e64 v130, v84, v204, s[28:29]
	v_cndmask_b32_e64 v131, v85, v204, s[30:31]
	v_add_f32_e32 v231, v192, v57
	v_sub_f32_e32 v57, v194, v229
	v_max3_f32 v76, v76, v130, v131
	v_cndmask_b32_e64 v194, v86, v204, s[34:35]
	v_cndmask_b32_e64 v232, v87, v204, s[36:37]
	v_max3_f32 v76, v76, v194, v232
	ds_bpermute_b32 v77, v157, v76
	v_pk_mul_f32 v[84:85], v[16:17], v[234:235] op_sel_hi:[1,0]
	v_pk_mul_f32 v[42:43], v[42:43], v[234:235] op_sel_hi:[1,0]
	v_pk_mul_f32 v[40:41], v[40:41], v[234:235] op_sel_hi:[1,0]
	v_pk_mul_f32 v[38:39], v[38:39], v[234:235] op_sel_hi:[1,0]
	s_waitcnt lgkmcnt(0)
	v_max_f32_e32 v77, v77, v77
	v_max_f32_e32 v133, v76, v77
	ds_bpermute_b32 v134, v159, v133
	v_pk_mul_f32 v[36:37], v[36:37], v[234:235] op_sel_hi:[1,0]
	v_pk_mul_f32 v[78:79], v[22:23], v[234:235] op_sel_hi:[1,0]
	v_pk_mul_f32 v[76:77], v[20:21], v[234:235] op_sel_hi:[1,0]
	v_pk_mul_f32 v[86:87], v[18:19], v[234:235] op_sel_hi:[1,0]
	s_waitcnt lgkmcnt(0)
	v_max3_f32 v226, v171, v133, v134
	v_sub_f32_e32 v16, v56, v226
	v_exp_f32_e32 v235, v16
	v_sub_f32_e32 v17, v58, v226
	v_exp_f32_e32 v236, v17
	v_sub_f32_e32 v17, v128, v226
	v_exp_f32_e32 v57, v57
	v_exp_f32_e32 v56, v17
	v_sub_f32_e32 v17, v129, v226
	v_exp_f32_e32 v58, v17
	v_sub_f32_e32 v17, v130, v226
	v_cvt_pk_bf16_f32 v132, v190, v192
	v_add_f32_e32 v16, 0, v235
	v_exp_f32_e32 v190, v17
	v_add_f32_e32 v230, v236, v16
	v_pk_add_f32 v[16:17], v[56:57], v[230:231]
	v_sub_f32_e32 v20, v131, v226
	v_pk_add_f32 v[16:17], v[58:59], v[16:17]
	v_cvt_pk_bf16_f32 v133, v57, v59
	v_cvt_pk_bf16_f32 v134, v191, v193
	v_cvt_pk_bf16_f32 v135, v195, v233
	v_exp_f32_e32 v192, v20
	v_pk_add_f32 v[128:129], v[190:191], v[16:17]
	v_mfma_f32_16x16x32_bf16 v[16:19], v[120:123], v[132:135], v[40:43]
	ds_bpermute_b32 v62, v159, v60
	v_cmp_gt_i32_e64 s[22:23], v222, v144
	s_or_b64 s[20:21], vcc, s[38:39]
	v_sub_f32_e32 v40, v194, v226
	v_mfma_f32_16x16x32_bf16 v[20:23], v[100:103], v[132:135], v[36:39]
	v_exp_f32_e32 v194, v40
	ds_read_b128 v[40:43], v151 offset:4096
	v_cvt_pk_bf16_f32 v38, v190, v192
	v_mfma_f32_16x16x32_bf16 v[76:79], v[112:115], v[132:135], v[76:79]
	v_sub_f32_e32 v36, v232, v226
	v_exp_f32_e32 v232, v36
	v_pk_add_f32 v[36:37], v[192:193], v[128:129]
	v_mov_b32_e32 v129, v234
	v_pk_add_f32 v[36:37], v[194:195], v[36:37]
	v_cvt_pk_bf16_f32 v39, v194, v232
	v_mfma_f32_16x16x32_bf16 v[84:87], v[104:107], v[132:135], v[84:87]
	v_add_f32_e64 v230, v232, v36
	v_add_f32_e64 v231, v233, v37
	v_sub_f32_e32 v36, v171, v226
	v_exp_f32_e32 v128, v36
	v_cvt_pk_bf16_f32 v36, v235, v236
	v_cvt_pk_bf16_f32 v37, v56, v58
	s_waitcnt lgkmcnt(1)
	v_pk_add_f32 v[130:131], v[60:61], v[62:63]
	v_pk_mul_f32 v[14:15], v[14:15], v[128:129] op_sel_hi:[1,0]
	v_pk_mul_f32 v[12:13], v[12:13], v[128:129] op_sel_hi:[1,0]
	v_pk_mul_f32 v[6:7], v[6:7], v[128:129] op_sel_hi:[1,0]
	v_pk_mul_f32 v[4:5], v[4:5], v[128:129] op_sel_hi:[1,0]
	v_mfma_f32_16x16x32_bf16 v[12:15], v[120:123], v[36:39], v[12:15]
	ds_bpermute_b32 v121, v157, v231
	ds_bpermute_b32 v120, v157, v230
	v_pk_mul_f32 v[10:11], v[10:11], v[128:129] op_sel_hi:[1,0]
	v_mfma_f32_16x16x32_bf16 v[4:7], v[112:115], v[36:39], v[4:7]
	ds_read_b128 v[112:115], v151 offset:6144
	v_pk_mul_f32 v[8:9], v[8:9], v[128:129] op_sel_hi:[1,0]
	v_pk_mul_f32 v[2:3], v[2:3], v[128:129] op_sel_hi:[1,0]
	v_pk_mul_f32 v[0:1], v[0:1], v[128:129] op_sel_hi:[1,0]
	v_mfma_f32_16x16x32_bf16 v[8:11], v[100:103], v[36:39], v[8:11]
	s_waitcnt lgkmcnt(1)
	v_pk_add_f32 v[132:133], v[230:231], v[120:121]
	ds_read_b128 v[120:123], v196 offset:6144
	s_or_b64 vcc, vcc, s[22:23]
	v_mfma_f32_16x16x32_bf16 v[0:3], v[104:107], v[36:39], v[0:3]
	ds_read_b128 v[36:39], v196 offset:4096
	ds_read2st64_b64 v[102:105], v223 offset0:16 offset1:20
	ds_bpermute_b32 v135, v159, v133
	v_mfma_f32_16x16x32_bf16 v[56:59], v[40:43], v[64:67], 0
	ds_bpermute_b32 v134, v159, v132
	s_waitcnt lgkmcnt(2)
	v_mov_b32_e32 v100, v102
	v_mfma_f32_16x16x32_bf16 v[60:63], v[112:115], v[64:67], 0
	ds_read2st64_b64 v[64:67], v225 offset0:16 offset1:20
	v_mov_b32_e32 v101, v103
	s_waitcnt lgkmcnt(0)
	v_mov_b32_e32 v102, v64
	v_mfma_f32_16x16x32_bf16 v[56:59], v[36:39], v[80:83], v[56:59]
	v_mov_b32_e32 v103, v65
	v_mov_b32_e32 v64, v104
	v_mov_b32_e32 v65, v105
	v_mfma_f32_16x16x32_bf16 v[60:63], v[120:123], v[80:83], v[60:63]
	ds_read_b64 v[104:105], v223 offset:12288
	ds_read_b64 v[106:107], v225 offset:12288
	ds_read_b64 v[80:81], v227 offset:8192
	ds_read_b64 v[82:83], v228 offset:8192
	v_cndmask_b32_e64 v56, v56, v204, s[10:11]
	v_cndmask_b32_e64 v151, v57, v204, s[8:9]
	v_max3_f32 v57, v56, s75, v151
	v_cndmask_b32_e64 v171, v58, v204, s[12:13]
	v_cndmask_b32_e64 v190, v59, v204, s[16:17]
	v_max3_f32 v57, v57, v171, v190
	v_cndmask_b32_e64 v192, v60, v204, s[14:15]
	v_cndmask_b32_e64 v194, v61, v204, s[18:19]
	v_max3_f32 v57, v57, v192, v194
	v_cndmask_b32_e64 v196, v62, v204, s[20:21]
	v_cndmask_b32_e32 v222, v63, v204, vcc
	v_max3_f32 v57, v57, v196, v222
	ds_bpermute_b32 v58, v157, v57
	s_waitcnt lgkmcnt(0)
	s_waitcnt vmcnt(0)
	s_barrier
	v_max_f32_e32 v58, v58, v58
	v_max_f32_e32 v57, v57, v58
	ds_bpermute_b32 v58, v159, v57
	s_waitcnt lgkmcnt(0)
	v_max3_f32 v223, v197, v57, v58
	v_sub_f32_e32 v56, v56, v223
	v_exp_f32_e32 v191, v56
	v_mfma_f32_16x16x32_bf16 v[56:59], v[40:43], v[72:75], 0
	v_sub_f32_e32 v60, v151, v223
	v_sub_f32_e32 v225, v197, v223
	v_exp_f32_e32 v197, v60
	v_mfma_f32_16x16x32_bf16 v[60:63], v[112:115], v[72:75], 0
	v_sub_f32_e32 v72, v190, v223
	v_exp_f32_e32 v73, v72
	v_sub_f32_e32 v72, v192, v223
	v_mfma_f32_16x16x32_bf16 v[56:59], v[36:39], v[68:71], v[56:59]
	v_exp_f32_e32 v193, v72
	v_sub_f32_e32 v72, v194, v223
	v_exp_f32_e32 v235, v72
	v_mfma_f32_16x16x32_bf16 v[60:63], v[120:123], v[68:71], v[60:63]
	v_sub_f32_e32 v70, v196, v223
	s_nop 2
	v_cndmask_b32_e64 v56, v56, v204, s[10:11]
	v_cndmask_b32_e64 v57, v57, v204, s[8:9]
	v_max3_f32 v68, v56, s75, v57
	v_cndmask_b32_e64 v58, v58, v204, s[12:13]
	v_cndmask_b32_e64 v59, v59, v204, s[16:17]
	v_max3_f32 v68, v68, v58, v59
	v_cndmask_b32_e64 v60, v60, v204, s[14:15]
	v_cndmask_b32_e64 v61, v61, v204, s[18:19]
	v_max3_f32 v68, v68, v60, v61
	v_cndmask_b32_e64 v62, v62, v204, s[20:21]
	v_cndmask_b32_e32 v63, v63, v204, vcc
	v_max3_f32 v68, v68, v62, v63
	ds_bpermute_b32 v69, v157, v68
	v_exp_f32_e32 v71, v70
	v_sub_f32_e32 v70, v222, v223
	v_sub_f32_e32 v151, v171, v223
	v_exp_f32_e32 v195, v151
	s_waitcnt lgkmcnt(0)
	v_max_f32_e32 v69, v69, v69
	v_max_f32_e32 v68, v68, v69
	ds_bpermute_b32 v72, v159, v68
	v_exp_f32_e32 v69, v225
	v_exp_f32_e32 v75, v70
	v_cvt_pk_bf16_f32 v230, v191, v197
	v_cvt_pk_bf16_f32 v231, v195, v73
	s_waitcnt lgkmcnt(0)
	v_max3_f32 v222, v224, v68, v72
	v_sub_f32_e32 v56, v56, v222
	v_exp_f32_e32 v190, v56
	v_sub_f32_e32 v56, v57, v222
	v_exp_f32_e32 v196, v56
	v_mov_b32_e32 v228, v69
	v_pk_add_f32 v[56:57], v[190:191], 0 op_sel_hi:[1,0]
	v_pk_mul_f32 v[50:51], v[50:51], v[228:229] op_sel_hi:[1,0]
	v_pk_add_f32 v[236:237], v[196:197], v[56:57]
	v_sub_f32_e32 v56, v58, v222
	v_exp_f32_e32 v194, v56
	v_sub_f32_e32 v56, v59, v222
	v_exp_f32_e32 v72, v56
	v_sub_f32_e32 v56, v60, v222
	v_exp_f32_e32 v192, v56
	v_sub_f32_e32 v56, v61, v222
	v_exp_f32_e32 v234, v56
	v_sub_f32_e32 v56, v62, v222
	v_pk_mul_f32 v[48:49], v[48:49], v[228:229] op_sel_hi:[1,0]
	v_cvt_pk_bf16_f32 v232, v193, v235
	v_cvt_pk_bf16_f32 v233, v71, v75
	v_exp_f32_e32 v70, v56
	v_sub_f32_e32 v56, v63, v222
	v_mfma_f32_16x16x32_bf16 v[60:63], v[100:103], v[230:233], v[48:51]
	v_exp_f32_e32 v74, v56
	v_sub_f32_e32 v68, v224, v222
	v_exp_f32_e32 v68, v68
	v_pk_mul_f32 v[50:51], v[54:55], v[228:229] op_sel_hi:[1,0]
	v_pk_mul_f32 v[48:49], v[52:53], v[228:229] op_sel_hi:[1,0]
	v_pk_mul_f32 v[46:47], v[46:47], v[68:69] op_sel_hi:[1,0]
	s_nop 0
	v_mfma_f32_16x16x32_bf16 v[56:59], v[64:67], v[230:233], v[48:51]
	v_mul_f32_e64 v44, v44, v68
	v_mul_f32_e64 v45, v45, v68
	v_pk_mul_f32 v[30:31], v[30:31], v[68:69] op_sel_hi:[1,0]
	v_pk_mul_f32 v[28:29], v[28:29], v[68:69] op_sel_hi:[1,0]
	v_pk_mul_f32 v[50:51], v[90:91], v[228:229] op_sel_hi:[1,0]
	v_pk_mul_f32 v[48:49], v[88:89], v[228:229] op_sel_hi:[1,0]
	v_cvt_pk_bf16_f32 v89, v194, v72
	v_cvt_pk_bf16_f32 v91, v70, v74
	v_cvt_pk_bf16_f32 v88, v190, v196
	v_pk_mul_f32 v[34:35], v[34:35], v[68:69] op_sel_hi:[1,0]
	v_pk_mul_f32 v[32:33], v[32:33], v[68:69] op_sel_hi:[1,0]
	v_mfma_f32_16x16x32_bf16 v[52:55], v[104:107], v[230:233], v[48:51]
	v_mul_f32_e64 v26, v26, v68
	v_mul_f32_e64 v27, v27, v68
	v_pk_mul_f32 v[24:25], v[24:25], v[68:69] op_sel_hi:[1,0]
	v_cvt_pk_bf16_f32 v90, v192, v234
	v_pk_mul_f32 v[48:49], v[92:93], v[228:229] op_sel_hi:[1,0]
	v_pk_add_f32 v[92:93], v[194:195], v[236:237]
	v_pk_mul_f32 v[50:51], v[94:95], v[228:229] op_sel_hi:[1,0]
	v_pk_add_f32 v[72:73], v[72:73], v[92:93]
	v_mfma_f32_16x16x32_bf16 v[92:95], v[40:43], v[96:99], 0
	v_add_f32_e64 v72, v192, v72
	v_add_f32_e64 v73, v193, v73
	v_pk_add_f32 v[72:73], v[234:235], v[72:73]
	v_mfma_f32_16x16x32_bf16 v[96:99], v[112:115], v[96:99], 0
	v_add_f32_e64 v70, v70, v72
	v_add_f32_e64 v71, v71, v73
	v_pk_fma_f32 v[72:73], v[184:185], v[188:189], v[130:131]
	v_pk_add_f32 v[74:75], v[74:75], v[70:71]
	v_mfma_f32_16x16x32_bf16 v[92:95], v[36:39], v[124:127], v[92:95]
	ds_bpermute_b32 v191, v157, v75
	ds_bpermute_b32 v190, v157, v74
	v_pk_add_f32 v[70:71], v[132:133], v[134:135]
	v_mfma_f32_16x16x32_bf16 v[96:99], v[120:123], v[124:127], v[96:99]
	v_fma_f32 v70, v186, v128, v70
	v_fma_f32 v71, v187, v129, v71
	s_nop 1
	v_cndmask_b32_e64 v92, v92, v204, s[10:11]
	v_cndmask_b32_e64 v93, v93, v204, s[8:9]
	v_max3_f32 v124, v92, s75, v93
	v_cndmask_b32_e64 v125, v94, v204, s[12:13]
	v_cndmask_b32_e64 v126, v95, v204, s[16:17]
	v_max3_f32 v94, v124, v125, v126
	v_cndmask_b32_e64 v124, v96, v204, s[14:15]
	v_cndmask_b32_e64 v127, v97, v204, s[18:19]
	v_max3_f32 v94, v94, v124, v127
	v_cndmask_b32_e64 v98, v98, v204, s[20:21]
	v_cndmask_b32_e32 v130, v99, v204, vcc
	v_max3_f32 v94, v94, v98, v130
	ds_bpermute_b32 v95, v157, v94
	v_mfma_f32_16x16x32_bf16 v[40:43], v[40:43], v[116:119], 0
	s_waitcnt lgkmcnt(1)
	v_pk_add_f32 v[74:75], v[74:75], v[190:191]
	ds_bpermute_b32 v129, v159, v75
	ds_bpermute_b32 v128, v159, v74
	s_waitcnt lgkmcnt(2)
	v_max_f32_e32 v95, v95, v95
	v_max_f32_e32 v94, v94, v95
	ds_bpermute_b32 v95, v159, v94
	v_mfma_f32_16x16x32_bf16 v[36:39], v[36:39], v[108:111], v[40:43]
	s_waitcnt lgkmcnt(1)
	v_pk_add_f32 v[74:75], v[74:75], v[128:129]
	s_waitcnt lgkmcnt(0)
	v_max3_f32 v191, v229, v94, v95
	v_mfma_f32_16x16x32_bf16 v[94:97], v[112:115], v[116:119], 0
	v_sub_f32_e32 v40, v126, v191
	v_exp_f32_e32 v99, v40
	s_nop 0
	v_cndmask_b32_e64 v36, v36, v204, s[10:11]
	v_mfma_f32_16x16x32_bf16 v[40:43], v[120:123], v[108:111], v[94:97]
	v_cndmask_b32_e64 v37, v37, v204, s[8:9]
	v_cndmask_b32_e64 v38, v38, v204, s[12:13]
	v_cndmask_b32_e64 v39, v39, v204, s[16:17]
	v_mfma_f32_16x16x32_bf16 v[44:47], v[100:103], v[88:91], v[44:47]
	v_fma_f32 v184, v72, v68, v74
	v_fma_f32 v185, v73, v69, v75
	s_nop 1
	v_cndmask_b32_e64 v40, v40, v204, s[14:15]
	v_cndmask_b32_e64 v41, v41, v204, s[18:19]
	v_mfma_f32_16x16x32_bf16 v[28:31], v[64:67], v[88:91], v[28:31]
	v_cndmask_b32_e64 v42, v42, v204, s[20:21]
	v_cndmask_b32_e32 v43, v43, v204, vcc
	s_andn2_b64 vcc, exec, s[4:5]
	v_mfma_f32_16x16x32_bf16 v[32:35], v[104:107], v[88:91], v[32:35]
	v_mfma_f32_16x16x32_bf16 v[24:27], v[80:83], v[88:91], v[24:27]
	v_sub_f32_e32 v89, v92, v191
	v_max3_f32 v92, v36, s75, v37
	v_max3_f32 v92, v92, v38, v39
	v_max3_f32 v92, v92, v40, v41
	v_max3_f32 v92, v92, v42, v43
	ds_bpermute_b32 v94, v157, v92
	v_sub_f32_e32 v90, v93, v191
	v_exp_f32_e32 v91, v90
	v_sub_f32_e32 v90, v125, v191
	v_exp_f32_e32 v93, v90
	s_waitcnt lgkmcnt(0)
	v_max_f32_e32 v94, v94, v94
	v_max_f32_e32 v92, v92, v94
	ds_bpermute_b32 v94, v159, v92
	v_sub_f32_e32 v90, v124, v191
	v_exp_f32_e32 v109, v90
	v_sub_f32_e32 v90, v127, v191
	v_sub_f32_e32 v88, v229, v191
	s_waitcnt lgkmcnt(0)
	v_max3_f32 v171, v226, v92, v94
	v_exp_f32_e32 v111, v90
	v_sub_f32_e32 v90, v98, v191
	v_sub_f32_e32 v36, v36, v171
	v_exp_f32_e32 v89, v89
	v_exp_f32_e32 v113, v90
	v_sub_f32_e32 v90, v130, v191
	v_exp_f32_e32 v117, v88
	v_exp_f32_e32 v88, v36
	v_sub_f32_e32 v36, v37, v171
	v_exp_f32_e32 v115, v90
	v_exp_f32_e32 v90, v36
	v_sub_f32_e32 v36, v38, v171
	v_exp_f32_e32 v92, v36
	v_sub_f32_e32 v36, v39, v171
	v_exp_f32_e32 v98, v36
	v_sub_f32_e32 v38, v40, v171
	v_pk_add_f32 v[36:37], v[88:89], 0 op_sel_hi:[1,0]
	v_exp_f32_e32 v108, v38
	v_sub_f32_e32 v38, v41, v171
	v_pk_add_f32 v[36:37], v[90:91], v[36:37]
	v_exp_f32_e32 v110, v38
	v_sub_f32_e32 v38, v42, v171
	v_pk_add_f32 v[36:37], v[92:93], v[36:37]
	v_exp_f32_e32 v112, v38
	v_sub_f32_e32 v38, v43, v171
	v_pk_add_f32 v[36:37], v[98:99], v[36:37]
	v_exp_f32_e32 v114, v38
	v_pk_add_f32 v[36:37], v[108:109], v[36:37]
	v_cvt_pk_bf16_f32 v94, v89, v91
	v_sub_f32_e32 v89, v226, v171
	v_pk_add_f32 v[36:37], v[110:111], v[36:37]
	v_mov_b32_e32 v122, v117
	v_pk_add_f32 v[36:37], v[112:113], v[36:37]
	v_exp_f32_e32 v116, v89
	v_pk_add_f32 v[36:37], v[114:115], v[36:37]
	ds_bpermute_b32 v39, v157, v37
	ds_bpermute_b32 v38, v157, v36
	v_pk_mul_f32 v[18:19], v[18:19], v[122:123] op_sel_hi:[1,0]
	v_pk_mul_f32 v[16:17], v[16:17], v[122:123] op_sel_hi:[1,0]
	v_cvt_pk_bf16_f32 v95, v93, v99
	v_cvt_pk_bf16_f32 v96, v109, v111
	s_waitcnt lgkmcnt(0)
	v_pk_add_f32 v[118:119], v[36:37], v[38:39]
	ds_bpermute_b32 v121, v159, v119
	ds_bpermute_b32 v120, v159, v118
	v_cvt_pk_bf16_f32 v97, v113, v115
	v_pk_mul_f32 v[14:15], v[14:15], v[116:117] op_sel_hi:[1,0]
	v_mfma_f32_16x16x32_bf16 v[40:43], v[100:103], v[94:97], v[16:19]
	v_mul_f32_e64 v12, v12, v116
	v_mul_f32_e64 v13, v13, v116
	v_pk_mul_f32 v[10:11], v[10:11], v[116:117] op_sel_hi:[1,0]
	v_pk_mul_f32 v[8:9], v[8:9], v[116:117] op_sel_hi:[1,0]
	v_pk_mul_f32 v[18:19], v[22:23], v[122:123] op_sel_hi:[1,0]
	v_pk_mul_f32 v[16:17], v[20:21], v[122:123] op_sel_hi:[1,0]
	v_pk_mul_f32 v[6:7], v[6:7], v[116:117] op_sel_hi:[1,0]
	v_pk_mul_f32 v[4:5], v[4:5], v[116:117] op_sel_hi:[1,0]
	v_mfma_f32_16x16x32_bf16 v[36:39], v[64:67], v[94:97], v[16:19]
	v_mul_f32_e64 v2, v2, v116
	v_mul_f32_e64 v3, v3, v116
	v_pk_mul_f32 v[0:1], v[0:1], v[116:117] op_sel_hi:[1,0]
	v_pk_mul_f32 v[18:19], v[78:79], v[122:123] op_sel_hi:[1,0]
	v_pk_mul_f32 v[16:17], v[76:77], v[122:123] op_sel_hi:[1,0]
	v_mfma_f32_16x16x32_bf16 v[48:51], v[80:83], v[230:233], v[48:51]
	v_cvt_pk_bf16_f32 v76, v88, v90
	v_cvt_pk_bf16_f32 v77, v92, v98
	v_cvt_pk_bf16_f32 v78, v108, v110
	v_cvt_pk_bf16_f32 v79, v112, v114
	s_nop 0
	v_mfma_f32_16x16x32_bf16 v[20:23], v[104:107], v[94:97], v[16:19]
	s_nop 2
	v_mul_f32_e64 v18, v86, v122
	v_mul_f32_e64 v19, v87, v122
	v_pk_mul_f32 v[16:17], v[84:85], v[122:123] op_sel_hi:[1,0]
	v_mfma_f32_16x16x32_bf16 v[12:15], v[100:103], v[76:79], v[12:15]
	s_nop 0
	v_mfma_f32_16x16x32_bf16 v[16:19], v[80:83], v[94:97], v[16:19]
	v_mfma_f32_16x16x32_bf16 v[8:11], v[64:67], v[76:79], v[8:11]
	s_waitcnt lgkmcnt(0)
	v_pk_add_f32 v[64:65], v[118:119], v[120:121]
	s_nop 0
	v_pk_fma_f32 v[186:187], v[70:71], v[116:117], v[64:65]
	v_mfma_f32_16x16x32_bf16 v[4:7], v[104:107], v[76:79], v[4:7]
	v_cndmask_b32_e64 v64, 0, 1, s[6:7]
	s_nop 0
	v_readfirstlane_b32 s6, v64
	v_mfma_f32_16x16x32_bf16 v[0:3], v[80:83], v[76:79], v[0:3]
	s_xor_b32 s42, s42, s6
	s_cbranch_vccz .LBB0_107
	v_mov_b32_e32 v88, v161
	v_mov_b64_e32 v[64:65], v[182:183]
	s_branch .LBB0_101

.LBB0_115:
	v_add_u32_e32 v120, s10, v208
	v_add_u32_e32 v189, v120, v149
	v_add_u32_e32 v190, v120, v155
	v_add_u32_e32 v52, v120, v210
	v_lshl_or_b32 v124, v50, 6, v145
	ds_read_b128 v[84:87], v189
	ds_read_b128 v[76:79], v190
	ds_read_b128 v[80:83], v189 offset:2048
	ds_read_b128 v[72:75], v190 offset:2048
	ds_read2st64_b64 v[48:51], v52 offset0:16 offset1:20
	v_add_u32_e32 v122, s10, v209
	v_add_u32_e32 v53, v120, v211
	ds_read2st64_b64 v[64:67], v53 offset0:16 offset1:20
	v_add_u32_e32 v174, v147, v149
	s_waitcnt lgkmcnt(0)
	v_mov_b32_e32 v68, v48
	v_add_u32_e32 v48, v122, v210
	ds_read_b64 v[60:61], v52 offset:12288
	ds_read_b64 v[62:63], v53 offset:12288
	ds_read_b64 v[56:57], v48 offset:8192
	ds_read_b128 v[52:55], v174 offset:32768
	v_add_u32_e32 v112, 0x200, v124
	v_cmp_le_i32_e32 vcc, v124, v144
	v_cmp_gt_i32_e64 s[8:9], v112, v144
	v_add_u32_e32 v112, 0x201, v124
	s_and_b64 s[22:23], vcc, s[8:9]
	v_cmp_lt_i32_e32 vcc, v124, v144
	v_cmp_gt_i32_e64 s[8:9], v112, v144
	v_or_b32_e32 v113, 2, v124
	v_add_u32_e32 v48, v122, v211
	v_add_u32_e32 v172, v147, v155
	s_and_b64 s[24:25], vcc, s[8:9]
	v_cmp_le_i32_e32 vcc, v113, v144
	v_add_u32_e32 v113, 0x202, v124
	v_mov_b32_e32 v69, v49
	v_mov_b32_e32 v70, v64
	v_mov_b32_e32 v71, v65
	v_mov_b32_e32 v64, v50
	v_mov_b32_e32 v65, v51
	ds_read_b64 v[58:59], v48 offset:8192
	ds_read_b128 v[48:51], v172 offset:32768
	v_cmp_gt_i32_e64 s[8:9], v113, v144
	v_or_b32_e32 v113, 3, v124
	s_waitcnt lgkmcnt(2)
	v_mfma_f32_16x16x32_bf16 v[104:107], v[84:87], v[52:55], 0
	s_and_b64 s[26:27], vcc, s[8:9]
	v_cmp_le_i32_e32 vcc, v113, v144
	v_add_u32_e32 v113, 0x203, v124
	v_cmp_gt_i32_e64 s[8:9], v113, v144
	v_or_b32_e32 v113, 16, v124
	v_mfma_f32_16x16x32_bf16 v[108:111], v[80:83], v[52:55], 0
	s_and_b64 s[28:29], vcc, s[8:9]
	v_cmp_le_i32_e32 vcc, v113, v144
	v_add_u32_e32 v113, 0x210, v124
	v_cmp_gt_i32_e64 s[8:9], v113, v144
	v_or_b32_e32 v113, 17, v124
	s_waitcnt lgkmcnt(0)
	v_mfma_f32_16x16x32_bf16 v[104:107], v[76:79], v[48:51], v[104:107]
	s_and_b64 s[30:31], vcc, s[8:9]
	v_cmp_le_i32_e32 vcc, v113, v144
	v_add_u32_e32 v113, 0x211, v124
	v_cmp_gt_i32_e64 s[8:9], v113, v144
	v_or_b32_e32 v113, 18, v124
	v_mfma_f32_16x16x32_bf16 v[108:111], v[72:75], v[48:51], v[108:111]
	s_and_b64 s[34:35], vcc, s[8:9]
	v_cmp_le_i32_e32 vcc, v113, v144
	v_add_u32_e32 v113, 0x212, v124
	v_cmp_gt_i32_e64 s[8:9], v113, v144
	v_or_b32_e32 v113, 19, v124
	v_cndmask_b32_e64 v104, v204, v104, s[22:23]
	v_cndmask_b32_e64 v105, v204, v105, s[24:25]
	s_and_b64 s[36:37], vcc, s[8:9]
	v_cmp_le_i32_e32 vcc, v113, v144
	v_add_u32_e32 v113, 0x213, v124
	v_max3_f32 v112, v104, s75, v105
	v_cndmask_b32_e64 v106, v204, v106, s[26:27]
	v_cndmask_b32_e64 v107, v204, v107, s[28:29]
	v_cmp_gt_i32_e64 s[8:9], v113, v144
	v_max3_f32 v112, v112, v106, v107
	v_cndmask_b32_e64 v108, v204, v108, s[30:31]
	v_cndmask_b32_e64 v109, v204, v109, s[34:35]
	s_and_b64 s[38:39], vcc, s[8:9]
	v_max3_f32 v112, v112, v108, v109
	v_cndmask_b32_e64 v110, v204, v110, s[36:37]
	v_cndmask_b32_e64 v111, v204, v111, s[38:39]
	v_max3_f32 v112, v112, v110, v111
	ds_bpermute_b32 v113, v183, v112
	v_add_u32_e32 v191, v120, v212
	v_add_u32_e32 v192, v120, v213
	v_add_u32_e32 v193, v122, v212
	v_add_u32_e32 v194, v122, v213
	s_waitcnt lgkmcnt(0)
	v_max_f32_e32 v113, v113, v113
	v_max_f32_e32 v112, v112, v113
	ds_bpermute_b32 v113, v186, v112
	s_waitcnt lgkmcnt(0)
	v_max3_f32 v151, v184, v112, v113
	v_sub_f32_e32 v112, v184, v151
	v_exp_f32_e32 v134, v112
	v_sub_f32_e32 v104, v104, v151
	v_exp_f32_e32 v104, v104
	v_sub_f32_e32 v105, v105, v151
	v_pk_mul_f32 v[116:117], v[100:101], v[134:135] op_sel_hi:[1,0]
	v_pk_mul_f32 v[100:101], v[88:89], v[134:135] op_sel_hi:[1,0]
	v_or_b32_e32 v88, 32, v124
	v_cmp_le_i32_e32 vcc, v88, v144
	v_add_u32_e32 v88, 0x220, v124
	v_cmp_gt_i32_e64 s[8:9], v88, v144
	v_or_b32_e32 v88, 33, v124
	s_and_b64 vcc, vcc, s[8:9]
	v_cmp_le_i32_e64 s[8:9], v88, v144
	v_add_u32_e32 v88, 0x221, v124
	v_cmp_gt_i32_e64 s[10:11], v88, v144
	v_or_b32_e32 v88, 34, v124
	s_and_b64 s[8:9], s[8:9], s[10:11]
	v_cmp_le_i32_e64 s[10:11], v88, v144
	v_add_u32_e32 v88, 0x222, v124
	v_cmp_gt_i32_e64 s[12:13], v88, v144
	v_or_b32_e32 v88, 35, v124
	s_and_b64 s[10:11], s[10:11], s[12:13]
	v_cmp_le_i32_e64 s[12:13], v88, v144
	v_add_u32_e32 v88, 0x223, v124
	v_cmp_gt_i32_e64 s[14:15], v88, v144
	v_or_b32_e32 v88, 48, v124
	s_and_b64 s[12:13], s[12:13], s[14:15]
	v_cmp_le_i32_e64 s[14:15], v88, v144
	v_add_u32_e32 v88, 0x230, v124
	v_cmp_gt_i32_e64 s[16:17], v88, v144
	v_or_b32_e32 v88, 49, v124
	s_and_b64 s[14:15], s[14:15], s[16:17]
	v_cmp_le_i32_e64 s[16:17], v88, v144
	v_add_u32_e32 v88, 0x231, v124
	v_exp_f32_e32 v105, v105
	v_cmp_gt_i32_e64 s[18:19], v88, v144
	v_or_b32_e32 v88, 50, v124
	s_and_b64 s[16:17], s[16:17], s[18:19]
	v_cmp_le_i32_e64 s[18:19], v88, v144
	v_add_u32_e32 v88, 0x232, v124
	v_cmp_gt_i32_e64 s[20:21], v88, v144
	v_or_b32_e32 v88, 51, v124
	v_add_f32_e32 v113, 0, v104
	v_sub_f32_e32 v106, v106, v151
	s_and_b64 s[18:19], s[18:19], s[20:21]
	v_cmp_le_i32_e64 s[20:21], v88, v144
	v_add_u32_e32 v88, 0x233, v124
	v_add_f32_e32 v167, v105, v113
	v_exp_f32_e32 v121, v106
	v_sub_f32_e32 v106, v107, v151
	v_pk_mul_f32 v[118:119], v[102:103], v[134:135] op_sel_hi:[1,0]
	v_pk_mul_f32 v[114:115], v[94:95], v[134:135] op_sel_hi:[1,0]
	v_pk_mul_f32 v[112:113], v[92:93], v[134:135] op_sel_hi:[1,0]
	v_pk_mul_f32 v[102:103], v[90:91], v[134:135] op_sel_hi:[1,0]
	v_cmp_gt_i32_e64 s[42:43], v88, v144
	ds_read_b128 v[92:95], v174 offset:40960
	ds_read_b128 v[88:91], v172 offset:40960
	v_exp_f32_e32 v123, v106
	v_sub_f32_e32 v106, v108, v151
	v_exp_f32_e32 v125, v106
	v_sub_f32_e32 v106, v109, v151
	v_exp_f32_e32 v127, v106
	v_sub_f32_e32 v106, v110, v151
	v_exp_f32_e32 v129, v106
	v_sub_f32_e32 v106, v111, v151
	v_pk_mul_f32 v[110:111], v[98:99], v[134:135] op_sel_hi:[1,0]
	v_pk_mul_f32 v[108:109], v[96:97], v[134:135] op_sel_hi:[1,0]
	s_waitcnt lgkmcnt(1)
	v_mfma_f32_16x16x32_bf16 v[96:99], v[84:87], v[92:95], 0
	v_exp_f32_e32 v131, v106
	v_cvt_pk_bf16_f32 v104, v104, v105
	v_cvt_pk_bf16_f32 v105, v121, v123
	v_mfma_f32_16x16x32_bf16 v[176:179], v[80:83], v[92:95], 0
	v_cvt_pk_bf16_f32 v106, v125, v127
	v_cvt_pk_bf16_f32 v107, v129, v131
	s_and_b64 s[20:21], s[20:21], s[42:43]
	s_waitcnt lgkmcnt(0)
	v_mfma_f32_16x16x32_bf16 v[96:99], v[76:79], v[88:91], v[96:99]
	v_mfma_f32_16x16x32_bf16 v[176:179], v[72:75], v[88:91], v[176:179]
	v_mfma_f32_16x16x32_bf16 v[108:111], v[64:67], v[104:107], v[108:111]
	s_nop 5
	v_cndmask_b32_e64 v96, v204, v96, s[22:23]
	v_cndmask_b32_e64 v97, v204, v97, s[24:25]
	v_max3_f32 v120, v96, s75, v97
	v_cndmask_b32_e64 v98, v204, v98, s[26:27]
	v_cndmask_b32_e64 v99, v204, v99, s[28:29]
	v_max3_f32 v120, v120, v98, v99
	v_cndmask_b32_e64 v124, v204, v176, s[30:31]
	v_cndmask_b32_e64 v126, v204, v177, s[34:35]
	v_max3_f32 v120, v120, v124, v126
	v_cndmask_b32_e64 v128, v204, v178, s[36:37]
	v_cndmask_b32_e64 v130, v204, v179, s[38:39]
	v_max3_f32 v120, v120, v128, v130
	ds_bpermute_b32 v122, v183, v120
	v_mfma_f32_16x16x32_bf16 v[112:115], v[60:63], v[104:107], v[112:115]
	s_waitcnt lgkmcnt(0)
	v_max_f32_e32 v122, v122, v122
	v_max_f32_e32 v120, v120, v122
	ds_bpermute_b32 v122, v186, v120
	s_waitcnt lgkmcnt(0)
	v_max3_f32 v195, v182, v120, v122
	v_sub_f32_e32 v96, v96, v195
	v_exp_f32_e32 v135, v96
	v_sub_f32_e32 v97, v97, v195
	v_exp_f32_e32 v171, v97
	v_add_f32_e32 v96, 0, v135
	v_add_f32_e32 v166, v171, v96
	v_sub_f32_e32 v96, v98, v195
	v_exp_f32_e32 v120, v96
	v_sub_f32_e32 v98, v99, v195
	v_exp_f32_e32 v122, v98
	v_sub_f32_e32 v98, v124, v195
	v_exp_f32_e32 v124, v98
	v_sub_f32_e32 v98, v126, v195
	v_exp_f32_e32 v126, v98
	v_sub_f32_e32 v98, v128, v195
	v_pk_add_f32 v[96:97], v[120:121], v[166:167]
	v_exp_f32_e32 v128, v98
	v_sub_f32_e32 v98, v130, v195
	v_pk_add_f32 v[96:97], v[122:123], v[96:97]
	v_exp_f32_e32 v130, v98
	v_pk_add_f32 v[96:97], v[124:125], v[96:97]
	s_nop 0
	v_pk_add_f32 v[96:97], v[126:127], v[96:97]
	s_nop 0
	v_pk_add_f32 v[96:97], v[128:129], v[96:97]
	s_nop 0
	v_pk_add_f32 v[96:97], v[130:131], v[96:97]
	ds_bpermute_b32 v99, v183, v97
	ds_bpermute_b32 v98, v183, v96
	s_waitcnt lgkmcnt(0)
	v_pk_add_f32 v[166:167], v[96:97], v[98:99]
	ds_bpermute_b32 v177, v186, v167
	ds_bpermute_b32 v176, v186, v166
	v_mfma_f32_16x16x32_bf16 v[96:99], v[68:71], v[104:107], v[116:119]
	v_mfma_f32_16x16x32_bf16 v[116:119], v[56:59], v[104:107], v[100:103]
	v_mov_b32_e32 v105, v134
	v_cvt_pk_bf16_f32 v102, v124, v126
	v_cvt_pk_bf16_f32 v103, v128, v130
	s_nop 1
	v_sub_f32_e32 v100, v182, v195
	v_exp_f32_e32 v104, v100
	s_waitcnt lgkmcnt(0)
	v_pk_add_f32 v[100:101], v[166:167], v[176:177]
	v_pk_mul_f32 v[38:39], v[38:39], v[104:105] op_sel_hi:[1,0]
	v_pk_fma_f32 v[166:167], v[132:133], v[104:105], v[100:101]
	v_cvt_pk_bf16_f32 v101, v120, v122
	v_pk_mul_f32 v[36:37], v[36:37], v[104:105] op_sel_hi:[1,0]
	v_pk_mul_f32 v[34:35], v[34:35], v[104:105] op_sel_hi:[1,0]
	v_pk_mul_f32 v[32:33], v[32:33], v[104:105] op_sel_hi:[1,0]
	v_pk_mul_f32 v[30:31], v[30:31], v[104:105] op_sel_hi:[1,0]
	v_pk_mul_f32 v[28:29], v[28:29], v[104:105] op_sel_hi:[1,0]
	v_pk_mul_f32 v[26:27], v[26:27], v[104:105] op_sel_hi:[1,0]
	v_pk_mul_f32 v[24:25], v[24:25], v[104:105] op_sel_hi:[1,0]
	ds_read_b128 v[120:123], v174 offset:49152
	ds_read_b128 v[104:107], v172 offset:49152
	v_cvt_pk_bf16_f32 v100, v135, v171
	s_waitcnt lgkmcnt(1)
	v_mfma_f32_16x16x32_bf16 v[124:127], v[80:83], v[120:123], 0
	v_mfma_f32_16x16x32_bf16 v[36:39], v[68:71], v[100:103], v[36:39]
	v_mfma_f32_16x16x32_bf16 v[32:35], v[64:67], v[100:103], v[32:35]
	v_mfma_f32_16x16x32_bf16 v[28:31], v[60:63], v[100:103], v[28:31]
	v_mfma_f32_16x16x32_bf16 v[24:27], v[56:59], v[100:103], v[24:27]
	v_mfma_f32_16x16x32_bf16 v[100:103], v[84:87], v[120:123], 0
	s_waitcnt lgkmcnt(0)
	v_mfma_f32_16x16x32_bf16 v[100:103], v[76:79], v[104:107], v[100:103]
	v_mfma_f32_16x16x32_bf16 v[124:127], v[72:75], v[104:107], v[124:127]
	s_nop 6
	v_cndmask_b32_e64 v100, v204, v100, s[22:23]
	v_cndmask_b32_e64 v101, v204, v101, s[24:25]
	v_max3_f32 v128, v100, s75, v101
	v_cndmask_b32_e64 v102, v204, v102, s[26:27]
	v_cndmask_b32_e64 v103, v204, v103, s[28:29]
	v_max3_f32 v128, v128, v102, v103
	v_cndmask_b32_e64 v124, v204, v124, s[30:31]
	v_cndmask_b32_e64 v125, v204, v125, s[34:35]
	v_max3_f32 v128, v128, v124, v125
	v_cndmask_b32_e64 v126, v204, v126, s[36:37]
	v_cndmask_b32_e64 v127, v204, v127, s[38:39]
	v_max3_f32 v128, v128, v126, v127
	ds_bpermute_b32 v129, v183, v128
	s_waitcnt lgkmcnt(0)
	v_max_f32_e32 v129, v129, v129
	v_max_f32_e32 v128, v128, v129
	ds_bpermute_b32 v129, v186, v128
	s_waitcnt lgkmcnt(0)
	v_max3_f32 v196, v170, v128, v129
	v_sub_f32_e32 v128, v170, v196
	v_sub_f32_e32 v102, v102, v196
	v_exp_f32_e32 v171, v102
	v_sub_f32_e32 v102, v103, v196
	v_exp_f32_e32 v182, v128
	v_exp_f32_e32 v173, v102
	v_sub_f32_e32 v102, v124, v196
	v_sub_f32_e32 v100, v100, v196
	v_exp_f32_e32 v175, v102
	v_sub_f32_e32 v102, v125, v196
	v_exp_f32_e32 v100, v100
	v_sub_f32_e32 v101, v101, v196
	v_exp_f32_e32 v177, v102
	v_sub_f32_e32 v102, v126, v196
	v_exp_f32_e32 v101, v101
	v_exp_f32_e32 v179, v102
	v_sub_f32_e32 v102, v127, v196
	v_pk_mul_f32 v[134:135], v[46:47], v[182:183] op_sel_hi:[1,0]
	v_pk_mul_f32 v[132:133], v[44:45], v[182:183] op_sel_hi:[1,0]
	v_pk_mul_f32 v[126:127], v[22:23], v[182:183] op_sel_hi:[1,0]
	v_pk_mul_f32 v[124:125], v[20:21], v[182:183] op_sel_hi:[1,0]
	v_pk_mul_f32 v[46:47], v[18:19], v[182:183] op_sel_hi:[1,0]
	v_pk_mul_f32 v[44:45], v[16:17], v[182:183] op_sel_hi:[1,0]
	ds_read_b128 v[20:23], v174 offset:57344
	ds_read_b128 v[16:19], v172 offset:57344
	v_add_f32_e32 v129, 0, v100
	v_add_f32_e32 v185, v101, v129
	v_pk_mul_f32 v[130:131], v[42:43], v[182:183] op_sel_hi:[1,0]
	v_pk_mul_f32 v[128:129], v[40:41], v[182:183] op_sel_hi:[1,0]
	s_waitcnt lgkmcnt(1)
	v_mfma_f32_16x16x32_bf16 v[40:43], v[84:87], v[20:23], 0
	v_exp_f32_e32 v181, v102
	v_cvt_pk_bf16_f32 v100, v100, v101
	v_cvt_pk_bf16_f32 v101, v171, v173
	v_mfma_f32_16x16x32_bf16 v[80:83], v[80:83], v[20:23], 0
	v_cvt_pk_bf16_f32 v102, v175, v177
	v_cvt_pk_bf16_f32 v103, v179, v181
	s_waitcnt lgkmcnt(0)
	v_mfma_f32_16x16x32_bf16 v[40:43], v[76:79], v[16:19], v[40:43]
	v_mfma_f32_16x16x32_bf16 v[72:75], v[72:75], v[16:19], v[80:83]
	v_mfma_f32_16x16x32_bf16 v[80:83], v[56:59], v[100:103], v[44:47]
	s_nop 5
	v_cndmask_b32_e64 v40, v204, v40, s[22:23]
	v_cndmask_b32_e64 v41, v204, v41, s[24:25]
	v_max3_f32 v76, v40, s75, v41
	v_cndmask_b32_e64 v42, v204, v42, s[26:27]
	v_cndmask_b32_e64 v43, v204, v43, s[28:29]
	v_max3_f32 v76, v76, v42, v43
	v_cndmask_b32_e64 v72, v204, v72, s[30:31]
	v_cndmask_b32_e64 v73, v204, v73, s[34:35]
	v_max3_f32 v76, v76, v72, v73
	v_cndmask_b32_e64 v74, v204, v74, s[36:37]
	v_cndmask_b32_e64 v75, v204, v75, s[38:39]
	v_max3_f32 v76, v76, v74, v75
	ds_bpermute_b32 v77, v183, v76
	s_waitcnt lgkmcnt(0)
	v_max_f32_e32 v77, v77, v77
	v_max_f32_e32 v76, v76, v77
	ds_bpermute_b32 v77, v186, v76
	s_waitcnt lgkmcnt(0)
	v_max3_f32 v197, v188, v76, v77
	v_sub_f32_e32 v40, v40, v197
	v_exp_f32_e32 v214, v40
	v_sub_f32_e32 v41, v41, v197
	v_exp_f32_e32 v215, v41
	v_sub_f32_e32 v44, v188, v197
	v_add_f32_e32 v40, 0, v214
	v_mfma_f32_16x16x32_bf16 v[76:79], v[60:63], v[100:103], v[124:127]
	v_add_f32_e32 v184, v215, v40
	v_sub_f32_e32 v40, v42, v197
	v_exp_f32_e32 v170, v40
	v_sub_f32_e32 v42, v43, v197
	v_exp_f32_e32 v172, v42
	v_sub_f32_e32 v42, v72, v197
	v_exp_f32_e32 v174, v42
	v_sub_f32_e32 v42, v73, v197
	v_exp_f32_e32 v176, v42
	v_sub_f32_e32 v42, v74, v197
	v_pk_add_f32 v[40:41], v[170:171], v[184:185]
	v_exp_f32_e32 v178, v42
	v_sub_f32_e32 v42, v75, v197
	v_pk_add_f32 v[40:41], v[172:173], v[40:41]
	v_exp_f32_e32 v180, v42
	v_pk_add_f32 v[40:41], v[174:175], v[40:41]
	v_mfma_f32_16x16x32_bf16 v[72:75], v[64:67], v[100:103], v[128:131]
	v_add_f32_e64 v40, v176, v40
	v_add_f32_e64 v41, v177, v41
	v_cvt_pk_bf16_f32 v46, v174, v176
	v_cvt_pk_bf16_f32 v47, v178, v180
	v_pk_add_f32 v[40:41], v[178:179], v[40:41]
	s_nop 0
	v_pk_add_f32 v[40:41], v[180:181], v[40:41]
	ds_bpermute_b32 v43, v183, v41
	ds_bpermute_b32 v42, v183, v40
	s_waitcnt lgkmcnt(0)
	v_pk_add_f32 v[84:85], v[40:41], v[42:43]
	ds_bpermute_b32 v87, v186, v85
	ds_bpermute_b32 v86, v186, v84
	v_mfma_f32_16x16x32_bf16 v[40:43], v[68:71], v[100:103], v[132:135]
	v_exp_f32_e32 v100, v44
	v_mov_b32_e32 v101, v182
	s_waitcnt lgkmcnt(0)
	v_pk_add_f32 v[44:45], v[84:85], v[86:87]
	s_nop 0
	v_pk_fma_f32 v[134:135], v[164:165], v[100:101], v[44:45]
	v_cvt_pk_bf16_f32 v44, v214, v215
	v_cvt_pk_bf16_f32 v45, v170, v172
	v_pk_mul_f32 v[14:15], v[14:15], v[100:101] op_sel_hi:[1,0]
	v_pk_mul_f32 v[12:13], v[12:13], v[100:101] op_sel_hi:[1,0]
	v_pk_mul_f32 v[10:11], v[10:11], v[100:101] op_sel_hi:[1,0]
	v_pk_mul_f32 v[8:9], v[8:9], v[100:101] op_sel_hi:[1,0]
	v_pk_mul_f32 v[6:7], v[6:7], v[100:101] op_sel_hi:[1,0]
	v_pk_mul_f32 v[4:5], v[4:5], v[100:101] op_sel_hi:[1,0]
	v_pk_mul_f32 v[2:3], v[2:3], v[100:101] op_sel_hi:[1,0]
	v_pk_mul_f32 v[0:1], v[0:1], v[100:101] op_sel_hi:[1,0]
	v_mfma_f32_16x16x32_bf16 v[12:15], v[68:71], v[44:47], v[12:15]
	v_mfma_f32_16x16x32_bf16 v[8:11], v[64:67], v[44:47], v[8:11]
	v_mfma_f32_16x16x32_bf16 v[4:7], v[60:63], v[44:47], v[4:7]
	v_mfma_f32_16x16x32_bf16 v[0:3], v[56:59], v[44:47], v[0:3]
	ds_read_b128 v[124:127], v189 offset:4096
	ds_read_b128 v[44:47], v190 offset:4096
	ds_read_b128 v[128:131], v189 offset:6144
	ds_read_b128 v[84:87], v190 offset:6144
	ds_read2st64_b64 v[56:59], v191 offset0:16 offset1:20
	ds_read2st64_b64 v[64:67], v192 offset0:16 offset1:20
	s_waitcnt lgkmcnt(1)
	v_mov_b32_e32 v68, v56
	v_mfma_f32_16x16x32_bf16 v[100:103], v[124:127], v[52:55], 0
	v_mov_b32_e32 v69, v57
	s_waitcnt lgkmcnt(0)
	v_mov_b32_e32 v70, v64
	v_mov_b32_e32 v71, v65
	v_mfma_f32_16x16x32_bf16 v[52:55], v[128:131], v[52:55], 0
	v_mov_b32_e32 v64, v58
	v_mov_b32_e32 v65, v59
	ds_read_b64 v[60:61], v191 offset:12288
	ds_read_b64 v[62:63], v192 offset:12288
	ds_read_b64 v[56:57], v193 offset:8192
	ds_read_b64 v[58:59], v194 offset:8192
	v_mfma_f32_16x16x32_bf16 v[100:103], v[44:47], v[48:51], v[100:103]
	s_waitcnt lgkmcnt(0)
	s_waitcnt vmcnt(0)
	s_barrier
	v_mfma_f32_16x16x32_bf16 v[48:51], v[84:87], v[48:51], v[52:55]
	s_nop 4
	v_cndmask_b32_e32 v52, v204, v100, vcc
	v_cndmask_b32_e64 v53, v204, v101, s[8:9]
	v_max3_f32 v54, v52, s75, v53
	v_cndmask_b32_e64 v100, v204, v102, s[10:11]
	v_cndmask_b32_e64 v101, v204, v103, s[12:13]
	v_max3_f32 v54, v54, v100, v101
	v_cndmask_b32_e64 v48, v204, v48, s[14:15]
	v_cndmask_b32_e64 v49, v204, v49, s[16:17]
	v_max3_f32 v54, v54, v48, v49
	v_cndmask_b32_e64 v50, v204, v50, s[18:19]
	v_cndmask_b32_e64 v51, v204, v51, s[20:21]
	v_max3_f32 v54, v54, v50, v51
	ds_bpermute_b32 v55, v183, v54
	s_waitcnt lgkmcnt(0)
	v_max_f32_e32 v55, v55, v55
	v_max_f32_e32 v54, v54, v55
	ds_bpermute_b32 v55, v186, v54
	s_waitcnt lgkmcnt(0)
	v_max3_f32 v184, v151, v54, v55
	v_sub_f32_e32 v52, v52, v184
	v_exp_f32_e32 v55, v52
	v_sub_f32_e32 v52, v53, v184
	v_exp_f32_e32 v165, v52
	v_sub_f32_e32 v52, v100, v184
	v_exp_f32_e32 v171, v52
	v_sub_f32_e32 v52, v101, v184
	v_mfma_f32_16x16x32_bf16 v[100:103], v[124:127], v[92:95], 0
	v_sub_f32_e32 v54, v151, v184
	v_exp_f32_e32 v173, v52
	v_exp_f32_e32 v53, v54
	v_mfma_f32_16x16x32_bf16 v[92:95], v[128:131], v[92:95], 0
	v_sub_f32_e32 v48, v48, v184
	v_exp_f32_e32 v175, v48
	v_sub_f32_e32 v48, v49, v184
	v_mfma_f32_16x16x32_bf16 v[100:103], v[44:47], v[88:91], v[100:103]
	v_exp_f32_e32 v177, v48
	v_sub_f32_e32 v48, v50, v184
	v_exp_f32_e32 v179, v48
	v_mfma_f32_16x16x32_bf16 v[88:91], v[84:87], v[88:91], v[92:95]
	v_sub_f32_e32 v48, v51, v184
	s_nop 2
	v_cndmask_b32_e32 v52, v204, v100, vcc
	v_exp_f32_e32 v181, v48
	v_cndmask_b32_e64 v92, v204, v101, s[8:9]
	v_max3_f32 v54, v52, s75, v92
	v_cndmask_b32_e64 v93, v204, v102, s[10:11]
	v_cndmask_b32_e64 v94, v204, v103, s[12:13]
	v_max3_f32 v54, v54, v93, v94
	v_cndmask_b32_e64 v95, v204, v88, s[14:15]
	v_cndmask_b32_e64 v100, v204, v89, s[16:17]
	v_max3_f32 v54, v54, v95, v100
	v_cndmask_b32_e64 v90, v204, v90, s[18:19]
	v_cndmask_b32_e64 v91, v204, v91, s[20:21]
	v_max3_f32 v54, v54, v90, v91
	ds_bpermute_b32 v88, v183, v54
	v_mov_b32_e32 v188, v53
	v_cvt_pk_bf16_f32 v48, v55, v165
	v_cvt_pk_bf16_f32 v49, v171, v173
	v_cvt_pk_bf16_f32 v50, v175, v177
	s_waitcnt lgkmcnt(0)
	v_max_f32_e32 v88, v88, v88
	v_max_f32_e32 v54, v54, v88
	ds_bpermute_b32 v88, v186, v54
	v_cvt_pk_bf16_f32 v51, v179, v181
	s_waitcnt lgkmcnt(0)
	v_max3_f32 v182, v195, v54, v88
	v_sub_f32_e32 v52, v52, v182
	v_exp_f32_e32 v54, v52
	v_sub_f32_e32 v52, v92, v182
	v_exp_f32_e32 v164, v52
	v_sub_f32_e32 v52, v93, v182
	v_exp_f32_e32 v170, v52
	v_sub_f32_e32 v52, v94, v182
	v_exp_f32_e32 v172, v52
	v_sub_f32_e32 v52, v95, v182
	v_pk_add_f32 v[88:89], v[54:55], 0 op_sel_hi:[1,0]
	v_exp_f32_e32 v174, v52
	v_sub_f32_e32 v52, v100, v182
	v_pk_add_f32 v[88:89], v[164:165], v[88:89]
	v_exp_f32_e32 v176, v52
	v_sub_f32_e32 v52, v90, v182
	v_pk_add_f32 v[88:89], v[170:171], v[88:89]
	v_exp_f32_e32 v178, v52
	v_sub_f32_e32 v52, v91, v182
	v_pk_add_f32 v[88:89], v[172:173], v[88:89]
	v_exp_f32_e32 v180, v52
	v_pk_add_f32 v[88:89], v[174:175], v[88:89]
	v_sub_f32_e32 v52, v195, v182
	v_pk_add_f32 v[88:89], v[176:177], v[88:89]
	v_exp_f32_e32 v52, v52
	v_pk_add_f32 v[88:89], v[178:179], v[88:89]
	v_pk_mul_f32 v[38:39], v[38:39], v[52:53] op_sel_hi:[1,0]
	v_pk_add_f32 v[88:89], v[180:181], v[88:89]
	ds_bpermute_b32 v91, v183, v89
	ds_bpermute_b32 v90, v183, v88
	v_pk_mul_f32 v[36:37], v[36:37], v[52:53] op_sel_hi:[1,0]
	v_pk_mul_f32 v[34:35], v[34:35], v[52:53] op_sel_hi:[1,0]
	v_pk_mul_f32 v[32:33], v[32:33], v[52:53] op_sel_hi:[1,0]
	v_pk_mul_f32 v[30:31], v[30:31], v[52:53] op_sel_hi:[1,0]
	s_waitcnt lgkmcnt(0)
	v_pk_add_f32 v[88:89], v[88:89], v[90:91]
	ds_bpermute_b32 v91, v186, v89
	ds_bpermute_b32 v90, v186, v88
	v_pk_mul_f32 v[28:29], v[28:29], v[52:53] op_sel_hi:[1,0]
	v_pk_mul_f32 v[26:27], v[26:27], v[52:53] op_sel_hi:[1,0]
	v_pk_mul_f32 v[24:25], v[24:25], v[52:53] op_sel_hi:[1,0]
	s_waitcnt lgkmcnt(0)
	v_pk_add_f32 v[132:133], v[88:89], v[90:91]
	v_pk_mul_f32 v[90:91], v[98:99], v[188:189] op_sel_hi:[1,0]
	v_pk_mul_f32 v[88:89], v[96:97], v[188:189] op_sel_hi:[1,0]
	v_pk_fma_f32 v[132:133], v[166:167], v[52:53], v[132:133]
	s_nop 0
	v_mfma_f32_16x16x32_bf16 v[100:103], v[68:71], v[48:51], v[88:91]
	s_nop 2
	v_mul_f32_e64 v90, v110, v188
	v_mul_f32_e64 v91, v111, v188
	v_pk_mul_f32 v[88:89], v[108:109], v[188:189] op_sel_hi:[1,0]
	s_nop 1
	v_mfma_f32_16x16x32_bf16 v[96:99], v[64:67], v[48:51], v[88:91]
	s_nop 2
	v_mul_f32_e64 v90, v114, v188
	v_mul_f32_e64 v91, v115, v188
	v_pk_mul_f32 v[88:89], v[112:113], v[188:189] op_sel_hi:[1,0]
	s_nop 1
	v_mfma_f32_16x16x32_bf16 v[92:95], v[60:63], v[48:51], v[88:91]
	s_nop 2
	v_mul_f32_e64 v90, v118, v188
	v_mul_f32_e64 v91, v119, v188
	v_pk_mul_f32 v[88:89], v[116:117], v[188:189] op_sel_hi:[1,0]
	s_nop 1
	v_mfma_f32_16x16x32_bf16 v[88:91], v[56:59], v[48:51], v[88:91]
	v_cvt_pk_bf16_f32 v48, v54, v164
	v_cvt_pk_bf16_f32 v49, v170, v172
	v_cvt_pk_bf16_f32 v50, v174, v176
	v_cvt_pk_bf16_f32 v51, v178, v180
	v_mfma_f32_16x16x32_bf16 v[52:55], v[128:131], v[120:123], 0
	v_mfma_f32_16x16x32_bf16 v[36:39], v[68:71], v[48:51], v[36:39]
	v_mfma_f32_16x16x32_bf16 v[32:35], v[64:67], v[48:51], v[32:35]
	v_mfma_f32_16x16x32_bf16 v[28:31], v[60:63], v[48:51], v[28:31]
	v_mfma_f32_16x16x32_bf16 v[24:27], v[56:59], v[48:51], v[24:27]
	v_mfma_f32_16x16x32_bf16 v[48:51], v[124:127], v[120:123], 0
	v_mfma_f32_16x16x32_bf16 v[48:51], v[44:47], v[104:107], v[48:51]
	v_mfma_f32_16x16x32_bf16 v[118:121], v[124:127], v[20:23], 0
	v_mfma_f32_16x16x32_bf16 v[52:55], v[84:87], v[104:107], v[52:55]
	s_nop 5
	v_cndmask_b32_e32 v48, v204, v48, vcc
	v_cndmask_b32_e64 v49, v204, v49, s[8:9]
	v_max3_f32 v104, v48, s75, v49
	v_mfma_f32_16x16x32_bf16 v[20:23], v[128:131], v[20:23], 0
	v_cndmask_b32_e64 v50, v204, v50, s[10:11]
	v_cndmask_b32_e64 v51, v204, v51, s[12:13]
	v_max3_f32 v104, v104, v50, v51
	v_mfma_f32_16x16x32_bf16 v[44:47], v[44:47], v[16:19], v[118:121]
	v_cndmask_b32_e64 v52, v204, v52, s[14:15]
	v_cndmask_b32_e64 v53, v204, v53, s[16:17]
	v_max3_f32 v104, v104, v52, v53
	v_cndmask_b32_e64 v54, v204, v54, s[18:19]
	v_cndmask_b32_e64 v106, v204, v55, s[20:21]
	v_mfma_f32_16x16x32_bf16 v[16:19], v[84:87], v[16:19], v[20:23]
	v_max3_f32 v55, v104, v54, v106
	ds_bpermute_b32 v104, v183, v55
	s_waitcnt lgkmcnt(0)
	v_max_f32_e32 v104, v104, v104
	v_cndmask_b32_e32 v20, v204, v44, vcc
	v_cndmask_b32_e64 v21, v204, v45, s[8:9]
	v_max3_f32 v22, v20, s75, v21
	v_cndmask_b32_e64 v23, v204, v46, s[10:11]
	v_cndmask_b32_e64 v44, v204, v47, s[12:13]
	v_max3_f32 v22, v22, v23, v44
	v_cndmask_b32_e64 v45, v204, v16, s[14:15]
	v_cndmask_b32_e64 v46, v204, v17, s[16:17]
	v_max3_f32 v16, v22, v45, v46
	v_cndmask_b32_e64 v18, v204, v18, s[18:19]
	v_cndmask_b32_e64 v19, v204, v19, s[20:21]
	v_max3_f32 v16, v16, v18, v19
	ds_bpermute_b32 v17, v183, v16
	v_max_f32_e32 v55, v55, v104
	ds_bpermute_b32 v104, v186, v55
	s_andn2_b64 vcc, exec, s[4:5]
	s_waitcnt lgkmcnt(1)
	v_max_f32_e32 v17, v17, v17
	v_max_f32_e32 v16, v16, v17
	s_waitcnt lgkmcnt(0)
	v_max3_f32 v170, v196, v55, v104
	ds_bpermute_b32 v17, v186, v16
	v_sub_f32_e32 v48, v48, v170
	v_exp_f32_e32 v55, v48
	v_sub_f32_e32 v48, v49, v170
	v_exp_f32_e32 v105, v48
	v_sub_f32_e32 v48, v50, v170
	v_exp_f32_e32 v107, v48
	v_sub_f32_e32 v48, v51, v170
	v_exp_f32_e32 v109, v48
	v_sub_f32_e32 v48, v52, v170
	s_waitcnt lgkmcnt(0)
	v_max3_f32 v188, v197, v16, v17
	v_exp_f32_e32 v111, v48
	v_sub_f32_e32 v48, v53, v170
	v_sub_f32_e32 v16, v20, v188
	v_sub_f32_e32 v104, v196, v170
	v_exp_f32_e32 v113, v48
	v_sub_f32_e32 v48, v54, v170
	v_exp_f32_e32 v54, v16
	v_sub_f32_e32 v20, v21, v188
	v_exp_f32_e32 v53, v104
	v_exp_f32_e32 v104, v20
	v_sub_f32_e32 v20, v23, v188
	v_exp_f32_e32 v115, v48
	v_sub_f32_e32 v48, v106, v170
	v_exp_f32_e32 v106, v20
	v_sub_f32_e32 v20, v44, v188
	v_exp_f32_e32 v108, v20
	v_sub_f32_e32 v20, v45, v188
	v_pk_add_f32 v[16:17], v[54:55], 0 op_sel_hi:[1,0]
	v_exp_f32_e32 v110, v20
	v_sub_f32_e32 v20, v46, v188
	v_pk_add_f32 v[16:17], v[104:105], v[16:17]
	v_exp_f32_e32 v112, v20
	v_sub_f32_e32 v18, v18, v188
	v_pk_add_f32 v[16:17], v[106:107], v[16:17]
	v_exp_f32_e32 v114, v18
	v_sub_f32_e32 v18, v19, v188
	v_exp_f32_e32 v117, v48
	v_pk_add_f32 v[16:17], v[108:109], v[16:17]
	v_exp_f32_e32 v116, v18
	v_pk_add_f32 v[16:17], v[110:111], v[16:17]
	v_mov_b32_e32 v86, v53
	v_pk_add_f32 v[16:17], v[112:113], v[16:17]
	v_cvt_pk_bf16_f32 v48, v55, v105
	v_cvt_pk_bf16_f32 v49, v107, v109
	v_cvt_pk_bf16_f32 v50, v111, v113
	v_cvt_pk_bf16_f32 v51, v115, v117
	s_nop 0
	v_pk_add_f32 v[16:17], v[114:115], v[16:17]
	s_nop 0
	v_pk_add_f32 v[16:17], v[116:117], v[16:17]
	ds_bpermute_b32 v19, v183, v17
	ds_bpermute_b32 v18, v183, v16
	s_waitcnt lgkmcnt(0)
	v_pk_add_f32 v[16:17], v[16:17], v[18:19]
	v_sub_f32_e32 v18, v197, v188
	ds_bpermute_b32 v19, v186, v17
	v_exp_f32_e32 v52, v18
	ds_bpermute_b32 v18, v186, v16
	v_pk_mul_f32 v[14:15], v[14:15], v[52:53] op_sel_hi:[1,0]
	v_pk_mul_f32 v[12:13], v[12:13], v[52:53] op_sel_hi:[1,0]
	s_waitcnt lgkmcnt(0)
	v_pk_add_f32 v[84:85], v[16:17], v[18:19]
	v_pk_mul_f32 v[18:19], v[42:43], v[86:87] op_sel_hi:[1,0]
	v_pk_mul_f32 v[16:17], v[40:41], v[86:87] op_sel_hi:[1,0]
	v_pk_mul_f32 v[10:11], v[10:11], v[52:53] op_sel_hi:[1,0]
	v_pk_mul_f32 v[8:9], v[8:9], v[52:53] op_sel_hi:[1,0]
	v_mfma_f32_16x16x32_bf16 v[44:47], v[68:71], v[48:51], v[16:19]
	v_mul_f32_e64 v6, v6, v52
	v_mul_f32_e64 v7, v7, v52
	v_pk_mul_f32 v[4:5], v[4:5], v[52:53] op_sel_hi:[1,0]
	v_pk_mul_f32 v[2:3], v[2:3], v[52:53] op_sel_hi:[1,0]
	v_pk_mul_f32 v[18:19], v[74:75], v[86:87] op_sel_hi:[1,0]
	v_pk_mul_f32 v[16:17], v[72:73], v[86:87] op_sel_hi:[1,0]
	v_pk_mul_f32 v[0:1], v[0:1], v[52:53] op_sel_hi:[1,0]
	v_pk_fma_f32 v[164:165], v[134:135], v[52:53], v[84:85]
	v_mfma_f32_16x16x32_bf16 v[40:43], v[64:67], v[48:51], v[16:19]
	s_nop 2
	v_mul_f32_e64 v18, v78, v86
	v_mul_f32_e64 v19, v79, v86
	v_pk_mul_f32 v[16:17], v[76:77], v[86:87] op_sel_hi:[1,0]
	s_nop 1
	v_mfma_f32_16x16x32_bf16 v[20:23], v[60:63], v[48:51], v[16:19]
	s_nop 2
	v_mul_f32_e64 v18, v82, v86
	v_mul_f32_e64 v19, v83, v86
	v_pk_mul_f32 v[16:17], v[80:81], v[86:87] op_sel_hi:[1,0]
	s_nop 1
	v_mfma_f32_16x16x32_bf16 v[16:19], v[56:59], v[48:51], v[16:19]
	v_cvt_pk_bf16_f32 v48, v54, v104
	v_cvt_pk_bf16_f32 v49, v106, v108
	v_cvt_pk_bf16_f32 v50, v110, v112
	v_cvt_pk_bf16_f32 v51, v114, v116
	s_nop 0
	v_mfma_f32_16x16x32_bf16 v[12:15], v[68:71], v[48:51], v[12:15]
	v_mfma_f32_16x16x32_bf16 v[8:11], v[64:67], v[48:51], v[8:11]
	v_mfma_f32_16x16x32_bf16 v[4:7], v[60:63], v[48:51], v[4:7]
	v_mfma_f32_16x16x32_bf16 v[0:3], v[56:59], v[48:51], v[0:3]
	v_cndmask_b32_e64 v48, 0, 1, s[6:7]
	s_nop 0
	v_readfirstlane_b32 s6, v48
	s_xor_b32 s84, s84, s6
	s_cbranch_vccz .LBB0_69
	v_mov_b32_e32 v50, v187
	v_mov_b64_e32 v[48:49], v[162:163]
	s_branch .LBB0_111

.LBB0_362:
	s_lshr_b32 s4, s20, 2
	s_and_b32 s4, s4, 24
	s_and_b32 s5, s20, 7
	s_or_b32 s4, s4, s5
	s_lshl_b32 s4, s4, 10
	v_mov_b32 v8, v198
	s_or_b32 s4, s4, s65
	v_ashrrev_i32_e32 v12, 2, v8
	v_add_u32_e32 v0, s4, v12
	s_waitcnt lgkmcnt(0)
	v_ashrrev_i32_e32 v1, 31, v0
	s_lshl_b32 s5, s20, 5
	v_lshlrev_b64 v[0:1], 13, v[0:1]
	v_lshlrev_b32_e32 v2, 4, v8
	s_and_b32 s5, s5, 0x300
	v_lshl_add_u64 v[0:1], s[92:93], 0, v[0:1]
	v_and_b32_e32 v152, 48, v2
	v_lshl_add_u64 v[14:15], v[0:1], 0, v[152:153]
	v_add_u32_e32 v0, s5, v12
	v_ashrrev_i32_e32 v1, 31, v0
	v_lshlrev_b64 v[0:1], 13, v[0:1]
	s_mov_b32 s12, 0x80000
	v_lshl_add_u64 v[0:1], s[6:7], 0, v[0:1]
	v_add_co_u32_e32 v54, vcc, s12, v14
	v_lshl_add_u64 v[0:1], v[0:1], 0, v[152:153]
	s_nop 0
	v_addc_co_u32_e32 v55, vcc, 0, v15, vcc
	s_lshl_b32 s13, s19, 13
	s_lshl_b32 s21, s20, 8
	s_and_b32 s22, s18, 7
	v_lshrrev_b32_e32 v6, 2, v8
	v_add_co_u32_e32 v2, vcc, s12, v0
	s_and_b32 s13, s13, 0x600000
	s_and_b32 s21, s21, 0x6000
	s_lshl_b32 s24, s22, 10
	v_and_b32_e32 v6, 12, v6
	s_movk_i32 s22, 0x1230
	v_addc_co_u32_e32 v3, vcc, 0, v1, vcc
	s_mov_b32 s12, 0x100000
	v_lshrrev_b32_e64 v10, v6, s22
	s_add_u32 s22, s15, s13
	v_add_co_u32_e32 v4, vcc, s12, v0
	s_addc_u32 s23, s16, 0
	s_or_b32 s13, s24, s21
	v_addc_co_u32_e32 v5, vcc, 0, v1, vcc
	s_mov_b32 s12, 0x180000
	v_and_b32_e32 v22, 3, v8
	v_ashrrev_i32_e32 v13, 31, v12
	v_xor_b32_e32 v8, v10, v8
	s_or_b32 s13, s13, s65
	v_add_co_u32_e32 v20, vcc, s12, v0
	v_lshlrev_b32_e32 v9, 6, v12
	v_lshlrev_b64 v[6:7], 13, v[12:13]
	v_lshlrev_b32_e32 v8, 4, v8
	v_add_u32_e32 v12, s13, v12
	v_addc_co_u32_e32 v21, vcc, 0, v1, vcc
	s_nop 0
	v_readfirstlane_b32 s26, v14
	v_readfirstlane_b32 s27, v15
	v_readfirstlane_b32 s28, v0
	v_readfirstlane_b32 s29, v1
	v_lshrrev_b32_e32 v250, 6, v198
	s_nop 0
	v_readfirstlane_b32 s24, v250
	s_lshl_b32 s24, s24, 10
	v_lshrrev_b32_e32 v250, 2, v200
	v_lshrrev_b32_e32 v251, 4, v200
	v_lshlrev_b32_e32 v251, 2, v251
	v_mov_b32_e32 v248, 0x1230
	v_lshrrev_b32_e32 v251, v251, v248
	v_xor_b32_e32 v251, v251, v200
	v_and_b32_e32 v251, 3, v251
	v_lshlrev_b32_e32 v251, 4, v251
	v_lshl_add_u32 v244, v250, 13, v251
	v_add_u32_e32 v245, 0x80000, v244
	v_add_u32_e32 v246, 0x100000, v244
	v_add_u32_e32 v247, 0x180000, v244
	s_mov_b32 s25, 0
	s_add_u32 m0, s25, s24
	s_nop 0
	global_load_lds_dwordx4 v244, s[26:27]
	s_add_u32 m0, m0, 0x1000
	s_nop 0
	global_load_lds_dwordx4 v245, s[26:27]
	s_add_u32 m0, m0, 0x1000
	s_nop 0
	global_load_lds_dwordx4 v244, s[28:29]
	s_add_u32 m0, m0, 0x1000
	s_nop 0
	global_load_lds_dwordx4 v245, s[28:29]
	s_add_u32 m0, m0, 0x1000
	s_nop 0
	global_load_lds_dwordx4 v246, s[28:29]
	s_add_u32 m0, m0, 0x1000
	s_nop 0
	global_load_lds_dwordx4 v247, s[28:29]
	s_add_u32 s26, s26, 64
	s_addc_u32 s27, s27, 0
	s_add_u32 s28, s28, 64
	s_addc_u32 s29, s29, 0
	s_add_u32 s25, s25, 24576
	s_cmp_eq_u32 s25, 73728
	s_cselect_b32 s25, 0, s25
	s_add_u32 m0, s25, s24
	s_nop 0
	global_load_lds_dwordx4 v244, s[26:27]
	s_add_u32 m0, m0, 0x1000
	s_nop 0
	global_load_lds_dwordx4 v245, s[26:27]
	s_add_u32 m0, m0, 0x1000
	s_nop 0
	global_load_lds_dwordx4 v244, s[28:29]
	s_add_u32 m0, m0, 0x1000
	s_nop 0
	global_load_lds_dwordx4 v245, s[28:29]
	s_add_u32 m0, m0, 0x1000
	s_nop 0
	global_load_lds_dwordx4 v246, s[28:29]
	s_add_u32 m0, m0, 0x1000
	s_nop 0
	global_load_lds_dwordx4 v247, s[28:29]
	s_add_u32 s26, s26, 64
	s_addc_u32 s27, s27, 0
	s_add_u32 s28, s28, 64
	s_addc_u32 s29, s29, 0
	s_add_u32 s25, s25, 24576
	s_cmp_eq_u32 s25, 73728
	s_cselect_b32 s25, 0, s25
	s_add_u32 m0, s25, s24
	s_nop 0
	global_load_lds_dwordx4 v244, s[26:27]
	s_add_u32 m0, m0, 0x1000
	s_nop 0
	global_load_lds_dwordx4 v245, s[26:27]
	s_add_u32 m0, m0, 0x1000
	s_nop 0
	global_load_lds_dwordx4 v244, s[28:29]
	s_add_u32 m0, m0, 0x1000
	s_nop 0
	global_load_lds_dwordx4 v245, s[28:29]
	s_add_u32 m0, m0, 0x1000
	s_nop 0
	global_load_lds_dwordx4 v246, s[28:29]
	s_add_u32 m0, m0, 0x1000
	s_nop 0
	global_load_lds_dwordx4 v247, s[28:29]
	s_add_u32 s26, s26, 64
	s_addc_u32 s27, s27, 0
	s_add_u32 s28, s28, 64
	s_addc_u32 s29, s29, 0
	s_add_u32 s25, s25, 24576
	s_cmp_eq_u32 s25, 73728
	s_cselect_b32 s25, 0, s25
	v_mov_b32_e32 v24, 0
	v_mov_b32_e32 v25, v24
	v_mov_b32_e32 v26, v24
	v_mov_b32_e32 v27, v24
	v_mov_b32_e32 v28, v24
	v_mov_b32_e32 v29, v24
	v_mov_b32_e32 v54, v24
	v_mov_b32_e32 v55, v24
	v_mov_b32_e32 v56, v24
	v_mov_b32_e32 v57, v24
	v_mov_b32_e32 v58, v24
	v_mov_b32_e32 v59, v24
	v_mov_b32_e32 v64, v24
	v_mov_b32_e32 v65, v24
	v_mov_b32_e32 v66, v24
	v_mov_b32_e32 v67, v24
	v_mov_b32_e32 v68, v24
	v_mov_b32_e32 v69, v24
	v_mov_b32_e32 v70, v24
	v_mov_b32_e32 v71, v24
	v_mov_b32_e32 v60, v24
	v_mov_b32_e32 v61, v24
	v_mov_b32_e32 v62, v24
	v_mov_b32_e32 v63, v24
	v_mov_b32_e32 v100, v24
	v_mov_b32_e32 v30, v24
	v_mov_b32_e32 v31, v24
	v_mov_b32_e32 v32, v24
	v_mov_b32_e32 v33, v24
	v_mov_b32_e32 v34, v24
	v_mov_b32_e32 v35, v24
	v_mov_b32_e32 v36, v24
	v_mov_b32_e32 v37, v24
	v_mov_b32_e32 v38, v24
	v_mov_b32_e32 v39, v24
	v_mov_b32_e32 v52, v24
	v_mov_b32_e32 v53, v24
	v_mov_b32_e32 v40, v24
	v_mov_b32_e32 v41, v24
	v_mov_b32_e32 v42, v24
	v_mov_b32_e32 v43, v24
	v_mov_b32_e32 v44, v24
	v_mov_b32_e32 v45, v24
	v_mov_b32_e32 v46, v24
	v_mov_b32_e32 v47, v24
	v_mov_b32_e32 v48, v24
	v_mov_b32_e32 v49, v24
	v_mov_b32_e32 v50, v24
	v_mov_b32_e32 v51, v24
	v_mov_b32_e32 v101, v24
	v_mov_b32_e32 v102, v24
	v_mov_b32_e32 v103, v24
	v_mov_b32_e32 v104, v24
	v_mov_b32_e32 v105, v24
	v_mov_b32_e32 v106, v24
	v_mov_b32_e32 v107, v24
	v_mov_b32_e32 v120, v24
	v_mov_b32_e32 v121, v24
	v_mov_b32_e32 v122, v24
	v_mov_b32_e32 v123, v24
	v_mov_b32_e32 v128, v24
	v_mov_b32_e32 v129, v24
	v_mov_b32_e32 v130, v24
	v_mov_b32_e32 v131, v24
	v_mov_b32_e32 v108, v24
	v_mov_b32_e32 v109, v24
	v_mov_b32_e32 v110, v24
	v_mov_b32_e32 v111, v24
	v_mov_b32_e32 v112, v24
	v_mov_b32_e32 v113, v24
	v_mov_b32_e32 v114, v24
	v_mov_b32_e32 v115, v24
	v_mov_b32_e32 v116, v24
	v_mov_b32_e32 v117, v24
	v_mov_b32_e32 v118, v24
	v_mov_b32_e32 v119, v24
	v_mov_b32_e32 v124, v24
	v_mov_b32_e32 v125, v24
	v_mov_b32_e32 v126, v24
	v_mov_b32_e32 v127, v24
	v_mov_b32_e32 v80, v24
	v_mov_b32_e32 v81, v24
	v_mov_b32_e32 v82, v24
	v_mov_b32_e32 v83, v24
	v_mov_b32_e32 v84, v24
	v_mov_b32_e32 v85, v24
	v_mov_b32_e32 v86, v24
	v_mov_b32_e32 v87, v24
	v_mov_b32_e32 v96, v24
	v_mov_b32_e32 v97, v24
	v_mov_b32_e32 v98, v24
	v_mov_b32_e32 v99, v24
	v_mov_b32_e32 v72, v24
	v_mov_b32_e32 v73, v24
	v_mov_b32_e32 v74, v24
	v_mov_b32_e32 v75, v24
	v_mov_b32_e32 v132, v24
	v_mov_b32_e32 v133, v24
	v_mov_b32_e32 v134, v24
	v_mov_b32_e32 v135, v24
	v_mov_b32_e32 v136, v24
	v_mov_b32_e32 v137, v24
	v_mov_b32_e32 v138, v24
	v_mov_b32_e32 v139, v24
	v_mov_b32_e32 v140, v24
	v_mov_b32_e32 v141, v24
	v_mov_b32_e32 v142, v24
	v_mov_b32_e32 v143, v24
	v_mov_b32_e32 v144, v24
	v_mov_b32_e32 v145, v24
	v_mov_b32_e32 v146, v24
	v_mov_b32_e32 v147, v24
	v_mov_b32_e32 v92, v24
	v_mov_b32_e32 v93, v24
	v_mov_b32_e32 v94, v24
	v_mov_b32_e32 v95, v24
	v_mov_b32_e32 v88, v24
	v_mov_b32_e32 v89, v24
	v_mov_b32_e32 v90, v24
	v_mov_b32_e32 v91, v24
	v_mov_b32_e32 v76, v24
	v_mov_b32_e32 v77, v24
	v_mov_b32_e32 v78, v24
	v_mov_b32_e32 v79, v24
	v_mov_b32_e32 v148, v24
	v_mov_b32_e32 v149, v24
	v_mov_b32_e32 v150, v24
	v_mov_b32_e32 v151, v24
	s_waitcnt vmcnt(12)
	s_barrier
	s_mov_b32 s30, 0
	v_add_u32_e32 v248, s30, v155
	v_add_u32_e32 v249, s30, v160
	ds_read_b128 v[186:189], v248
	ds_read_b128 v[212:215], v249 offset:8192
	ds_read_b128 v[190:193], v248 offset:1024
	ds_read_b128 v[216:219], v249 offset:9216
	ds_read_b128 v[194:197], v248 offset:2048
	ds_read_b128 v[220:223], v249 offset:10240
	ds_read_b128 v[208:211], v248 offset:3072
	ds_read_b128 v[224:227], v249 offset:11264
	ds_read_b128 v[228:231], v249 offset:12288
	ds_read_b128 v[232:235], v249 offset:13312
	ds_read_b128 v[236:239], v249 offset:14336
	ds_read_b128 v[240:243], v249 offset:15360
	s_add_u32 s30, s30, 24576
	s_cmp_eq_u32 s30, 73728
	s_cselect_b32 s30, 0, s30
	s_waitcnt vmcnt(6)
	s_waitcnt lgkmcnt(0)
	s_barrier
	s_mov_b32 s31, 62
.Lgm2_loop:
	v_add_u32_e32 v248, s30, v155
	v_add_u32_e32 v249, s30, v160
	v_mfma_f32_16x16x32_bf16 v[128:131], v[212:215], v[186:189], v[128:131]
	ds_read_b128 v[0:3], v248
	v_mfma_f32_16x16x32_bf16 v[68:71], v[212:215], v[190:193], v[68:71]
	ds_read_b128 v[16:19], v249 offset:8192
	v_mfma_f32_16x16x32_bf16 v[108:111], v[212:215], v[194:197], v[108:111]
	ds_read_b128 v[4:7], v248 offset:1024
	v_mfma_f32_16x16x32_bf16 v[132:135], v[212:215], v[208:211], v[132:135]
	ds_read_b128 v[20:23], v249 offset:9216
	v_mfma_f32_16x16x32_bf16 v[120:123], v[216:219], v[186:189], v[120:123]
	ds_read_b128 v[8:11], v248 offset:2048
	v_mfma_f32_16x16x32_bf16 v[64:67], v[216:219], v[190:193], v[64:67]
	ds_read_b128 v[162:165], v249 offset:10240
	v_mfma_f32_16x16x32_bf16 v[112:115], v[216:219], v[194:197], v[112:115]
	ds_read_b128 v[12:15], v248 offset:3072
	v_mfma_f32_16x16x32_bf16 v[136:139], v[216:219], v[208:211], v[136:139]
	ds_read_b128 v[166:169], v249 offset:11264
	v_mfma_f32_16x16x32_bf16 v[104:107], v[220:223], v[186:189], v[104:107]
	ds_read_b128 v[170:173], v249 offset:12288
	v_mfma_f32_16x16x32_bf16 v[56:59], v[220:223], v[190:193], v[56:59]
	ds_read_b128 v[174:177], v249 offset:13312
	v_mfma_f32_16x16x32_bf16 v[116:119], v[220:223], v[194:197], v[116:119]
	ds_read_b128 v[178:181], v249 offset:14336
	v_mfma_f32_16x16x32_bf16 v[140:143], v[220:223], v[208:211], v[140:143]
	ds_read_b128 v[182:185], v249 offset:15360
	s_add_u32 m0, s25, s24
	v_mfma_f32_16x16x32_bf16 v[100:103], v[224:227], v[186:189], v[100:103]
	global_load_lds_dwordx4 v244, s[26:27]
	v_mfma_f32_16x16x32_bf16 v[52:55], v[224:227], v[190:193], v[52:55]
	v_mfma_f32_16x16x32_bf16 v[124:127], v[224:227], v[194:197], v[124:127]
	s_add_u32 m0, m0, 0x1000
	v_mfma_f32_16x16x32_bf16 v[144:147], v[224:227], v[208:211], v[144:147]
	global_load_lds_dwordx4 v245, s[26:27]
	v_mfma_f32_16x16x32_bf16 v[60:63], v[228:231], v[186:189], v[60:63]
	v_mfma_f32_16x16x32_bf16 v[36:39], v[228:231], v[190:193], v[36:39]
	s_add_u32 m0, m0, 0x1000
	v_mfma_f32_16x16x32_bf16 v[80:83], v[228:231], v[194:197], v[80:83]
	global_load_lds_dwordx4 v244, s[28:29]
	v_mfma_f32_16x16x32_bf16 v[92:95], v[228:231], v[208:211], v[92:95]
	v_mfma_f32_16x16x32_bf16 v[48:51], v[232:235], v[186:189], v[48:51]
	s_add_u32 m0, m0, 0x1000
	v_mfma_f32_16x16x32_bf16 v[32:35], v[232:235], v[190:193], v[32:35]
	global_load_lds_dwordx4 v245, s[28:29]
	v_mfma_f32_16x16x32_bf16 v[84:87], v[232:235], v[194:197], v[84:87]
	v_mfma_f32_16x16x32_bf16 v[88:91], v[232:235], v[208:211], v[88:91]
	s_add_u32 m0, m0, 0x1000
	v_mfma_f32_16x16x32_bf16 v[44:47], v[236:239], v[186:189], v[44:47]
	global_load_lds_dwordx4 v246, s[28:29]
	v_mfma_f32_16x16x32_bf16 v[28:31], v[236:239], v[190:193], v[28:31]
	v_mfma_f32_16x16x32_bf16 v[96:99], v[236:239], v[194:197], v[96:99]
	s_add_u32 m0, m0, 0x1000
	v_mfma_f32_16x16x32_bf16 v[76:79], v[236:239], v[208:211], v[76:79]
	global_load_lds_dwordx4 v247, s[28:29]
	v_mfma_f32_16x16x32_bf16 v[40:43], v[240:243], v[186:189], v[40:43]
	v_mfma_f32_16x16x32_bf16 v[24:27], v[240:243], v[190:193], v[24:27]
	v_mfma_f32_16x16x32_bf16 v[72:75], v[240:243], v[194:197], v[72:75]
	v_mfma_f32_16x16x32_bf16 v[148:151], v[240:243], v[208:211], v[148:151]
	s_add_u32 s26, s26, 64
	s_addc_u32 s27, s27, 0
	s_add_u32 s28, s28, 64
	s_addc_u32 s29, s29, 0
	s_add_u32 s25, s25, 24576
	s_cmp_eq_u32 s25, 73728
	s_cselect_b32 s25, 0, s25
	s_add_u32 s30, s30, 24576
	s_cmp_eq_u32 s30, 73728
	s_cselect_b32 s30, 0, s30
	s_waitcnt vmcnt(6)
	s_waitcnt lgkmcnt(0)
	s_barrier
	v_add_u32_e32 v248, s30, v155
	v_add_u32_e32 v249, s30, v160
	v_mfma_f32_16x16x32_bf16 v[128:131], v[16:19], v[0:3], v[128:131]
	ds_read_b128 v[186:189], v248
	v_mfma_f32_16x16x32_bf16 v[68:71], v[16:19], v[4:7], v[68:71]
	ds_read_b128 v[212:215], v249 offset:8192
	v_mfma_f32_16x16x32_bf16 v[108:111], v[16:19], v[8:11], v[108:111]
	ds_read_b128 v[190:193], v248 offset:1024
	v_mfma_f32_16x16x32_bf16 v[132:135], v[16:19], v[12:15], v[132:135]
	ds_read_b128 v[216:219], v249 offset:9216
	v_mfma_f32_16x16x32_bf16 v[120:123], v[20:23], v[0:3], v[120:123]
	ds_read_b128 v[194:197], v248 offset:2048
	v_mfma_f32_16x16x32_bf16 v[64:67], v[20:23], v[4:7], v[64:67]
	ds_read_b128 v[220:223], v249 offset:10240
	v_mfma_f32_16x16x32_bf16 v[112:115], v[20:23], v[8:11], v[112:115]
	ds_read_b128 v[208:211], v248 offset:3072
	v_mfma_f32_16x16x32_bf16 v[136:139], v[20:23], v[12:15], v[136:139]
	ds_read_b128 v[224:227], v249 offset:11264
	v_mfma_f32_16x16x32_bf16 v[104:107], v[162:165], v[0:3], v[104:107]
	ds_read_b128 v[228:231], v249 offset:12288
	v_mfma_f32_16x16x32_bf16 v[56:59], v[162:165], v[4:7], v[56:59]
	ds_read_b128 v[232:235], v249 offset:13312
	v_mfma_f32_16x16x32_bf16 v[116:119], v[162:165], v[8:11], v[116:119]
	ds_read_b128 v[236:239], v249 offset:14336
	v_mfma_f32_16x16x32_bf16 v[140:143], v[162:165], v[12:15], v[140:143]
	ds_read_b128 v[240:243], v249 offset:15360
	s_add_u32 m0, s25, s24
	v_mfma_f32_16x16x32_bf16 v[100:103], v[166:169], v[0:3], v[100:103]
	global_load_lds_dwordx4 v244, s[26:27]
	v_mfma_f32_16x16x32_bf16 v[52:55], v[166:169], v[4:7], v[52:55]
	v_mfma_f32_16x16x32_bf16 v[124:127], v[166:169], v[8:11], v[124:127]
	s_add_u32 m0, m0, 0x1000
	v_mfma_f32_16x16x32_bf16 v[144:147], v[166:169], v[12:15], v[144:147]
	global_load_lds_dwordx4 v245, s[26:27]
	v_mfma_f32_16x16x32_bf16 v[60:63], v[170:173], v[0:3], v[60:63]
	v_mfma_f32_16x16x32_bf16 v[36:39], v[170:173], v[4:7], v[36:39]
	s_add_u32 m0, m0, 0x1000
	v_mfma_f32_16x16x32_bf16 v[80:83], v[170:173], v[8:11], v[80:83]
	global_load_lds_dwordx4 v244, s[28:29]
	v_mfma_f32_16x16x32_bf16 v[92:95], v[170:173], v[12:15], v[92:95]
	v_mfma_f32_16x16x32_bf16 v[48:51], v[174:177], v[0:3], v[48:51]
	s_add_u32 m0, m0, 0x1000
	v_mfma_f32_16x16x32_bf16 v[32:35], v[174:177], v[4:7], v[32:35]
	global_load_lds_dwordx4 v245, s[28:29]
	v_mfma_f32_16x16x32_bf16 v[84:87], v[174:177], v[8:11], v[84:87]
	v_mfma_f32_16x16x32_bf16 v[88:91], v[174:177], v[12:15], v[88:91]
	s_add_u32 m0, m0, 0x1000
	v_mfma_f32_16x16x32_bf16 v[44:47], v[178:181], v[0:3], v[44:47]
	global_load_lds_dwordx4 v246, s[28:29]
	v_mfma_f32_16x16x32_bf16 v[28:31], v[178:181], v[4:7], v[28:31]
	v_mfma_f32_16x16x32_bf16 v[96:99], v[178:181], v[8:11], v[96:99]
	s_add_u32 m0, m0, 0x1000
	v_mfma_f32_16x16x32_bf16 v[76:79], v[178:181], v[12:15], v[76:79]
	global_load_lds_dwordx4 v247, s[28:29]
	v_mfma_f32_16x16x32_bf16 v[40:43], v[182:185], v[0:3], v[40:43]
	v_mfma_f32_16x16x32_bf16 v[24:27], v[182:185], v[4:7], v[24:27]
	v_mfma_f32_16x16x32_bf16 v[72:75], v[182:185], v[8:11], v[72:75]
	v_mfma_f32_16x16x32_bf16 v[148:151], v[182:185], v[12:15], v[148:151]
	s_add_u32 s26, s26, 64
	s_addc_u32 s27, s27, 0
	s_add_u32 s28, s28, 64
	s_addc_u32 s29, s29, 0
	s_add_u32 s25, s25, 24576
	s_cmp_eq_u32 s25, 73728
	s_cselect_b32 s25, 0, s25
	s_add_u32 s30, s30, 24576
	s_cmp_eq_u32 s30, 73728
	s_cselect_b32 s30, 0, s30
	s_waitcnt vmcnt(6)
	s_waitcnt lgkmcnt(0)
	s_barrier
	s_sub_u32 s31, s31, 1
	s_cmp_lg_u32 s31, 0
	s_cbranch_scc1 .Lgm2_loop
	v_add_u32_e32 v248, s30, v155
	v_add_u32_e32 v249, s30, v160
	v_mfma_f32_16x16x32_bf16 v[128:131], v[212:215], v[186:189], v[128:131]
	ds_read_b128 v[0:3], v248
	v_mfma_f32_16x16x32_bf16 v[68:71], v[212:215], v[190:193], v[68:71]
	ds_read_b128 v[16:19], v249 offset:8192
	v_mfma_f32_16x16x32_bf16 v[108:111], v[212:215], v[194:197], v[108:111]
	ds_read_b128 v[4:7], v248 offset:1024
	v_mfma_f32_16x16x32_bf16 v[132:135], v[212:215], v[208:211], v[132:135]
	ds_read_b128 v[20:23], v249 offset:9216
	v_mfma_f32_16x16x32_bf16 v[120:123], v[216:219], v[186:189], v[120:123]
	ds_read_b128 v[8:11], v248 offset:2048
	v_mfma_f32_16x16x32_bf16 v[64:67], v[216:219], v[190:193], v[64:67]
	ds_read_b128 v[162:165], v249 offset:10240
	v_mfma_f32_16x16x32_bf16 v[112:115], v[216:219], v[194:197], v[112:115]
	ds_read_b128 v[12:15], v248 offset:3072
	v_mfma_f32_16x16x32_bf16 v[136:139], v[216:219], v[208:211], v[136:139]
	ds_read_b128 v[166:169], v249 offset:11264
	v_mfma_f32_16x16x32_bf16 v[104:107], v[220:223], v[186:189], v[104:107]
	ds_read_b128 v[170:173], v249 offset:12288
	v_mfma_f32_16x16x32_bf16 v[56:59], v[220:223], v[190:193], v[56:59]
	ds_read_b128 v[174:177], v249 offset:13312
	v_mfma_f32_16x16x32_bf16 v[116:119], v[220:223], v[194:197], v[116:119]
	ds_read_b128 v[178:181], v249 offset:14336
	v_mfma_f32_16x16x32_bf16 v[140:143], v[220:223], v[208:211], v[140:143]
	ds_read_b128 v[182:185], v249 offset:15360
	s_add_u32 m0, s25, s24
	v_mfma_f32_16x16x32_bf16 v[100:103], v[224:227], v[186:189], v[100:103]
	global_load_lds_dwordx4 v244, s[26:27]
	v_mfma_f32_16x16x32_bf16 v[52:55], v[224:227], v[190:193], v[52:55]
	v_mfma_f32_16x16x32_bf16 v[124:127], v[224:227], v[194:197], v[124:127]
	s_add_u32 m0, m0, 0x1000
	v_mfma_f32_16x16x32_bf16 v[144:147], v[224:227], v[208:211], v[144:147]
	global_load_lds_dwordx4 v245, s[26:27]
	v_mfma_f32_16x16x32_bf16 v[60:63], v[228:231], v[186:189], v[60:63]
	v_mfma_f32_16x16x32_bf16 v[36:39], v[228:231], v[190:193], v[36:39]
	s_add_u32 m0, m0, 0x1000
	v_mfma_f32_16x16x32_bf16 v[80:83], v[228:231], v[194:197], v[80:83]
	global_load_lds_dwordx4 v244, s[28:29]
	v_mfma_f32_16x16x32_bf16 v[92:95], v[228:231], v[208:211], v[92:95]
	v_mfma_f32_16x16x32_bf16 v[48:51], v[232:235], v[186:189], v[48:51]
	s_add_u32 m0, m0, 0x1000
	v_mfma_f32_16x16x32_bf16 v[32:35], v[232:235], v[190:193], v[32:35]
	global_load_lds_dwordx4 v245, s[28:29]
	v_mfma_f32_16x16x32_bf16 v[84:87], v[232:235], v[194:197], v[84:87]
	v_mfma_f32_16x16x32_bf16 v[88:91], v[232:235], v[208:211], v[88:91]
	s_add_u32 m0, m0, 0x1000
	v_mfma_f32_16x16x32_bf16 v[44:47], v[236:239], v[186:189], v[44:47]
	global_load_lds_dwordx4 v246, s[28:29]
	v_mfma_f32_16x16x32_bf16 v[28:31], v[236:239], v[190:193], v[28:31]
	v_mfma_f32_16x16x32_bf16 v[96:99], v[236:239], v[194:197], v[96:99]
	s_add_u32 m0, m0, 0x1000
	v_mfma_f32_16x16x32_bf16 v[76:79], v[236:239], v[208:211], v[76:79]
	global_load_lds_dwordx4 v247, s[28:29]
	v_mfma_f32_16x16x32_bf16 v[40:43], v[240:243], v[186:189], v[40:43]
	v_mfma_f32_16x16x32_bf16 v[24:27], v[240:243], v[190:193], v[24:27]
	v_mfma_f32_16x16x32_bf16 v[72:75], v[240:243], v[194:197], v[72:75]
	v_mfma_f32_16x16x32_bf16 v[148:151], v[240:243], v[208:211], v[148:151]
	s_add_u32 s26, s26, 64
	s_addc_u32 s27, s27, 0
	s_add_u32 s28, s28, 64
	s_addc_u32 s29, s29, 0
	s_add_u32 s25, s25, 24576
	s_cmp_eq_u32 s25, 73728
	s_cselect_b32 s25, 0, s25
	s_add_u32 s30, s30, 24576
	s_cmp_eq_u32 s30, 73728
	s_cselect_b32 s30, 0, s30
	s_waitcnt vmcnt(6)
	s_waitcnt lgkmcnt(0)
	s_barrier
	v_add_u32_e32 v248, s30, v155
	v_add_u32_e32 v249, s30, v160
	v_mfma_f32_16x16x32_bf16 v[128:131], v[16:19], v[0:3], v[128:131]
	ds_read_b128 v[186:189], v248
	v_mfma_f32_16x16x32_bf16 v[68:71], v[16:19], v[4:7], v[68:71]
	ds_read_b128 v[212:215], v249 offset:8192
	v_mfma_f32_16x16x32_bf16 v[108:111], v[16:19], v[8:11], v[108:111]
	ds_read_b128 v[190:193], v248 offset:1024
	v_mfma_f32_16x16x32_bf16 v[132:135], v[16:19], v[12:15], v[132:135]
	ds_read_b128 v[216:219], v249 offset:9216
	v_mfma_f32_16x16x32_bf16 v[120:123], v[20:23], v[0:3], v[120:123]
	ds_read_b128 v[194:197], v248 offset:2048
	v_mfma_f32_16x16x32_bf16 v[64:67], v[20:23], v[4:7], v[64:67]
	ds_read_b128 v[220:223], v249 offset:10240
	v_mfma_f32_16x16x32_bf16 v[112:115], v[20:23], v[8:11], v[112:115]
	ds_read_b128 v[208:211], v248 offset:3072
	v_mfma_f32_16x16x32_bf16 v[136:139], v[20:23], v[12:15], v[136:139]
	ds_read_b128 v[224:227], v249 offset:11264
	v_mfma_f32_16x16x32_bf16 v[104:107], v[162:165], v[0:3], v[104:107]
	ds_read_b128 v[228:231], v249 offset:12288
	v_mfma_f32_16x16x32_bf16 v[56:59], v[162:165], v[4:7], v[56:59]
	ds_read_b128 v[232:235], v249 offset:13312
	v_mfma_f32_16x16x32_bf16 v[116:119], v[162:165], v[8:11], v[116:119]
	ds_read_b128 v[236:239], v249 offset:14336
	v_mfma_f32_16x16x32_bf16 v[140:143], v[162:165], v[12:15], v[140:143]
	ds_read_b128 v[240:243], v249 offset:15360
	v_mfma_f32_16x16x32_bf16 v[100:103], v[166:169], v[0:3], v[100:103]
	v_mfma_f32_16x16x32_bf16 v[52:55], v[166:169], v[4:7], v[52:55]
	v_mfma_f32_16x16x32_bf16 v[124:127], v[166:169], v[8:11], v[124:127]
	v_mfma_f32_16x16x32_bf16 v[144:147], v[166:169], v[12:15], v[144:147]
	v_mfma_f32_16x16x32_bf16 v[60:63], v[170:173], v[0:3], v[60:63]
	v_mfma_f32_16x16x32_bf16 v[36:39], v[170:173], v[4:7], v[36:39]
	v_mfma_f32_16x16x32_bf16 v[80:83], v[170:173], v[8:11], v[80:83]
	v_mfma_f32_16x16x32_bf16 v[92:95], v[170:173], v[12:15], v[92:95]
	v_mfma_f32_16x16x32_bf16 v[48:51], v[174:177], v[0:3], v[48:51]
	v_mfma_f32_16x16x32_bf16 v[32:35], v[174:177], v[4:7], v[32:35]
	v_mfma_f32_16x16x32_bf16 v[84:87], v[174:177], v[8:11], v[84:87]
	v_mfma_f32_16x16x32_bf16 v[88:91], v[174:177], v[12:15], v[88:91]
	v_mfma_f32_16x16x32_bf16 v[44:47], v[178:181], v[0:3], v[44:47]
	v_mfma_f32_16x16x32_bf16 v[28:31], v[178:181], v[4:7], v[28:31]
	v_mfma_f32_16x16x32_bf16 v[96:99], v[178:181], v[8:11], v[96:99]
	v_mfma_f32_16x16x32_bf16 v[76:79], v[178:181], v[12:15], v[76:79]
	v_mfma_f32_16x16x32_bf16 v[40:43], v[182:185], v[0:3], v[40:43]
	v_mfma_f32_16x16x32_bf16 v[24:27], v[182:185], v[4:7], v[24:27]
	v_mfma_f32_16x16x32_bf16 v[72:75], v[182:185], v[8:11], v[72:75]
	v_mfma_f32_16x16x32_bf16 v[148:151], v[182:185], v[12:15], v[148:151]
	s_add_u32 s30, s30, 24576
	s_cmp_eq_u32 s30, 73728
	s_cselect_b32 s30, 0, s30
	s_waitcnt vmcnt(0)
	s_waitcnt lgkmcnt(0)
	s_barrier
	v_add_u32_e32 v248, s30, v155
	v_add_u32_e32 v249, s30, v160
	v_mfma_f32_16x16x32_bf16 v[128:131], v[212:215], v[186:189], v[128:131]
	ds_read_b128 v[0:3], v248
	v_mfma_f32_16x16x32_bf16 v[68:71], v[212:215], v[190:193], v[68:71]
	ds_read_b128 v[16:19], v249 offset:8192
	v_mfma_f32_16x16x32_bf16 v[108:111], v[212:215], v[194:197], v[108:111]
	ds_read_b128 v[4:7], v248 offset:1024
	v_mfma_f32_16x16x32_bf16 v[132:135], v[212:215], v[208:211], v[132:135]
	ds_read_b128 v[20:23], v249 offset:9216
	v_mfma_f32_16x16x32_bf16 v[120:123], v[216:219], v[186:189], v[120:123]
	ds_read_b128 v[8:11], v248 offset:2048
	v_mfma_f32_16x16x32_bf16 v[64:67], v[216:219], v[190:193], v[64:67]
	ds_read_b128 v[162:165], v249 offset:10240
	v_mfma_f32_16x16x32_bf16 v[112:115], v[216:219], v[194:197], v[112:115]
	ds_read_b128 v[12:15], v248 offset:3072
	v_mfma_f32_16x16x32_bf16 v[136:139], v[216:219], v[208:211], v[136:139]
	ds_read_b128 v[166:169], v249 offset:11264
	v_mfma_f32_16x16x32_bf16 v[104:107], v[220:223], v[186:189], v[104:107]
	ds_read_b128 v[170:173], v249 offset:12288
	v_mfma_f32_16x16x32_bf16 v[56:59], v[220:223], v[190:193], v[56:59]
	ds_read_b128 v[174:177], v249 offset:13312
	v_mfma_f32_16x16x32_bf16 v[116:119], v[220:223], v[194:197], v[116:119]
	ds_read_b128 v[178:181], v249 offset:14336
	v_mfma_f32_16x16x32_bf16 v[140:143], v[220:223], v[208:211], v[140:143]
	ds_read_b128 v[182:185], v249 offset:15360
	v_mfma_f32_16x16x32_bf16 v[100:103], v[224:227], v[186:189], v[100:103]
	v_mfma_f32_16x16x32_bf16 v[52:55], v[224:227], v[190:193], v[52:55]
	v_mfma_f32_16x16x32_bf16 v[124:127], v[224:227], v[194:197], v[124:127]
	v_mfma_f32_16x16x32_bf16 v[144:147], v[224:227], v[208:211], v[144:147]
	v_mfma_f32_16x16x32_bf16 v[60:63], v[228:231], v[186:189], v[60:63]
	v_mfma_f32_16x16x32_bf16 v[36:39], v[228:231], v[190:193], v[36:39]
	v_mfma_f32_16x16x32_bf16 v[80:83], v[228:231], v[194:197], v[80:83]
	v_mfma_f32_16x16x32_bf16 v[92:95], v[228:231], v[208:211], v[92:95]
	v_mfma_f32_16x16x32_bf16 v[48:51], v[232:235], v[186:189], v[48:51]
	v_mfma_f32_16x16x32_bf16 v[32:35], v[232:235], v[190:193], v[32:35]
	v_mfma_f32_16x16x32_bf16 v[84:87], v[232:235], v[194:197], v[84:87]
	v_mfma_f32_16x16x32_bf16 v[88:91], v[232:235], v[208:211], v[88:91]
	v_mfma_f32_16x16x32_bf16 v[44:47], v[236:239], v[186:189], v[44:47]
	v_mfma_f32_16x16x32_bf16 v[28:31], v[236:239], v[190:193], v[28:31]
	v_mfma_f32_16x16x32_bf16 v[96:99], v[236:239], v[194:197], v[96:99]
	v_mfma_f32_16x16x32_bf16 v[76:79], v[236:239], v[208:211], v[76:79]
	v_mfma_f32_16x16x32_bf16 v[40:43], v[240:243], v[186:189], v[40:43]
	v_mfma_f32_16x16x32_bf16 v[24:27], v[240:243], v[190:193], v[24:27]
	v_mfma_f32_16x16x32_bf16 v[72:75], v[240:243], v[194:197], v[72:75]
	v_mfma_f32_16x16x32_bf16 v[148:151], v[240:243], v[208:211], v[148:151]
	s_add_u32 s30, s30, 24576
	s_cmp_eq_u32 s30, 73728
	s_cselect_b32 s30, 0, s30
	s_waitcnt lgkmcnt(0)
	s_barrier
	v_mfma_f32_16x16x32_bf16 v[128:131], v[16:19], v[0:3], v[128:131]
	v_mfma_f32_16x16x32_bf16 v[68:71], v[16:19], v[4:7], v[68:71]
	v_mfma_f32_16x16x32_bf16 v[108:111], v[16:19], v[8:11], v[108:111]
	v_mfma_f32_16x16x32_bf16 v[132:135], v[16:19], v[12:15], v[132:135]
	v_mfma_f32_16x16x32_bf16 v[120:123], v[20:23], v[0:3], v[120:123]
	v_mfma_f32_16x16x32_bf16 v[64:67], v[20:23], v[4:7], v[64:67]
	v_mfma_f32_16x16x32_bf16 v[112:115], v[20:23], v[8:11], v[112:115]
	v_mfma_f32_16x16x32_bf16 v[136:139], v[20:23], v[12:15], v[136:139]
	v_mfma_f32_16x16x32_bf16 v[104:107], v[162:165], v[0:3], v[104:107]
	v_mfma_f32_16x16x32_bf16 v[56:59], v[162:165], v[4:7], v[56:59]
	v_mfma_f32_16x16x32_bf16 v[116:119], v[162:165], v[8:11], v[116:119]
	v_mfma_f32_16x16x32_bf16 v[140:143], v[162:165], v[12:15], v[140:143]
	v_mfma_f32_16x16x32_bf16 v[100:103], v[166:169], v[0:3], v[100:103]
	v_mfma_f32_16x16x32_bf16 v[52:55], v[166:169], v[4:7], v[52:55]
	v_mfma_f32_16x16x32_bf16 v[124:127], v[166:169], v[8:11], v[124:127]
	v_mfma_f32_16x16x32_bf16 v[144:147], v[166:169], v[12:15], v[144:147]
	v_mfma_f32_16x16x32_bf16 v[60:63], v[170:173], v[0:3], v[60:63]
	v_mfma_f32_16x16x32_bf16 v[36:39], v[170:173], v[4:7], v[36:39]
	v_mfma_f32_16x16x32_bf16 v[80:83], v[170:173], v[8:11], v[80:83]
	v_mfma_f32_16x16x32_bf16 v[92:95], v[170:173], v[12:15], v[92:95]
	v_mfma_f32_16x16x32_bf16 v[48:51], v[174:177], v[0:3], v[48:51]
	v_mfma_f32_16x16x32_bf16 v[32:35], v[174:177], v[4:7], v[32:35]
	v_mfma_f32_16x16x32_bf16 v[84:87], v[174:177], v[8:11], v[84:87]
	v_mfma_f32_16x16x32_bf16 v[88:91], v[174:177], v[12:15], v[88:91]
	v_mfma_f32_16x16x32_bf16 v[44:47], v[178:181], v[0:3], v[44:47]
	v_mfma_f32_16x16x32_bf16 v[28:31], v[178:181], v[4:7], v[28:31]
	v_mfma_f32_16x16x32_bf16 v[96:99], v[178:181], v[8:11], v[96:99]
	v_mfma_f32_16x16x32_bf16 v[76:79], v[178:181], v[12:15], v[76:79]
	v_mfma_f32_16x16x32_bf16 v[40:43], v[182:185], v[0:3], v[40:43]
	v_mfma_f32_16x16x32_bf16 v[24:27], v[182:185], v[4:7], v[24:27]
	v_mfma_f32_16x16x32_bf16 v[72:75], v[182:185], v[8:11], v[72:75]
	v_mfma_f32_16x16x32_bf16 v[148:151], v[182:185], v[12:15], v[148:151]
	v_mov_b32 v250, v198
	s_nop 0
	v_and_b32_e32 v251, 15, v250
	v_bfe_u32 v156, v250, 4, 2
	v_bfe_u32 v157, v250, 6, 1
	v_bfe_u32 v158, v250, 7, 1
	v_lshl_add_u32 v158, v158, 6, s4
	v_add_u32_e32 v158, v158, v251
	v_lshl_add_u32 v157, v157, 7, s5
	v_lshl_add_u32 v159, v156, 2, v157
	v_lshlrev_b32_e32 v246, 2, v159
	v_lshl_add_u32 v244, v158, 12, v246
	v_lshlrev_b32_e32 v161, 1, v159
	v_lshl_add_u32 v245, v158, 11, v161
	v_lshrrev_b32_e32 v161, 6, v157
	v_lshlrev_b32_e32 v161, 2, v161
	v_lshl_add_u32 v247, v158, 6, v161
	v_xor_b32_e32 v248, 16, v200
	v_lshlrev_b32_e32 v248, 2, v248
	v_xor_b32_e32 v249, 32, v200
	v_lshlrev_b32_e32 v249, 2, v249
	s_mov_b32 s24, s78
	s_mov_b32 s25, s79
	s_mov_b32 s26, s78
	s_mov_b32 s27, s79
	s_mov_b32 s28, s96
	s_mov_b32 s29, s97
	s_mov_b32 s30, s94
	s_mov_b32 s31, s95
	s_cmp_lg_u64 s[8:9], 0
	s_cbranch_scc0 .Lgm2_noemit
	global_load_dwordx4 v[208:211], v246, s[10:11]
	global_load_dwordx4 v[212:215], v246, s[10:11] offset:64
	global_load_dwordx4 v[216:219], v246, s[10:11] offset:128
	global_load_dwordx4 v[220:223], v246, s[10:11] offset:192
	global_load_dwordx4 v[224:227], v246, s[10:11] offset:256
	global_load_dwordx4 v[228:231], v246, s[10:11] offset:320
	global_load_dwordx4 v[232:235], v246, s[10:11] offset:384
	global_load_dwordx4 v[236:239], v246, s[10:11] offset:448
	global_load_dwordx4 v[0:3], v244, s[24:25]
	global_load_dwordx4 v[4:7], v244, s[24:25] offset:64
	global_load_dwordx4 v[8:11], v244, s[24:25] offset:128
	global_load_dwordx4 v[12:15], v244, s[24:25] offset:192
	global_load_dwordx4 v[16:19], v244, s[24:25] offset:256
	global_load_dwordx4 v[20:23], v244, s[24:25] offset:320
	global_load_dwordx4 v[162:165], v244, s[24:25] offset:384
	global_load_dwordx4 v[166:169], v244, s[24:25] offset:448
	s_add_u32 s24, s24, 0x10000
	s_addc_u32 s25, s25, 0
	global_load_dwordx4 v[170:173], v244, s[24:25]
	global_load_dwordx4 v[174:177], v244, s[24:25] offset:64
	global_load_dwordx4 v[178:181], v244, s[24:25] offset:128
	global_load_dwordx4 v[182:185], v244, s[24:25] offset:192
	global_load_dwordx4 v[186:189], v244, s[24:25] offset:256
	global_load_dwordx4 v[190:193], v244, s[24:25] offset:320
	global_load_dwordx4 v[194:197], v244, s[24:25] offset:384
	global_load_dwordx4 v[240:243], v244, s[24:25] offset:448
	s_add_u32 s24, s24, 0x10000
	s_addc_u32 s25, s25, 0
	s_waitcnt vmcnt(12)
	v_add_f32_e32 v0, v128, v0
	v_add_f32_e32 v1, v129, v1
	v_add_f32_e32 v2, v130, v2
	v_add_f32_e32 v3, v131, v3
	global_store_dwordx4 v244, v[0:3], s[26:27]
	v_mul_f32_e32 v156, v0, v208
	v_mul_f32_e32 v157, v1, v209
	v_mul_f32_e32 v158, v2, v210
	v_mul_f32_e32 v159, v3, v211
	v_cvt_pk_bf16_f32 v156, v156, v157
	v_cvt_pk_bf16_f32 v157, v158, v159
	global_store_dwordx2 v245, v[156:157], s[28:29]
	v_mul_f32_e32 v158, v0, v0
	v_mul_f32_e32 v159, v1, v1
	v_mul_f32_e32 v250, v2, v2
	v_mul_f32_e32 v251, v3, v3
	v_add_f32_e32 v158, v158, v159
	v_add_f32_e32 v250, v250, v251
	v_add_f32_e32 v161, v158, v250
	v_add_f32_e32 v4, v120, v4
	v_add_f32_e32 v5, v121, v5
	v_add_f32_e32 v6, v122, v6
	v_add_f32_e32 v7, v123, v7
	global_store_dwordx4 v244, v[4:7], s[26:27] offset:64
	v_mul_f32_e32 v156, v4, v212
	v_mul_f32_e32 v157, v5, v213
	v_mul_f32_e32 v158, v6, v214
	v_mul_f32_e32 v159, v7, v215
	v_cvt_pk_bf16_f32 v156, v156, v157
	v_cvt_pk_bf16_f32 v157, v158, v159
	global_store_dwordx2 v245, v[156:157], s[28:29] offset:32
	v_mul_f32_e32 v158, v4, v4
	v_mul_f32_e32 v159, v5, v5
	v_mul_f32_e32 v250, v6, v6
	v_mul_f32_e32 v251, v7, v7
	v_add_f32_e32 v158, v158, v159
	v_add_f32_e32 v250, v250, v251
	v_add_f32_e32 v158, v158, v250
	v_add_f32_e32 v161, v161, v158
	v_add_f32_e32 v8, v104, v8
	v_add_f32_e32 v9, v105, v9
	v_add_f32_e32 v10, v106, v10
	v_add_f32_e32 v11, v107, v11
	global_store_dwordx4 v244, v[8:11], s[26:27] offset:128
	v_mul_f32_e32 v156, v8, v216
	v_mul_f32_e32 v157, v9, v217
	v_mul_f32_e32 v158, v10, v218
	v_mul_f32_e32 v159, v11, v219
	v_cvt_pk_bf16_f32 v156, v156, v157
	v_cvt_pk_bf16_f32 v157, v158, v159
	global_store_dwordx2 v245, v[156:157], s[28:29] offset:64
	v_mul_f32_e32 v158, v8, v8
	v_mul_f32_e32 v159, v9, v9
	v_mul_f32_e32 v250, v10, v10
	v_mul_f32_e32 v251, v11, v11
	v_add_f32_e32 v158, v158, v159
	v_add_f32_e32 v250, v250, v251
	v_add_f32_e32 v158, v158, v250
	v_add_f32_e32 v161, v161, v158
	v_add_f32_e32 v12, v100, v12
	v_add_f32_e32 v13, v101, v13
	v_add_f32_e32 v14, v102, v14
	v_add_f32_e32 v15, v103, v15
	global_store_dwordx4 v244, v[12:15], s[26:27] offset:192
	v_mul_f32_e32 v156, v12, v220
	v_mul_f32_e32 v157, v13, v221
	v_mul_f32_e32 v158, v14, v222
	v_mul_f32_e32 v159, v15, v223
	v_cvt_pk_bf16_f32 v156, v156, v157
	v_cvt_pk_bf16_f32 v157, v158, v159
	global_store_dwordx2 v245, v[156:157], s[28:29] offset:96
	v_mul_f32_e32 v158, v12, v12
	v_mul_f32_e32 v159, v13, v13
	v_mul_f32_e32 v250, v14, v14
	v_mul_f32_e32 v251, v15, v15
	v_add_f32_e32 v158, v158, v159
	v_add_f32_e32 v250, v250, v251
	v_add_f32_e32 v158, v158, v250
	v_add_f32_e32 v161, v161, v158
	ds_bpermute_b32 v158, v248, v161
	s_waitcnt lgkmcnt(0)
	v_add_f32_e32 v161, v161, v158
	ds_bpermute_b32 v158, v249, v161
	s_waitcnt lgkmcnt(0)
	v_add_f32_e32 v161, v161, v158
	global_store_dword v247, v161, s[30:31]
	global_load_dwordx4 v[0:3], v244, s[24:25]
	global_load_dwordx4 v[4:7], v244, s[24:25] offset:64
	global_load_dwordx4 v[8:11], v244, s[24:25] offset:128
	global_load_dwordx4 v[12:15], v244, s[24:25] offset:192
	s_waitcnt vmcnt(21)
	v_add_f32_e32 v16, v60, v16
	v_add_f32_e32 v17, v61, v17
	v_add_f32_e32 v18, v62, v18
	v_add_f32_e32 v19, v63, v19
	global_store_dwordx4 v244, v[16:19], s[26:27] offset:256
	v_mul_f32_e32 v156, v16, v224
	v_mul_f32_e32 v157, v17, v225
	v_mul_f32_e32 v158, v18, v226
	v_mul_f32_e32 v159, v19, v227
	v_cvt_pk_bf16_f32 v156, v156, v157
	v_cvt_pk_bf16_f32 v157, v158, v159
	global_store_dwordx2 v245, v[156:157], s[28:29] offset:128
	v_mul_f32_e32 v158, v16, v16
	v_mul_f32_e32 v159, v17, v17
	v_mul_f32_e32 v250, v18, v18
	v_mul_f32_e32 v251, v19, v19
	v_add_f32_e32 v158, v158, v159
	v_add_f32_e32 v250, v250, v251
	v_add_f32_e32 v161, v158, v250
	v_add_f32_e32 v20, v48, v20
	v_add_f32_e32 v21, v49, v21
	v_add_f32_e32 v22, v50, v22
	v_add_f32_e32 v23, v51, v23
	global_store_dwordx4 v244, v[20:23], s[26:27] offset:320
	v_mul_f32_e32 v156, v20, v228
	v_mul_f32_e32 v157, v21, v229
	v_mul_f32_e32 v158, v22, v230
	v_mul_f32_e32 v159, v23, v231
	v_cvt_pk_bf16_f32 v156, v156, v157
	v_cvt_pk_bf16_f32 v157, v158, v159
	global_store_dwordx2 v245, v[156:157], s[28:29] offset:160
	v_mul_f32_e32 v158, v20, v20
	v_mul_f32_e32 v159, v21, v21
	v_mul_f32_e32 v250, v22, v22
	v_mul_f32_e32 v251, v23, v23
	v_add_f32_e32 v158, v158, v159
	v_add_f32_e32 v250, v250, v251
	v_add_f32_e32 v158, v158, v250
	v_add_f32_e32 v161, v161, v158
	v_add_f32_e32 v162, v44, v162
	v_add_f32_e32 v163, v45, v163
	v_add_f32_e32 v164, v46, v164
	v_add_f32_e32 v165, v47, v165
	global_store_dwordx4 v244, v[162:165], s[26:27] offset:384
	v_mul_f32_e32 v156, v162, v232
	v_mul_f32_e32 v157, v163, v233
	v_mul_f32_e32 v158, v164, v234
	v_mul_f32_e32 v159, v165, v235
	v_cvt_pk_bf16_f32 v156, v156, v157
	v_cvt_pk_bf16_f32 v157, v158, v159
	global_store_dwordx2 v245, v[156:157], s[28:29] offset:192
	v_mul_f32_e32 v158, v162, v162
	v_mul_f32_e32 v159, v163, v163
	v_mul_f32_e32 v250, v164, v164
	v_mul_f32_e32 v251, v165, v165
	v_add_f32_e32 v158, v158, v159
	v_add_f32_e32 v250, v250, v251
	v_add_f32_e32 v158, v158, v250
	v_add_f32_e32 v161, v161, v158
	v_add_f32_e32 v166, v40, v166
	v_add_f32_e32 v167, v41, v167
	v_add_f32_e32 v168, v42, v168
	v_add_f32_e32 v169, v43, v169
	global_store_dwordx4 v244, v[166:169], s[26:27] offset:448
	v_mul_f32_e32 v156, v166, v236
	v_mul_f32_e32 v157, v167, v237
	v_mul_f32_e32 v158, v168, v238
	v_mul_f32_e32 v159, v169, v239
	v_cvt_pk_bf16_f32 v156, v156, v157
	v_cvt_pk_bf16_f32 v157, v158, v159
	global_store_dwordx2 v245, v[156:157], s[28:29] offset:224
	v_mul_f32_e32 v158, v166, v166
	v_mul_f32_e32 v159, v167, v167
	v_mul_f32_e32 v250, v168, v168
	v_mul_f32_e32 v251, v169, v169
	v_add_f32_e32 v158, v158, v159
	v_add_f32_e32 v250, v250, v251
	v_add_f32_e32 v158, v158, v250
	v_add_f32_e32 v161, v161, v158
	ds_bpermute_b32 v158, v248, v161
	s_waitcnt lgkmcnt(0)
	v_add_f32_e32 v161, v161, v158
	ds_bpermute_b32 v158, v249, v161
	s_waitcnt lgkmcnt(0)
	v_add_f32_e32 v161, v161, v158
	global_store_dword v247, v161, s[30:31] offset:4
	s_add_u32 s26, s26, 0x10000
	s_addc_u32 s27, s27, 0
	s_add_u32 s28, s28, 0x8000
	s_addc_u32 s29, s29, 0
	s_add_u32 s30, s30, 0x400
	s_addc_u32 s31, s31, 0
	global_load_dwordx4 v[16:19], v244, s[24:25] offset:256
	global_load_dwordx4 v[20:23], v244, s[24:25] offset:320
	global_load_dwordx4 v[162:165], v244, s[24:25] offset:384
	global_load_dwordx4 v[166:169], v244, s[24:25] offset:448
	s_add_u32 s24, s24, 0x10000
	s_addc_u32 s25, s25, 0
	s_waitcnt vmcnt(30)
	v_add_f32_e32 v170, v68, v170
	v_add_f32_e32 v171, v69, v171
	v_add_f32_e32 v172, v70, v172
	v_add_f32_e32 v173, v71, v173
	global_store_dwordx4 v244, v[170:173], s[26:27]
	v_mul_f32_e32 v156, v170, v208
	v_mul_f32_e32 v157, v171, v209
	v_mul_f32_e32 v158, v172, v210
	v_mul_f32_e32 v159, v173, v211
	v_cvt_pk_bf16_f32 v156, v156, v157
	v_cvt_pk_bf16_f32 v157, v158, v159
	global_store_dwordx2 v245, v[156:157], s[28:29]
	v_mul_f32_e32 v158, v170, v170
	v_mul_f32_e32 v159, v171, v171
	v_mul_f32_e32 v250, v172, v172
	v_mul_f32_e32 v251, v173, v173
	v_add_f32_e32 v158, v158, v159
	v_add_f32_e32 v250, v250, v251
	v_add_f32_e32 v161, v158, v250
	v_add_f32_e32 v174, v64, v174
	v_add_f32_e32 v175, v65, v175
	v_add_f32_e32 v176, v66, v176
	v_add_f32_e32 v177, v67, v177
	global_store_dwordx4 v244, v[174:177], s[26:27] offset:64
	v_mul_f32_e32 v156, v174, v212
	v_mul_f32_e32 v157, v175, v213
	v_mul_f32_e32 v158, v176, v214
	v_mul_f32_e32 v159, v177, v215
	v_cvt_pk_bf16_f32 v156, v156, v157
	v_cvt_pk_bf16_f32 v157, v158, v159
	global_store_dwordx2 v245, v[156:157], s[28:29] offset:32
	v_mul_f32_e32 v158, v174, v174
	v_mul_f32_e32 v159, v175, v175
	v_mul_f32_e32 v250, v176, v176
	v_mul_f32_e32 v251, v177, v177
	v_add_f32_e32 v158, v158, v159
	v_add_f32_e32 v250, v250, v251
	v_add_f32_e32 v158, v158, v250
	v_add_f32_e32 v161, v161, v158
	v_add_f32_e32 v178, v56, v178
	v_add_f32_e32 v179, v57, v179
	v_add_f32_e32 v180, v58, v180
	v_add_f32_e32 v181, v59, v181
	global_store_dwordx4 v244, v[178:181], s[26:27] offset:128
	v_mul_f32_e32 v156, v178, v216
	v_mul_f32_e32 v157, v179, v217
	v_mul_f32_e32 v158, v180, v218
	v_mul_f32_e32 v159, v181, v219
	v_cvt_pk_bf16_f32 v156, v156, v157
	v_cvt_pk_bf16_f32 v157, v158, v159
	global_store_dwordx2 v245, v[156:157], s[28:29] offset:64
	v_mul_f32_e32 v158, v178, v178
	v_mul_f32_e32 v159, v179, v179
	v_mul_f32_e32 v250, v180, v180
	v_mul_f32_e32 v251, v181, v181
	v_add_f32_e32 v158, v158, v159
	v_add_f32_e32 v250, v250, v251
	v_add_f32_e32 v158, v158, v250
	v_add_f32_e32 v161, v161, v158
	v_add_f32_e32 v182, v52, v182
	v_add_f32_e32 v183, v53, v183
	v_add_f32_e32 v184, v54, v184
	v_add_f32_e32 v185, v55, v185
	global_store_dwordx4 v244, v[182:185], s[26:27] offset:192
	v_mul_f32_e32 v156, v182, v220
	v_mul_f32_e32 v157, v183, v221
	v_mul_f32_e32 v158, v184, v222
	v_mul_f32_e32 v159, v185, v223
	v_cvt_pk_bf16_f32 v156, v156, v157
	v_cvt_pk_bf16_f32 v157, v158, v159
	global_store_dwordx2 v245, v[156:157], s[28:29] offset:96
	v_mul_f32_e32 v158, v182, v182
	v_mul_f32_e32 v159, v183, v183
	v_mul_f32_e32 v250, v184, v184
	v_mul_f32_e32 v251, v185, v185
	v_add_f32_e32 v158, v158, v159
	v_add_f32_e32 v250, v250, v251
	v_add_f32_e32 v158, v158, v250
	v_add_f32_e32 v161, v161, v158
	ds_bpermute_b32 v158, v248, v161
	s_waitcnt lgkmcnt(0)
	v_add_f32_e32 v161, v161, v158
	ds_bpermute_b32 v158, v249, v161
	s_waitcnt lgkmcnt(0)
	v_add_f32_e32 v161, v161, v158
	global_store_dword v247, v161, s[30:31]
	global_load_dwordx4 v[170:173], v244, s[24:25]
	global_load_dwordx4 v[174:177], v244, s[24:25] offset:64
	global_load_dwordx4 v[178:181], v244, s[24:25] offset:128
	global_load_dwordx4 v[182:185], v244, s[24:25] offset:192
	s_waitcnt vmcnt(39)
	v_add_f32_e32 v186, v36, v186
	v_add_f32_e32 v187, v37, v187
	v_add_f32_e32 v188, v38, v188
	v_add_f32_e32 v189, v39, v189
	global_store_dwordx4 v244, v[186:189], s[26:27] offset:256
	v_mul_f32_e32 v156, v186, v224
	v_mul_f32_e32 v157, v187, v225
	v_mul_f32_e32 v158, v188, v226
	v_mul_f32_e32 v159, v189, v227
	v_cvt_pk_bf16_f32 v156, v156, v157
	v_cvt_pk_bf16_f32 v157, v158, v159
	global_store_dwordx2 v245, v[156:157], s[28:29] offset:128
	v_mul_f32_e32 v158, v186, v186
	v_mul_f32_e32 v159, v187, v187
	v_mul_f32_e32 v250, v188, v188
	v_mul_f32_e32 v251, v189, v189
	v_add_f32_e32 v158, v158, v159
	v_add_f32_e32 v250, v250, v251
	v_add_f32_e32 v161, v158, v250
	v_add_f32_e32 v190, v32, v190
	v_add_f32_e32 v191, v33, v191
	v_add_f32_e32 v192, v34, v192
	v_add_f32_e32 v193, v35, v193
	global_store_dwordx4 v244, v[190:193], s[26:27] offset:320
	v_mul_f32_e32 v156, v190, v228
	v_mul_f32_e32 v157, v191, v229
	v_mul_f32_e32 v158, v192, v230
	v_mul_f32_e32 v159, v193, v231
	v_cvt_pk_bf16_f32 v156, v156, v157
	v_cvt_pk_bf16_f32 v157, v158, v159
	global_store_dwordx2 v245, v[156:157], s[28:29] offset:160
	v_mul_f32_e32 v158, v190, v190
	v_mul_f32_e32 v159, v191, v191
	v_mul_f32_e32 v250, v192, v192
	v_mul_f32_e32 v251, v193, v193
	v_add_f32_e32 v158, v158, v159
	v_add_f32_e32 v250, v250, v251
	v_add_f32_e32 v158, v158, v250
	v_add_f32_e32 v161, v161, v158
	v_add_f32_e32 v194, v28, v194
	v_add_f32_e32 v195, v29, v195
	v_add_f32_e32 v196, v30, v196
	v_add_f32_e32 v197, v31, v197
	global_store_dwordx4 v244, v[194:197], s[26:27] offset:384
	v_mul_f32_e32 v156, v194, v232
	v_mul_f32_e32 v157, v195, v233
	v_mul_f32_e32 v158, v196, v234
	v_mul_f32_e32 v159, v197, v235
	v_cvt_pk_bf16_f32 v156, v156, v157
	v_cvt_pk_bf16_f32 v157, v158, v159
	global_store_dwordx2 v245, v[156:157], s[28:29] offset:192
	v_mul_f32_e32 v158, v194, v194
	v_mul_f32_e32 v159, v195, v195
	v_mul_f32_e32 v250, v196, v196
	v_mul_f32_e32 v251, v197, v197
	v_add_f32_e32 v158, v158, v159
	v_add_f32_e32 v250, v250, v251
	v_add_f32_e32 v158, v158, v250
	v_add_f32_e32 v161, v161, v158
	v_add_f32_e32 v240, v24, v240
	v_add_f32_e32 v241, v25, v241
	v_add_f32_e32 v242, v26, v242
	v_add_f32_e32 v243, v27, v243
	global_store_dwordx4 v244, v[240:243], s[26:27] offset:448
	v_mul_f32_e32 v156, v240, v236
	v_mul_f32_e32 v157, v241, v237
	v_mul_f32_e32 v158, v242, v238
	v_mul_f32_e32 v159, v243, v239
	v_cvt_pk_bf16_f32 v156, v156, v157
	v_cvt_pk_bf16_f32 v157, v158, v159
	global_store_dwordx2 v245, v[156:157], s[28:29] offset:224
	v_mul_f32_e32 v158, v240, v240
	v_mul_f32_e32 v159, v241, v241
	v_mul_f32_e32 v250, v242, v242
	v_mul_f32_e32 v251, v243, v243
	v_add_f32_e32 v158, v158, v159
	v_add_f32_e32 v250, v250, v251
	v_add_f32_e32 v158, v158, v250
	v_add_f32_e32 v161, v161, v158
	ds_bpermute_b32 v158, v248, v161
	s_waitcnt lgkmcnt(0)
	v_add_f32_e32 v161, v161, v158
	ds_bpermute_b32 v158, v249, v161
	s_waitcnt lgkmcnt(0)
	v_add_f32_e32 v161, v161, v158
	global_store_dword v247, v161, s[30:31] offset:4
	s_add_u32 s26, s26, 0x10000
	s_addc_u32 s27, s27, 0
	s_add_u32 s28, s28, 0x8000
	s_addc_u32 s29, s29, 0
	s_add_u32 s30, s30, 0x400
	s_addc_u32 s31, s31, 0
	global_load_dwordx4 v[186:189], v244, s[24:25] offset:256
	global_load_dwordx4 v[190:193], v244, s[24:25] offset:320
	global_load_dwordx4 v[194:197], v244, s[24:25] offset:384
	global_load_dwordx4 v[240:243], v244, s[24:25] offset:448
	s_add_u32 s24, s24, 0x10000
	s_addc_u32 s25, s25, 0
	s_waitcnt vmcnt(39)
	v_add_f32_e32 v0, v108, v0
	v_add_f32_e32 v1, v109, v1
	v_add_f32_e32 v2, v110, v2
	v_add_f32_e32 v3, v111, v3
	global_store_dwordx4 v244, v[0:3], s[26:27]
	v_mul_f32_e32 v156, v0, v208
	v_mul_f32_e32 v157, v1, v209
	v_mul_f32_e32 v158, v2, v210
	v_mul_f32_e32 v159, v3, v211
	v_cvt_pk_bf16_f32 v156, v156, v157
	v_cvt_pk_bf16_f32 v157, v158, v159
	global_store_dwordx2 v245, v[156:157], s[28:29]
	v_mul_f32_e32 v158, v0, v0
	v_mul_f32_e32 v159, v1, v1
	v_mul_f32_e32 v250, v2, v2
	v_mul_f32_e32 v251, v3, v3
	v_add_f32_e32 v158, v158, v159
	v_add_f32_e32 v250, v250, v251
	v_add_f32_e32 v161, v158, v250
	v_add_f32_e32 v4, v112, v4
	v_add_f32_e32 v5, v113, v5
	v_add_f32_e32 v6, v114, v6
	v_add_f32_e32 v7, v115, v7
	global_store_dwordx4 v244, v[4:7], s[26:27] offset:64
	v_mul_f32_e32 v156, v4, v212
	v_mul_f32_e32 v157, v5, v213
	v_mul_f32_e32 v158, v6, v214
	v_mul_f32_e32 v159, v7, v215
	v_cvt_pk_bf16_f32 v156, v156, v157
	v_cvt_pk_bf16_f32 v157, v158, v159
	global_store_dwordx2 v245, v[156:157], s[28:29] offset:32
	v_mul_f32_e32 v158, v4, v4
	v_mul_f32_e32 v159, v5, v5
	v_mul_f32_e32 v250, v6, v6
	v_mul_f32_e32 v251, v7, v7
	v_add_f32_e32 v158, v158, v159
	v_add_f32_e32 v250, v250, v251
	v_add_f32_e32 v158, v158, v250
	v_add_f32_e32 v161, v161, v158
	v_add_f32_e32 v8, v116, v8
	v_add_f32_e32 v9, v117, v9
	v_add_f32_e32 v10, v118, v10
	v_add_f32_e32 v11, v119, v11
	global_store_dwordx4 v244, v[8:11], s[26:27] offset:128
	v_mul_f32_e32 v156, v8, v216
	v_mul_f32_e32 v157, v9, v217
	v_mul_f32_e32 v158, v10, v218
	v_mul_f32_e32 v159, v11, v219
	v_cvt_pk_bf16_f32 v156, v156, v157
	v_cvt_pk_bf16_f32 v157, v158, v159
	global_store_dwordx2 v245, v[156:157], s[28:29] offset:64
	v_mul_f32_e32 v158, v8, v8
	v_mul_f32_e32 v159, v9, v9
	v_mul_f32_e32 v250, v10, v10
	v_mul_f32_e32 v251, v11, v11
	v_add_f32_e32 v158, v158, v159
	v_add_f32_e32 v250, v250, v251
	v_add_f32_e32 v158, v158, v250
	v_add_f32_e32 v161, v161, v158
	v_add_f32_e32 v12, v124, v12
	v_add_f32_e32 v13, v125, v13
	v_add_f32_e32 v14, v126, v14
	v_add_f32_e32 v15, v127, v15
	global_store_dwordx4 v244, v[12:15], s[26:27] offset:192
	v_mul_f32_e32 v156, v12, v220
	v_mul_f32_e32 v157, v13, v221
	v_mul_f32_e32 v158, v14, v222
	v_mul_f32_e32 v159, v15, v223
	v_cvt_pk_bf16_f32 v156, v156, v157
	v_cvt_pk_bf16_f32 v157, v158, v159
	global_store_dwordx2 v245, v[156:157], s[28:29] offset:96
	v_mul_f32_e32 v158, v12, v12
	v_mul_f32_e32 v159, v13, v13
	v_mul_f32_e32 v250, v14, v14
	v_mul_f32_e32 v251, v15, v15
	v_add_f32_e32 v158, v158, v159
	v_add_f32_e32 v250, v250, v251
	v_add_f32_e32 v158, v158, v250
	v_add_f32_e32 v161, v161, v158
	ds_bpermute_b32 v158, v248, v161
	s_waitcnt lgkmcnt(0)
	v_add_f32_e32 v161, v161, v158
	ds_bpermute_b32 v158, v249, v161
	s_waitcnt lgkmcnt(0)
	v_add_f32_e32 v161, v161, v158
	global_store_dword v247, v161, s[30:31]
	s_waitcnt vmcnt(35)
	v_add_f32_e32 v16, v80, v16
	v_add_f32_e32 v17, v81, v17
	v_add_f32_e32 v18, v82, v18
	v_add_f32_e32 v19, v83, v19
	global_store_dwordx4 v244, v[16:19], s[26:27] offset:256
	v_mul_f32_e32 v156, v16, v224
	v_mul_f32_e32 v157, v17, v225
	v_mul_f32_e32 v158, v18, v226
	v_mul_f32_e32 v159, v19, v227
	v_cvt_pk_bf16_f32 v156, v156, v157
	v_cvt_pk_bf16_f32 v157, v158, v159
	global_store_dwordx2 v245, v[156:157], s[28:29] offset:128
	v_mul_f32_e32 v158, v16, v16
	v_mul_f32_e32 v159, v17, v17
	v_mul_f32_e32 v250, v18, v18
	v_mul_f32_e32 v251, v19, v19
	v_add_f32_e32 v158, v158, v159
	v_add_f32_e32 v250, v250, v251
	v_add_f32_e32 v161, v158, v250
	v_add_f32_e32 v20, v84, v20
	v_add_f32_e32 v21, v85, v21
	v_add_f32_e32 v22, v86, v22
	v_add_f32_e32 v23, v87, v23
	global_store_dwordx4 v244, v[20:23], s[26:27] offset:320
	v_mul_f32_e32 v156, v20, v228
	v_mul_f32_e32 v157, v21, v229
	v_mul_f32_e32 v158, v22, v230
	v_mul_f32_e32 v159, v23, v231
	v_cvt_pk_bf16_f32 v156, v156, v157
	v_cvt_pk_bf16_f32 v157, v158, v159
	global_store_dwordx2 v245, v[156:157], s[28:29] offset:160
	v_mul_f32_e32 v158, v20, v20
	v_mul_f32_e32 v159, v21, v21
	v_mul_f32_e32 v250, v22, v22
	v_mul_f32_e32 v251, v23, v23
	v_add_f32_e32 v158, v158, v159
	v_add_f32_e32 v250, v250, v251
	v_add_f32_e32 v158, v158, v250
	v_add_f32_e32 v161, v161, v158
	v_add_f32_e32 v162, v96, v162
	v_add_f32_e32 v163, v97, v163
	v_add_f32_e32 v164, v98, v164
	v_add_f32_e32 v165, v99, v165
	global_store_dwordx4 v244, v[162:165], s[26:27] offset:384
	v_mul_f32_e32 v156, v162, v232
	v_mul_f32_e32 v157, v163, v233
	v_mul_f32_e32 v158, v164, v234
	v_mul_f32_e32 v159, v165, v235
	v_cvt_pk_bf16_f32 v156, v156, v157
	v_cvt_pk_bf16_f32 v157, v158, v159
	global_store_dwordx2 v245, v[156:157], s[28:29] offset:192
	v_mul_f32_e32 v158, v162, v162
	v_mul_f32_e32 v159, v163, v163
	v_mul_f32_e32 v250, v164, v164
	v_mul_f32_e32 v251, v165, v165
	v_add_f32_e32 v158, v158, v159
	v_add_f32_e32 v250, v250, v251
	v_add_f32_e32 v158, v158, v250
	v_add_f32_e32 v161, v161, v158
	v_add_f32_e32 v166, v72, v166
	v_add_f32_e32 v167, v73, v167
	v_add_f32_e32 v168, v74, v168
	v_add_f32_e32 v169, v75, v169
	global_store_dwordx4 v244, v[166:169], s[26:27] offset:448
	v_mul_f32_e32 v156, v166, v236
	v_mul_f32_e32 v157, v167, v237
	v_mul_f32_e32 v158, v168, v238
	v_mul_f32_e32 v159, v169, v239
	v_cvt_pk_bf16_f32 v156, v156, v157
	v_cvt_pk_bf16_f32 v157, v158, v159
	global_store_dwordx2 v245, v[156:157], s[28:29] offset:224
	v_mul_f32_e32 v158, v166, v166
	v_mul_f32_e32 v159, v167, v167
	v_mul_f32_e32 v250, v168, v168
	v_mul_f32_e32 v251, v169, v169
	v_add_f32_e32 v158, v158, v159
	v_add_f32_e32 v250, v250, v251
	v_add_f32_e32 v158, v158, v250
	v_add_f32_e32 v161, v161, v158
	ds_bpermute_b32 v158, v248, v161
	s_waitcnt lgkmcnt(0)
	v_add_f32_e32 v161, v161, v158
	ds_bpermute_b32 v158, v249, v161
	s_waitcnt lgkmcnt(0)
	v_add_f32_e32 v161, v161, v158
	global_store_dword v247, v161, s[30:31] offset:4
	s_add_u32 s26, s26, 0x10000
	s_addc_u32 s27, s27, 0
	s_add_u32 s28, s28, 0x8000
	s_addc_u32 s29, s29, 0
	s_add_u32 s30, s30, 0x400
	s_addc_u32 s31, s31, 0
	s_waitcnt vmcnt(31)
	v_add_f32_e32 v170, v132, v170
	v_add_f32_e32 v171, v133, v171
	v_add_f32_e32 v172, v134, v172
	v_add_f32_e32 v173, v135, v173
	global_store_dwordx4 v244, v[170:173], s[26:27]
	v_mul_f32_e32 v156, v170, v208
	v_mul_f32_e32 v157, v171, v209
	v_mul_f32_e32 v158, v172, v210
	v_mul_f32_e32 v159, v173, v211
	v_cvt_pk_bf16_f32 v156, v156, v157
	v_cvt_pk_bf16_f32 v157, v158, v159
	global_store_dwordx2 v245, v[156:157], s[28:29]
	v_mul_f32_e32 v158, v170, v170
	v_mul_f32_e32 v159, v171, v171
	v_mul_f32_e32 v250, v172, v172
	v_mul_f32_e32 v251, v173, v173
	v_add_f32_e32 v158, v158, v159
	v_add_f32_e32 v250, v250, v251
	v_add_f32_e32 v161, v158, v250
	v_add_f32_e32 v174, v136, v174
	v_add_f32_e32 v175, v137, v175
	v_add_f32_e32 v176, v138, v176
	v_add_f32_e32 v177, v139, v177
	global_store_dwordx4 v244, v[174:177], s[26:27] offset:64
	v_mul_f32_e32 v156, v174, v212
	v_mul_f32_e32 v157, v175, v213
	v_mul_f32_e32 v158, v176, v214
	v_mul_f32_e32 v159, v177, v215
	v_cvt_pk_bf16_f32 v156, v156, v157
	v_cvt_pk_bf16_f32 v157, v158, v159
	global_store_dwordx2 v245, v[156:157], s[28:29] offset:32
	v_mul_f32_e32 v158, v174, v174
	v_mul_f32_e32 v159, v175, v175
	v_mul_f32_e32 v250, v176, v176
	v_mul_f32_e32 v251, v177, v177
	v_add_f32_e32 v158, v158, v159
	v_add_f32_e32 v250, v250, v251
	v_add_f32_e32 v158, v158, v250
	v_add_f32_e32 v161, v161, v158
	v_add_f32_e32 v178, v140, v178
	v_add_f32_e32 v179, v141, v179
	v_add_f32_e32 v180, v142, v180
	v_add_f32_e32 v181, v143, v181
	global_store_dwordx4 v244, v[178:181], s[26:27] offset:128
	v_mul_f32_e32 v156, v178, v216
	v_mul_f32_e32 v157, v179, v217
	v_mul_f32_e32 v158, v180, v218
	v_mul_f32_e32 v159, v181, v219
	v_cvt_pk_bf16_f32 v156, v156, v157
	v_cvt_pk_bf16_f32 v157, v158, v159
	global_store_dwordx2 v245, v[156:157], s[28:29] offset:64
	v_mul_f32_e32 v158, v178, v178
	v_mul_f32_e32 v159, v179, v179
	v_mul_f32_e32 v250, v180, v180
	v_mul_f32_e32 v251, v181, v181
	v_add_f32_e32 v158, v158, v159
	v_add_f32_e32 v250, v250, v251
	v_add_f32_e32 v158, v158, v250
	v_add_f32_e32 v161, v161, v158
	v_add_f32_e32 v182, v144, v182
	v_add_f32_e32 v183, v145, v183
	v_add_f32_e32 v184, v146, v184
	v_add_f32_e32 v185, v147, v185
	global_store_dwordx4 v244, v[182:185], s[26:27] offset:192
	v_mul_f32_e32 v156, v182, v220
	v_mul_f32_e32 v157, v183, v221
	v_mul_f32_e32 v158, v184, v222
	v_mul_f32_e32 v159, v185, v223
	v_cvt_pk_bf16_f32 v156, v156, v157
	v_cvt_pk_bf16_f32 v157, v158, v159
	global_store_dwordx2 v245, v[156:157], s[28:29] offset:96
	v_mul_f32_e32 v158, v182, v182
	v_mul_f32_e32 v159, v183, v183
	v_mul_f32_e32 v250, v184, v184
	v_mul_f32_e32 v251, v185, v185
	v_add_f32_e32 v158, v158, v159
	v_add_f32_e32 v250, v250, v251
	v_add_f32_e32 v158, v158, v250
	v_add_f32_e32 v161, v161, v158
	ds_bpermute_b32 v158, v248, v161
	s_waitcnt lgkmcnt(0)
	v_add_f32_e32 v161, v161, v158
	ds_bpermute_b32 v158, v249, v161
	s_waitcnt lgkmcnt(0)
	v_add_f32_e32 v161, v161, v158
	global_store_dword v247, v161, s[30:31]
	s_waitcnt vmcnt(27)
	v_add_f32_e32 v186, v92, v186
	v_add_f32_e32 v187, v93, v187
	v_add_f32_e32 v188, v94, v188
	v_add_f32_e32 v189, v95, v189
	global_store_dwordx4 v244, v[186:189], s[26:27] offset:256
	v_mul_f32_e32 v156, v186, v224
	v_mul_f32_e32 v157, v187, v225
	v_mul_f32_e32 v158, v188, v226
	v_mul_f32_e32 v159, v189, v227
	v_cvt_pk_bf16_f32 v156, v156, v157
	v_cvt_pk_bf16_f32 v157, v158, v159
	global_store_dwordx2 v245, v[156:157], s[28:29] offset:128
	v_mul_f32_e32 v158, v186, v186
	v_mul_f32_e32 v159, v187, v187
	v_mul_f32_e32 v250, v188, v188
	v_mul_f32_e32 v251, v189, v189
	v_add_f32_e32 v158, v158, v159
	v_add_f32_e32 v250, v250, v251
	v_add_f32_e32 v161, v158, v250
	v_add_f32_e32 v190, v88, v190
	v_add_f32_e32 v191, v89, v191
	v_add_f32_e32 v192, v90, v192
	v_add_f32_e32 v193, v91, v193
	global_store_dwordx4 v244, v[190:193], s[26:27] offset:320
	v_mul_f32_e32 v156, v190, v228
	v_mul_f32_e32 v157, v191, v229
	v_mul_f32_e32 v158, v192, v230
	v_mul_f32_e32 v159, v193, v231
	v_cvt_pk_bf16_f32 v156, v156, v157
	v_cvt_pk_bf16_f32 v157, v158, v159
	global_store_dwordx2 v245, v[156:157], s[28:29] offset:160
	v_mul_f32_e32 v158, v190, v190
	v_mul_f32_e32 v159, v191, v191
	v_mul_f32_e32 v250, v192, v192
	v_mul_f32_e32 v251, v193, v193
	v_add_f32_e32 v158, v158, v159
	v_add_f32_e32 v250, v250, v251
	v_add_f32_e32 v158, v158, v250
	v_add_f32_e32 v161, v161, v158
	v_add_f32_e32 v194, v76, v194
	v_add_f32_e32 v195, v77, v195
	v_add_f32_e32 v196, v78, v196
	v_add_f32_e32 v197, v79, v197
	global_store_dwordx4 v244, v[194:197], s[26:27] offset:384
	v_mul_f32_e32 v156, v194, v232
	v_mul_f32_e32 v157, v195, v233
	v_mul_f32_e32 v158, v196, v234
	v_mul_f32_e32 v159, v197, v235
	v_cvt_pk_bf16_f32 v156, v156, v157
	v_cvt_pk_bf16_f32 v157, v158, v159
	global_store_dwordx2 v245, v[156:157], s[28:29] offset:192
	v_mul_f32_e32 v158, v194, v194
	v_mul_f32_e32 v159, v195, v195
	v_mul_f32_e32 v250, v196, v196
	v_mul_f32_e32 v251, v197, v197
	v_add_f32_e32 v158, v158, v159
	v_add_f32_e32 v250, v250, v251
	v_add_f32_e32 v158, v158, v250
	v_add_f32_e32 v161, v161, v158
	v_add_f32_e32 v240, v148, v240
	v_add_f32_e32 v241, v149, v241
	v_add_f32_e32 v242, v150, v242
	v_add_f32_e32 v243, v151, v243
	global_store_dwordx4 v244, v[240:243], s[26:27] offset:448
	v_mul_f32_e32 v156, v240, v236
	v_mul_f32_e32 v157, v241, v237
	v_mul_f32_e32 v158, v242, v238
	v_mul_f32_e32 v159, v243, v239
	v_cvt_pk_bf16_f32 v156, v156, v157
	v_cvt_pk_bf16_f32 v157, v158, v159
	global_store_dwordx2 v245, v[156:157], s[28:29] offset:224
	v_mul_f32_e32 v158, v240, v240
	v_mul_f32_e32 v159, v241, v241
	v_mul_f32_e32 v250, v242, v242
	v_mul_f32_e32 v251, v243, v243
	v_add_f32_e32 v158, v158, v159
	v_add_f32_e32 v250, v250, v251
	v_add_f32_e32 v158, v158, v250
	v_add_f32_e32 v161, v161, v158
	ds_bpermute_b32 v158, v248, v161
	s_waitcnt lgkmcnt(0)
	v_add_f32_e32 v161, v161, v158
	ds_bpermute_b32 v158, v249, v161
	s_waitcnt lgkmcnt(0)
	v_add_f32_e32 v161, v161, v158
	global_store_dword v247, v161, s[30:31] offset:4
	s_add_u32 s26, s26, 0x10000
	s_addc_u32 s27, s27, 0
	s_add_u32 s28, s28, 0x8000
	s_addc_u32 s29, s29, 0
	s_add_u32 s30, s30, 0x400
	s_addc_u32 s31, s31, 0
	s_branch .LBB0_360
.Lgm2_noemit:
	global_load_dwordx4 v[0:3], v244, s[24:25]
	global_load_dwordx4 v[4:7], v244, s[24:25] offset:64
	global_load_dwordx4 v[8:11], v244, s[24:25] offset:128
	global_load_dwordx4 v[12:15], v244, s[24:25] offset:192
	global_load_dwordx4 v[16:19], v244, s[24:25] offset:256
	global_load_dwordx4 v[20:23], v244, s[24:25] offset:320
	global_load_dwordx4 v[162:165], v244, s[24:25] offset:384
	global_load_dwordx4 v[166:169], v244, s[24:25] offset:448
	s_add_u32 s24, s24, 0x10000
	s_addc_u32 s25, s25, 0
	global_load_dwordx4 v[170:173], v244, s[24:25]
	global_load_dwordx4 v[174:177], v244, s[24:25] offset:64
	global_load_dwordx4 v[178:181], v244, s[24:25] offset:128
	global_load_dwordx4 v[182:185], v244, s[24:25] offset:192
	global_load_dwordx4 v[186:189], v244, s[24:25] offset:256
	global_load_dwordx4 v[190:193], v244, s[24:25] offset:320
	global_load_dwordx4 v[194:197], v244, s[24:25] offset:384
	global_load_dwordx4 v[240:243], v244, s[24:25] offset:448
	s_add_u32 s24, s24, 0x10000
	s_addc_u32 s25, s25, 0
	s_waitcnt vmcnt(12)
	v_add_f32_e32 v0, v128, v0
	v_add_f32_e32 v1, v129, v1
	v_add_f32_e32 v2, v130, v2
	v_add_f32_e32 v3, v131, v3
	global_store_dwordx4 v244, v[0:3], s[26:27]
	v_add_f32_e32 v4, v120, v4
	v_add_f32_e32 v5, v121, v5
	v_add_f32_e32 v6, v122, v6
	v_add_f32_e32 v7, v123, v7
	global_store_dwordx4 v244, v[4:7], s[26:27] offset:64
	v_add_f32_e32 v8, v104, v8
	v_add_f32_e32 v9, v105, v9
	v_add_f32_e32 v10, v106, v10
	v_add_f32_e32 v11, v107, v11
	global_store_dwordx4 v244, v[8:11], s[26:27] offset:128
	v_add_f32_e32 v12, v100, v12
	v_add_f32_e32 v13, v101, v13
	v_add_f32_e32 v14, v102, v14
	v_add_f32_e32 v15, v103, v15
	global_store_dwordx4 v244, v[12:15], s[26:27] offset:192
	global_load_dwordx4 v[0:3], v244, s[24:25]
	global_load_dwordx4 v[4:7], v244, s[24:25] offset:64
	global_load_dwordx4 v[8:11], v244, s[24:25] offset:128
	global_load_dwordx4 v[12:15], v244, s[24:25] offset:192
	s_waitcnt vmcnt(16)
	v_add_f32_e32 v16, v60, v16
	v_add_f32_e32 v17, v61, v17
	v_add_f32_e32 v18, v62, v18
	v_add_f32_e32 v19, v63, v19
	global_store_dwordx4 v244, v[16:19], s[26:27] offset:256
	v_add_f32_e32 v20, v48, v20
	v_add_f32_e32 v21, v49, v21
	v_add_f32_e32 v22, v50, v22
	v_add_f32_e32 v23, v51, v23
	global_store_dwordx4 v244, v[20:23], s[26:27] offset:320
	v_add_f32_e32 v162, v44, v162
	v_add_f32_e32 v163, v45, v163
	v_add_f32_e32 v164, v46, v164
	v_add_f32_e32 v165, v47, v165
	global_store_dwordx4 v244, v[162:165], s[26:27] offset:384
	v_add_f32_e32 v166, v40, v166
	v_add_f32_e32 v167, v41, v167
	v_add_f32_e32 v168, v42, v168
	v_add_f32_e32 v169, v43, v169
	global_store_dwordx4 v244, v[166:169], s[26:27] offset:448
	s_add_u32 s26, s26, 0x10000
	s_addc_u32 s27, s27, 0
	global_load_dwordx4 v[16:19], v244, s[24:25] offset:256
	global_load_dwordx4 v[20:23], v244, s[24:25] offset:320
	global_load_dwordx4 v[162:165], v244, s[24:25] offset:384
	global_load_dwordx4 v[166:169], v244, s[24:25] offset:448
	s_add_u32 s24, s24, 0x10000
	s_addc_u32 s25, s25, 0
	s_waitcnt vmcnt(20)
	v_add_f32_e32 v170, v68, v170
	v_add_f32_e32 v171, v69, v171
	v_add_f32_e32 v172, v70, v172
	v_add_f32_e32 v173, v71, v173
	global_store_dwordx4 v244, v[170:173], s[26:27]
	v_add_f32_e32 v174, v64, v174
	v_add_f32_e32 v175, v65, v175
	v_add_f32_e32 v176, v66, v176
	v_add_f32_e32 v177, v67, v177
	global_store_dwordx4 v244, v[174:177], s[26:27] offset:64
	v_add_f32_e32 v178, v56, v178
	v_add_f32_e32 v179, v57, v179
	v_add_f32_e32 v180, v58, v180
	v_add_f32_e32 v181, v59, v181
	global_store_dwordx4 v244, v[178:181], s[26:27] offset:128
	v_add_f32_e32 v182, v52, v182
	v_add_f32_e32 v183, v53, v183
	v_add_f32_e32 v184, v54, v184
	v_add_f32_e32 v185, v55, v185
	global_store_dwordx4 v244, v[182:185], s[26:27] offset:192
	global_load_dwordx4 v[170:173], v244, s[24:25]
	global_load_dwordx4 v[174:177], v244, s[24:25] offset:64
	global_load_dwordx4 v[178:181], v244, s[24:25] offset:128
	global_load_dwordx4 v[182:185], v244, s[24:25] offset:192
	s_waitcnt vmcnt(24)
	v_add_f32_e32 v186, v36, v186
	v_add_f32_e32 v187, v37, v187
	v_add_f32_e32 v188, v38, v188
	v_add_f32_e32 v189, v39, v189
	global_store_dwordx4 v244, v[186:189], s[26:27] offset:256
	v_add_f32_e32 v190, v32, v190
	v_add_f32_e32 v191, v33, v191
	v_add_f32_e32 v192, v34, v192
	v_add_f32_e32 v193, v35, v193
	global_store_dwordx4 v244, v[190:193], s[26:27] offset:320
	v_add_f32_e32 v194, v28, v194
	v_add_f32_e32 v195, v29, v195
	v_add_f32_e32 v196, v30, v196
	v_add_f32_e32 v197, v31, v197
	global_store_dwordx4 v244, v[194:197], s[26:27] offset:384
	v_add_f32_e32 v240, v24, v240
	v_add_f32_e32 v241, v25, v241
	v_add_f32_e32 v242, v26, v242
	v_add_f32_e32 v243, v27, v243
	global_store_dwordx4 v244, v[240:243], s[26:27] offset:448
	s_add_u32 s26, s26, 0x10000
	s_addc_u32 s27, s27, 0
	global_load_dwordx4 v[186:189], v244, s[24:25] offset:256
	global_load_dwordx4 v[190:193], v244, s[24:25] offset:320
	global_load_dwordx4 v[194:197], v244, s[24:25] offset:384
	global_load_dwordx4 v[240:243], v244, s[24:25] offset:448
	s_add_u32 s24, s24, 0x10000
	s_addc_u32 s25, s25, 0
	s_waitcnt vmcnt(24)
	v_add_f32_e32 v0, v108, v0
	v_add_f32_e32 v1, v109, v1
	v_add_f32_e32 v2, v110, v2
	v_add_f32_e32 v3, v111, v3
	global_store_dwordx4 v244, v[0:3], s[26:27]
	v_add_f32_e32 v4, v112, v4
	v_add_f32_e32 v5, v113, v5
	v_add_f32_e32 v6, v114, v6
	v_add_f32_e32 v7, v115, v7
	global_store_dwordx4 v244, v[4:7], s[26:27] offset:64
	v_add_f32_e32 v8, v116, v8
	v_add_f32_e32 v9, v117, v9
	v_add_f32_e32 v10, v118, v10
	v_add_f32_e32 v11, v119, v11
	global_store_dwordx4 v244, v[8:11], s[26:27] offset:128
	v_add_f32_e32 v12, v124, v12
	v_add_f32_e32 v13, v125, v13
	v_add_f32_e32 v14, v126, v14
	v_add_f32_e32 v15, v127, v15
	global_store_dwordx4 v244, v[12:15], s[26:27] offset:192
	s_waitcnt vmcnt(20)
	v_add_f32_e32 v16, v80, v16
	v_add_f32_e32 v17, v81, v17
	v_add_f32_e32 v18, v82, v18
	v_add_f32_e32 v19, v83, v19
	global_store_dwordx4 v244, v[16:19], s[26:27] offset:256
	v_add_f32_e32 v20, v84, v20
	v_add_f32_e32 v21, v85, v21
	v_add_f32_e32 v22, v86, v22
	v_add_f32_e32 v23, v87, v23
	global_store_dwordx4 v244, v[20:23], s[26:27] offset:320
	v_add_f32_e32 v162, v96, v162
	v_add_f32_e32 v163, v97, v163
	v_add_f32_e32 v164, v98, v164
	v_add_f32_e32 v165, v99, v165
	global_store_dwordx4 v244, v[162:165], s[26:27] offset:384
	v_add_f32_e32 v166, v72, v166
	v_add_f32_e32 v167, v73, v167
	v_add_f32_e32 v168, v74, v168
	v_add_f32_e32 v169, v75, v169
	global_store_dwordx4 v244, v[166:169], s[26:27] offset:448
	s_add_u32 s26, s26, 0x10000
	s_addc_u32 s27, s27, 0
	s_waitcnt vmcnt(16)
	v_add_f32_e32 v170, v132, v170
	v_add_f32_e32 v171, v133, v171
	v_add_f32_e32 v172, v134, v172
	v_add_f32_e32 v173, v135, v173
	global_store_dwordx4 v244, v[170:173], s[26:27]
	v_add_f32_e32 v174, v136, v174
	v_add_f32_e32 v175, v137, v175
	v_add_f32_e32 v176, v138, v176
	v_add_f32_e32 v177, v139, v177
	global_store_dwordx4 v244, v[174:177], s[26:27] offset:64
	v_add_f32_e32 v178, v140, v178
	v_add_f32_e32 v179, v141, v179
	v_add_f32_e32 v180, v142, v180
	v_add_f32_e32 v181, v143, v181
	global_store_dwordx4 v244, v[178:181], s[26:27] offset:128
	v_add_f32_e32 v182, v144, v182
	v_add_f32_e32 v183, v145, v183
	v_add_f32_e32 v184, v146, v184
	v_add_f32_e32 v185, v147, v185
	global_store_dwordx4 v244, v[182:185], s[26:27] offset:192
	s_waitcnt vmcnt(12)
	v_add_f32_e32 v186, v92, v186
	v_add_f32_e32 v187, v93, v187
	v_add_f32_e32 v188, v94, v188
	v_add_f32_e32 v189, v95, v189
	global_store_dwordx4 v244, v[186:189], s[26:27] offset:256
	v_add_f32_e32 v190, v88, v190
	v_add_f32_e32 v191, v89, v191
	v_add_f32_e32 v192, v90, v192
	v_add_f32_e32 v193, v91, v193
	global_store_dwordx4 v244, v[190:193], s[26:27] offset:320
	v_add_f32_e32 v194, v76, v194
	v_add_f32_e32 v195, v77, v195
	v_add_f32_e32 v196, v78, v196
	v_add_f32_e32 v197, v79, v197
	global_store_dwordx4 v244, v[194:197], s[26:27] offset:384
	v_add_f32_e32 v240, v148, v240
	v_add_f32_e32 v241, v149, v241
	v_add_f32_e32 v242, v150, v242
	v_add_f32_e32 v243, v151, v243
	global_store_dwordx4 v244, v[240:243], s[26:27] offset:448
	s_add_u32 s26, s26, 0x10000
	s_addc_u32 s27, s27, 0
	s_branch .LBB0_360

.LBB0_449:
	s_and_b32 s4, s43, 0xffff
	s_mulk_i32 s4, 0x4ec5
	s_lshr_b32 s4, s4, 21
	s_mul_i32 s5, s4, 0x68
	s_lshl_b32 s6, s4, 6
	s_lshl_b32 s4, s43, 3
	s_and_b32 s4, s4, 56
	s_or_b32 s16, s4, s6
	s_or_b32 s4, s16, s67
	v_mov_b32 v10, v198
	s_sub_i32 s5, s43, s5
	v_ashrrev_i32_e32 v0, 2, v10
	s_lshl_b32 s4, s4, 7
	s_lshl_b32 s5, s5, 5
	v_add_u32_e32 v2, s4, v0
	s_and_b32 s17, s5, 0xf00
	v_ashrrev_i32_e32 v3, 31, v2
	v_lshlrev_b64 v[2:3], 11, v[2:3]
	v_lshlrev_b32_e32 v1, 4, v10
	v_add_u32_e32 v4, s17, v0
	v_lshl_add_u64 v[2:3], s[96:97], 0, v[2:3]
	v_and_b32_e32 v152, 48, v1
	v_ashrrev_i32_e32 v5, 31, v4
	v_lshl_add_u64 v[2:3], v[2:3], 0, v[152:153]
	v_lshlrev_b64 v[4:5], 11, v[4:5]
	v_lshl_add_u64 v[156:157], s[8:9], 0, v[4:5]
	v_add_co_u32_e32 v6, vcc, s62, v2
	v_lshl_add_u64 v[4:5], v[156:157], 0, v[152:153]
	s_nop 0
	v_addc_co_u32_e32 v7, vcc, 0, v3, vcc
	v_add_co_u32_e32 v8, vcc, s62, v4
	s_and_b32 s7, s42, 56
	v_lshrrev_b32_e32 v1, 2, v10
	s_or_b32 s6, s67, s6
	v_addc_co_u32_e32 v9, vcc, 0, v5, vcc
	v_and_b32_e32 v12, 12, v1
	s_movk_i32 s20, 0x1230
	s_or_b32 s84, s6, s7
	v_add_co_u32_e32 v60, vcc, s33, v4
	v_lshrrev_b32_e64 v12, v12, s20
	s_lshl_b64 s[6:7], s[84:85], 18
	v_addc_co_u32_e32 v61, vcc, 0, v5, vcc
	v_and_b32_e32 v11, 3, v10
	v_ashrrev_i32_e32 v1, 31, v0
	v_xor_b32_e32 v10, v12, v10
	s_add_u32 s6, s82, s6
	v_add_co_u32_e32 v62, vcc, s72, v4
	v_lshlrev_b32_e32 v13, 6, v0
	v_lshlrev_b64 v[0:1], 11, v[0:1]
	v_lshlrev_b32_e32 v10, 4, v10
	s_addc_u32 s7, s83, s7
	v_addc_co_u32_e32 v63, vcc, 0, v5, vcc
	s_nop 0
	v_readfirstlane_b32 s26, v2
	v_readfirstlane_b32 s27, v3
	v_readfirstlane_b32 s28, v4
	v_readfirstlane_b32 s29, v5
	v_lshrrev_b32_e32 v250, 6, v198
	s_nop 0
	v_readfirstlane_b32 s24, v250
	s_lshl_b32 s24, s24, 10
	v_lshrrev_b32_e32 v250, 2, v200
	v_lshrrev_b32_e32 v251, 4, v200
	v_lshlrev_b32_e32 v251, 2, v251
	v_mov_b32_e32 v248, 0x1230
	v_lshrrev_b32_e32 v251, v251, v248
	v_xor_b32_e32 v251, v251, v200
	v_and_b32_e32 v251, 3, v251
	v_lshlrev_b32_e32 v251, 4, v251
	v_lshl_add_u32 v244, v250, 11, v251
	v_add_u32_e32 v245, 0x20000, v244
	v_add_u32_e32 v246, 0x40000, v244
	v_add_u32_e32 v247, 0x60000, v244
	s_mov_b32 s25, 0
	s_add_u32 m0, s25, s24
	s_nop 0
	global_load_lds_dwordx4 v244, s[26:27]
	s_add_u32 m0, m0, 0x1000
	s_nop 0
	global_load_lds_dwordx4 v245, s[26:27]
	s_add_u32 m0, m0, 0x1000
	s_nop 0
	global_load_lds_dwordx4 v244, s[28:29]
	s_add_u32 m0, m0, 0x1000
	s_nop 0
	global_load_lds_dwordx4 v245, s[28:29]
	s_add_u32 m0, m0, 0x1000
	s_nop 0
	global_load_lds_dwordx4 v246, s[28:29]
	s_add_u32 m0, m0, 0x1000
	s_nop 0
	global_load_lds_dwordx4 v247, s[28:29]
	s_add_u32 s26, s26, 64
	s_addc_u32 s27, s27, 0
	s_add_u32 s28, s28, 64
	s_addc_u32 s29, s29, 0
	s_add_u32 s25, s25, 24576
	s_cmp_eq_u32 s25, 73728
	s_cselect_b32 s25, 0, s25
	s_add_u32 m0, s25, s24
	s_nop 0
	global_load_lds_dwordx4 v244, s[26:27]
	s_add_u32 m0, m0, 0x1000
	s_nop 0
	global_load_lds_dwordx4 v245, s[26:27]
	s_add_u32 m0, m0, 0x1000
	s_nop 0
	global_load_lds_dwordx4 v244, s[28:29]
	s_add_u32 m0, m0, 0x1000
	s_nop 0
	global_load_lds_dwordx4 v245, s[28:29]
	s_add_u32 m0, m0, 0x1000
	s_nop 0
	global_load_lds_dwordx4 v246, s[28:29]
	s_add_u32 m0, m0, 0x1000
	s_nop 0
	global_load_lds_dwordx4 v247, s[28:29]
	s_add_u32 s26, s26, 64
	s_addc_u32 s27, s27, 0
	s_add_u32 s28, s28, 64
	s_addc_u32 s29, s29, 0
	s_add_u32 s25, s25, 24576
	s_cmp_eq_u32 s25, 73728
	s_cselect_b32 s25, 0, s25
	s_add_u32 m0, s25, s24
	s_nop 0
	global_load_lds_dwordx4 v244, s[26:27]
	s_add_u32 m0, m0, 0x1000
	s_nop 0
	global_load_lds_dwordx4 v245, s[26:27]
	s_add_u32 m0, m0, 0x1000
	s_nop 0
	global_load_lds_dwordx4 v244, s[28:29]
	s_add_u32 m0, m0, 0x1000
	s_nop 0
	global_load_lds_dwordx4 v245, s[28:29]
	s_add_u32 m0, m0, 0x1000
	s_nop 0
	global_load_lds_dwordx4 v246, s[28:29]
	s_add_u32 m0, m0, 0x1000
	s_nop 0
	global_load_lds_dwordx4 v247, s[28:29]
	s_add_u32 s26, s26, 64
	s_addc_u32 s27, s27, 0
	s_add_u32 s28, s28, 64
	s_addc_u32 s29, s29, 0
	s_add_u32 s25, s25, 24576
	s_cmp_eq_u32 s25, 73728
	s_cselect_b32 s25, 0, s25
	v_mov_b32_e32 v24, 0
	v_mov_b32_e32 v25, v24
	v_mov_b32_e32 v26, v24
	v_mov_b32_e32 v27, v24
	v_mov_b32_e32 v28, v24
	v_mov_b32_e32 v29, v24
	v_mov_b32_e32 v30, v24
	v_mov_b32_e32 v31, v24
	v_mov_b32_e32 v32, v24
	v_mov_b32_e32 v33, v24
	v_mov_b32_e32 v34, v24
	v_mov_b32_e32 v35, v24
	v_mov_b32_e32 v64, v24
	v_mov_b32_e32 v65, v24
	v_mov_b32_e32 v66, v24
	v_mov_b32_e32 v67, v24
	v_mov_b32_e32 v68, v24
	v_mov_b32_e32 v69, v24
	v_mov_b32_e32 v70, v24
	v_mov_b32_e32 v71, v24
	v_mov_b32_e32 v60, v24
	v_mov_b32_e32 v61, v24
	v_mov_b32_e32 v62, v24
	v_mov_b32_e32 v63, v24
	v_mov_b32_e32 v100, v24
	v_mov_b32_e32 v101, v24
	v_mov_b32_e32 v102, v24
	v_mov_b32_e32 v103, v24
	v_mov_b32_e32 v104, v24
	v_mov_b32_e32 v105, v24
	v_mov_b32_e32 v106, v24
	v_mov_b32_e32 v107, v24
	v_mov_b32_e32 v120, v24
	v_mov_b32_e32 v121, v24
	v_mov_b32_e32 v122, v24
	v_mov_b32_e32 v36, v24
	v_mov_b32_e32 v37, v24
	v_mov_b32_e32 v38, v24
	v_mov_b32_e32 v39, v24
	v_mov_b32_e32 v52, v24
	v_mov_b32_e32 v53, v24
	v_mov_b32_e32 v54, v24
	v_mov_b32_e32 v55, v24
	v_mov_b32_e32 v56, v24
	v_mov_b32_e32 v57, v24
	v_mov_b32_e32 v58, v24
	v_mov_b32_e32 v59, v24
	v_mov_b32_e32 v40, v24
	v_mov_b32_e32 v41, v24
	v_mov_b32_e32 v42, v24
	v_mov_b32_e32 v43, v24
	v_mov_b32_e32 v44, v24
	v_mov_b32_e32 v45, v24
	v_mov_b32_e32 v46, v24
	v_mov_b32_e32 v47, v24
	v_mov_b32_e32 v48, v24
	v_mov_b32_e32 v49, v24
	v_mov_b32_e32 v50, v24
	v_mov_b32_e32 v51, v24
	v_mov_b32_e32 v123, v24
	v_mov_b32_e32 v128, v24
	v_mov_b32_e32 v129, v24
	v_mov_b32_e32 v130, v24
	v_mov_b32_e32 v131, v24
	v_mov_b32_e32 v108, v24
	v_mov_b32_e32 v109, v24
	v_mov_b32_e32 v110, v24
	v_mov_b32_e32 v111, v24
	v_mov_b32_e32 v112, v24
	v_mov_b32_e32 v113, v24
	v_mov_b32_e32 v114, v24
	v_mov_b32_e32 v115, v24
	v_mov_b32_e32 v116, v24
	v_mov_b32_e32 v117, v24
	v_mov_b32_e32 v118, v24
	v_mov_b32_e32 v119, v24
	v_mov_b32_e32 v124, v24
	v_mov_b32_e32 v125, v24
	v_mov_b32_e32 v126, v24
	v_mov_b32_e32 v127, v24
	v_mov_b32_e32 v80, v24
	v_mov_b32_e32 v81, v24
	v_mov_b32_e32 v82, v24
	v_mov_b32_e32 v83, v24
	v_mov_b32_e32 v88, v24
	v_mov_b32_e32 v89, v24
	v_mov_b32_e32 v90, v24
	v_mov_b32_e32 v91, v24
	v_mov_b32_e32 v92, v24
	v_mov_b32_e32 v93, v24
	v_mov_b32_e32 v94, v24
	v_mov_b32_e32 v95, v24
	v_mov_b32_e32 v76, v24
	v_mov_b32_e32 v77, v24
	v_mov_b32_e32 v78, v24
	v_mov_b32_e32 v79, v24
	v_mov_b32_e32 v132, v24
	v_mov_b32_e32 v133, v24
	v_mov_b32_e32 v134, v24
	v_mov_b32_e32 v135, v24
	v_mov_b32_e32 v136, v24
	v_mov_b32_e32 v137, v24
	v_mov_b32_e32 v138, v24
	v_mov_b32_e32 v139, v24
	v_mov_b32_e32 v140, v24
	v_mov_b32_e32 v141, v24
	v_mov_b32_e32 v142, v24
	v_mov_b32_e32 v143, v24
	v_mov_b32_e32 v144, v24
	v_mov_b32_e32 v145, v24
	v_mov_b32_e32 v146, v24
	v_mov_b32_e32 v147, v24
	v_mov_b32_e32 v96, v24
	v_mov_b32_e32 v97, v24
	v_mov_b32_e32 v98, v24
	v_mov_b32_e32 v99, v24
	v_mov_b32_e32 v84, v24
	v_mov_b32_e32 v85, v24
	v_mov_b32_e32 v86, v24
	v_mov_b32_e32 v87, v24
	v_mov_b32_e32 v72, v24
	v_mov_b32_e32 v73, v24
	v_mov_b32_e32 v74, v24
	v_mov_b32_e32 v75, v24
	v_mov_b32_e32 v148, v24
	v_mov_b32_e32 v149, v24
	v_mov_b32_e32 v150, v24
	v_mov_b32_e32 v151, v24
	s_waitcnt vmcnt(12)
	s_barrier
	s_mov_b32 s30, 0
	v_add_u32_e32 v248, s30, v155
	v_add_u32_e32 v249, s30, v160
	ds_read_b128 v[186:189], v248
	ds_read_b128 v[212:215], v249 offset:8192
	ds_read_b128 v[190:193], v248 offset:1024
	ds_read_b128 v[216:219], v249 offset:9216
	ds_read_b128 v[194:197], v248 offset:2048
	ds_read_b128 v[220:223], v249 offset:10240
	ds_read_b128 v[208:211], v248 offset:3072
	ds_read_b128 v[224:227], v249 offset:11264
	ds_read_b128 v[228:231], v249 offset:12288
	ds_read_b128 v[232:235], v249 offset:13312
	ds_read_b128 v[236:239], v249 offset:14336
	ds_read_b128 v[240:243], v249 offset:15360
	s_add_u32 s30, s30, 24576
	s_cmp_eq_u32 s30, 73728
	s_cselect_b32 s30, 0, s30
	s_waitcnt vmcnt(6)
	s_waitcnt lgkmcnt(0)
	s_barrier
	s_mov_b32 s31, 14
.Lgm3_loop:
	v_add_u32_e32 v248, s30, v155
	v_add_u32_e32 v249, s30, v160
	v_mfma_f32_16x16x32_bf16 v[128:131], v[212:215], v[186:189], v[128:131]
	ds_read_b128 v[0:3], v248
	v_mfma_f32_16x16x32_bf16 v[68:71], v[212:215], v[190:193], v[68:71]
	ds_read_b128 v[16:19], v249 offset:8192
	v_mfma_f32_16x16x32_bf16 v[108:111], v[212:215], v[194:197], v[108:111]
	ds_read_b128 v[4:7], v248 offset:1024
	v_mfma_f32_16x16x32_bf16 v[132:135], v[212:215], v[208:211], v[132:135]
	ds_read_b128 v[20:23], v249 offset:9216
	v_mfma_f32_16x16x32_bf16 v[120:123], v[216:219], v[186:189], v[120:123]
	ds_read_b128 v[8:11], v248 offset:2048
	v_mfma_f32_16x16x32_bf16 v[64:67], v[216:219], v[190:193], v[64:67]
	ds_read_b128 v[162:165], v249 offset:10240
	v_mfma_f32_16x16x32_bf16 v[112:115], v[216:219], v[194:197], v[112:115]
	ds_read_b128 v[12:15], v248 offset:3072
	v_mfma_f32_16x16x32_bf16 v[136:139], v[216:219], v[208:211], v[136:139]
	ds_read_b128 v[166:169], v249 offset:11264
	v_mfma_f32_16x16x32_bf16 v[104:107], v[220:223], v[186:189], v[104:107]
	ds_read_b128 v[170:173], v249 offset:12288
	v_mfma_f32_16x16x32_bf16 v[56:59], v[220:223], v[190:193], v[56:59]
	ds_read_b128 v[174:177], v249 offset:13312
	v_mfma_f32_16x16x32_bf16 v[116:119], v[220:223], v[194:197], v[116:119]
	ds_read_b128 v[178:181], v249 offset:14336
	v_mfma_f32_16x16x32_bf16 v[140:143], v[220:223], v[208:211], v[140:143]
	ds_read_b128 v[182:185], v249 offset:15360
	s_add_u32 m0, s25, s24
	v_mfma_f32_16x16x32_bf16 v[100:103], v[224:227], v[186:189], v[100:103]
	global_load_lds_dwordx4 v244, s[26:27]
	v_mfma_f32_16x16x32_bf16 v[52:55], v[224:227], v[190:193], v[52:55]
	v_mfma_f32_16x16x32_bf16 v[124:127], v[224:227], v[194:197], v[124:127]
	s_add_u32 m0, m0, 0x1000
	v_mfma_f32_16x16x32_bf16 v[144:147], v[224:227], v[208:211], v[144:147]
	global_load_lds_dwordx4 v245, s[26:27]
	v_mfma_f32_16x16x32_bf16 v[60:63], v[228:231], v[186:189], v[60:63]
	v_mfma_f32_16x16x32_bf16 v[36:39], v[228:231], v[190:193], v[36:39]
	s_add_u32 m0, m0, 0x1000
	v_mfma_f32_16x16x32_bf16 v[80:83], v[228:231], v[194:197], v[80:83]
	global_load_lds_dwordx4 v244, s[28:29]
	v_mfma_f32_16x16x32_bf16 v[96:99], v[228:231], v[208:211], v[96:99]
	v_mfma_f32_16x16x32_bf16 v[48:51], v[232:235], v[186:189], v[48:51]
	s_add_u32 m0, m0, 0x1000
	v_mfma_f32_16x16x32_bf16 v[32:35], v[232:235], v[190:193], v[32:35]
	global_load_lds_dwordx4 v245, s[28:29]
	v_mfma_f32_16x16x32_bf16 v[88:91], v[232:235], v[194:197], v[88:91]
	v_mfma_f32_16x16x32_bf16 v[84:87], v[232:235], v[208:211], v[84:87]
	s_add_u32 m0, m0, 0x1000
	v_mfma_f32_16x16x32_bf16 v[44:47], v[236:239], v[186:189], v[44:47]
	global_load_lds_dwordx4 v246, s[28:29]
	v_mfma_f32_16x16x32_bf16 v[28:31], v[236:239], v[190:193], v[28:31]
	v_mfma_f32_16x16x32_bf16 v[92:95], v[236:239], v[194:197], v[92:95]
	s_add_u32 m0, m0, 0x1000
	v_mfma_f32_16x16x32_bf16 v[72:75], v[236:239], v[208:211], v[72:75]
	global_load_lds_dwordx4 v247, s[28:29]
	v_mfma_f32_16x16x32_bf16 v[40:43], v[240:243], v[186:189], v[40:43]
	v_mfma_f32_16x16x32_bf16 v[24:27], v[240:243], v[190:193], v[24:27]
	v_mfma_f32_16x16x32_bf16 v[76:79], v[240:243], v[194:197], v[76:79]
	v_mfma_f32_16x16x32_bf16 v[148:151], v[240:243], v[208:211], v[148:151]
	s_add_u32 s26, s26, 64
	s_addc_u32 s27, s27, 0
	s_add_u32 s28, s28, 64
	s_addc_u32 s29, s29, 0
	s_add_u32 s25, s25, 24576
	s_cmp_eq_u32 s25, 73728
	s_cselect_b32 s25, 0, s25
	s_add_u32 s30, s30, 24576
	s_cmp_eq_u32 s30, 73728
	s_cselect_b32 s30, 0, s30
	s_waitcnt vmcnt(6)
	s_waitcnt lgkmcnt(0)
	s_barrier
	v_add_u32_e32 v248, s30, v155
	v_add_u32_e32 v249, s30, v160
	v_mfma_f32_16x16x32_bf16 v[128:131], v[16:19], v[0:3], v[128:131]
	ds_read_b128 v[186:189], v248
	v_mfma_f32_16x16x32_bf16 v[68:71], v[16:19], v[4:7], v[68:71]
	ds_read_b128 v[212:215], v249 offset:8192
	v_mfma_f32_16x16x32_bf16 v[108:111], v[16:19], v[8:11], v[108:111]
	ds_read_b128 v[190:193], v248 offset:1024
	v_mfma_f32_16x16x32_bf16 v[132:135], v[16:19], v[12:15], v[132:135]
	ds_read_b128 v[216:219], v249 offset:9216
	v_mfma_f32_16x16x32_bf16 v[120:123], v[20:23], v[0:3], v[120:123]
	ds_read_b128 v[194:197], v248 offset:2048
	v_mfma_f32_16x16x32_bf16 v[64:67], v[20:23], v[4:7], v[64:67]
	ds_read_b128 v[220:223], v249 offset:10240
	v_mfma_f32_16x16x32_bf16 v[112:115], v[20:23], v[8:11], v[112:115]
	ds_read_b128 v[208:211], v248 offset:3072
	v_mfma_f32_16x16x32_bf16 v[136:139], v[20:23], v[12:15], v[136:139]
	ds_read_b128 v[224:227], v249 offset:11264
	v_mfma_f32_16x16x32_bf16 v[104:107], v[162:165], v[0:3], v[104:107]
	ds_read_b128 v[228:231], v249 offset:12288
	v_mfma_f32_16x16x32_bf16 v[56:59], v[162:165], v[4:7], v[56:59]
	ds_read_b128 v[232:235], v249 offset:13312
	v_mfma_f32_16x16x32_bf16 v[116:119], v[162:165], v[8:11], v[116:119]
	ds_read_b128 v[236:239], v249 offset:14336
	v_mfma_f32_16x16x32_bf16 v[140:143], v[162:165], v[12:15], v[140:143]
	ds_read_b128 v[240:243], v249 offset:15360
	s_add_u32 m0, s25, s24
	v_mfma_f32_16x16x32_bf16 v[100:103], v[166:169], v[0:3], v[100:103]
	global_load_lds_dwordx4 v244, s[26:27]
	v_mfma_f32_16x16x32_bf16 v[52:55], v[166:169], v[4:7], v[52:55]
	v_mfma_f32_16x16x32_bf16 v[124:127], v[166:169], v[8:11], v[124:127]
	s_add_u32 m0, m0, 0x1000
	v_mfma_f32_16x16x32_bf16 v[144:147], v[166:169], v[12:15], v[144:147]
	global_load_lds_dwordx4 v245, s[26:27]
	v_mfma_f32_16x16x32_bf16 v[60:63], v[170:173], v[0:3], v[60:63]
	v_mfma_f32_16x16x32_bf16 v[36:39], v[170:173], v[4:7], v[36:39]
	s_add_u32 m0, m0, 0x1000
	v_mfma_f32_16x16x32_bf16 v[80:83], v[170:173], v[8:11], v[80:83]
	global_load_lds_dwordx4 v244, s[28:29]
	v_mfma_f32_16x16x32_bf16 v[96:99], v[170:173], v[12:15], v[96:99]
	v_mfma_f32_16x16x32_bf16 v[48:51], v[174:177], v[0:3], v[48:51]
	s_add_u32 m0, m0, 0x1000
	v_mfma_f32_16x16x32_bf16 v[32:35], v[174:177], v[4:7], v[32:35]
	global_load_lds_dwordx4 v245, s[28:29]
	v_mfma_f32_16x16x32_bf16 v[88:91], v[174:177], v[8:11], v[88:91]
	v_mfma_f32_16x16x32_bf16 v[84:87], v[174:177], v[12:15], v[84:87]
	s_add_u32 m0, m0, 0x1000
	v_mfma_f32_16x16x32_bf16 v[44:47], v[178:181], v[0:3], v[44:47]
	global_load_lds_dwordx4 v246, s[28:29]
	v_mfma_f32_16x16x32_bf16 v[28:31], v[178:181], v[4:7], v[28:31]
	v_mfma_f32_16x16x32_bf16 v[92:95], v[178:181], v[8:11], v[92:95]
	s_add_u32 m0, m0, 0x1000
	v_mfma_f32_16x16x32_bf16 v[72:75], v[178:181], v[12:15], v[72:75]
	global_load_lds_dwordx4 v247, s[28:29]
	v_mfma_f32_16x16x32_bf16 v[40:43], v[182:185], v[0:3], v[40:43]
	v_mfma_f32_16x16x32_bf16 v[24:27], v[182:185], v[4:7], v[24:27]
	v_mfma_f32_16x16x32_bf16 v[76:79], v[182:185], v[8:11], v[76:79]
	v_mfma_f32_16x16x32_bf16 v[148:151], v[182:185], v[12:15], v[148:151]
	s_add_u32 s26, s26, 64
	s_addc_u32 s27, s27, 0
	s_add_u32 s28, s28, 64
	s_addc_u32 s29, s29, 0
	s_add_u32 s25, s25, 24576
	s_cmp_eq_u32 s25, 73728
	s_cselect_b32 s25, 0, s25
	s_add_u32 s30, s30, 24576
	s_cmp_eq_u32 s30, 73728
	s_cselect_b32 s30, 0, s30
	s_waitcnt vmcnt(6)
	s_waitcnt lgkmcnt(0)
	s_barrier
	s_sub_u32 s31, s31, 1
	s_cmp_lg_u32 s31, 0
	s_cbranch_scc1 .Lgm3_loop
	v_add_u32_e32 v248, s30, v155
	v_add_u32_e32 v249, s30, v160
	v_mfma_f32_16x16x32_bf16 v[128:131], v[212:215], v[186:189], v[128:131]
	ds_read_b128 v[0:3], v248
	v_mfma_f32_16x16x32_bf16 v[68:71], v[212:215], v[190:193], v[68:71]
	ds_read_b128 v[16:19], v249 offset:8192
	v_mfma_f32_16x16x32_bf16 v[108:111], v[212:215], v[194:197], v[108:111]
	ds_read_b128 v[4:7], v248 offset:1024
	v_mfma_f32_16x16x32_bf16 v[132:135], v[212:215], v[208:211], v[132:135]
	ds_read_b128 v[20:23], v249 offset:9216
	v_mfma_f32_16x16x32_bf16 v[120:123], v[216:219], v[186:189], v[120:123]
	ds_read_b128 v[8:11], v248 offset:2048
	v_mfma_f32_16x16x32_bf16 v[64:67], v[216:219], v[190:193], v[64:67]
	ds_read_b128 v[162:165], v249 offset:10240
	v_mfma_f32_16x16x32_bf16 v[112:115], v[216:219], v[194:197], v[112:115]
	ds_read_b128 v[12:15], v248 offset:3072
	v_mfma_f32_16x16x32_bf16 v[136:139], v[216:219], v[208:211], v[136:139]
	ds_read_b128 v[166:169], v249 offset:11264
	v_mfma_f32_16x16x32_bf16 v[104:107], v[220:223], v[186:189], v[104:107]
	ds_read_b128 v[170:173], v249 offset:12288
	v_mfma_f32_16x16x32_bf16 v[56:59], v[220:223], v[190:193], v[56:59]
	ds_read_b128 v[174:177], v249 offset:13312
	v_mfma_f32_16x16x32_bf16 v[116:119], v[220:223], v[194:197], v[116:119]
	ds_read_b128 v[178:181], v249 offset:14336
	v_mfma_f32_16x16x32_bf16 v[140:143], v[220:223], v[208:211], v[140:143]
	ds_read_b128 v[182:185], v249 offset:15360
	s_add_u32 m0, s25, s24
	v_mfma_f32_16x16x32_bf16 v[100:103], v[224:227], v[186:189], v[100:103]
	global_load_lds_dwordx4 v244, s[26:27]
	v_mfma_f32_16x16x32_bf16 v[52:55], v[224:227], v[190:193], v[52:55]
	v_mfma_f32_16x16x32_bf16 v[124:127], v[224:227], v[194:197], v[124:127]
	s_add_u32 m0, m0, 0x1000
	v_mfma_f32_16x16x32_bf16 v[144:147], v[224:227], v[208:211], v[144:147]
	global_load_lds_dwordx4 v245, s[26:27]
	v_mfma_f32_16x16x32_bf16 v[60:63], v[228:231], v[186:189], v[60:63]
	v_mfma_f32_16x16x32_bf16 v[36:39], v[228:231], v[190:193], v[36:39]
	s_add_u32 m0, m0, 0x1000
	v_mfma_f32_16x16x32_bf16 v[80:83], v[228:231], v[194:197], v[80:83]
	global_load_lds_dwordx4 v244, s[28:29]
	v_mfma_f32_16x16x32_bf16 v[96:99], v[228:231], v[208:211], v[96:99]
	v_mfma_f32_16x16x32_bf16 v[48:51], v[232:235], v[186:189], v[48:51]
	s_add_u32 m0, m0, 0x1000
	v_mfma_f32_16x16x32_bf16 v[32:35], v[232:235], v[190:193], v[32:35]
	global_load_lds_dwordx4 v245, s[28:29]
	v_mfma_f32_16x16x32_bf16 v[88:91], v[232:235], v[194:197], v[88:91]
	v_mfma_f32_16x16x32_bf16 v[84:87], v[232:235], v[208:211], v[84:87]
	s_add_u32 m0, m0, 0x1000
	v_mfma_f32_16x16x32_bf16 v[44:47], v[236:239], v[186:189], v[44:47]
	global_load_lds_dwordx4 v246, s[28:29]
	v_mfma_f32_16x16x32_bf16 v[28:31], v[236:239], v[190:193], v[28:31]
	v_mfma_f32_16x16x32_bf16 v[92:95], v[236:239], v[194:197], v[92:95]
	s_add_u32 m0, m0, 0x1000
	v_mfma_f32_16x16x32_bf16 v[72:75], v[236:239], v[208:211], v[72:75]
	global_load_lds_dwordx4 v247, s[28:29]
	v_mfma_f32_16x16x32_bf16 v[40:43], v[240:243], v[186:189], v[40:43]
	v_mfma_f32_16x16x32_bf16 v[24:27], v[240:243], v[190:193], v[24:27]
	v_mfma_f32_16x16x32_bf16 v[76:79], v[240:243], v[194:197], v[76:79]
	v_mfma_f32_16x16x32_bf16 v[148:151], v[240:243], v[208:211], v[148:151]
	s_add_u32 s26, s26, 64
	s_addc_u32 s27, s27, 0
	s_add_u32 s28, s28, 64
	s_addc_u32 s29, s29, 0
	s_add_u32 s25, s25, 24576
	s_cmp_eq_u32 s25, 73728
	s_cselect_b32 s25, 0, s25
	s_add_u32 s30, s30, 24576
	s_cmp_eq_u32 s30, 73728
	s_cselect_b32 s30, 0, s30
	s_waitcnt vmcnt(6)
	s_waitcnt lgkmcnt(0)
	s_barrier
	v_mfma_f32_16x16x32_bf16 v[128:131], v[16:19], v[0:3], v[128:131]
	v_mfma_f32_16x16x32_bf16 v[68:71], v[16:19], v[4:7], v[68:71]
	v_mfma_f32_16x16x32_bf16 v[108:111], v[16:19], v[8:11], v[108:111]
	v_mfma_f32_16x16x32_bf16 v[132:135], v[16:19], v[12:15], v[132:135]
	v_mfma_f32_16x16x32_bf16 v[120:123], v[20:23], v[0:3], v[120:123]
	v_mfma_f32_16x16x32_bf16 v[64:67], v[20:23], v[4:7], v[64:67]
	v_mfma_f32_16x16x32_bf16 v[112:115], v[20:23], v[8:11], v[112:115]
	v_mfma_f32_16x16x32_bf16 v[136:139], v[20:23], v[12:15], v[136:139]
	v_mfma_f32_16x16x32_bf16 v[104:107], v[162:165], v[0:3], v[104:107]
	v_mfma_f32_16x16x32_bf16 v[56:59], v[162:165], v[4:7], v[56:59]
	v_mfma_f32_16x16x32_bf16 v[116:119], v[162:165], v[8:11], v[116:119]
	v_mfma_f32_16x16x32_bf16 v[140:143], v[162:165], v[12:15], v[140:143]
	v_mfma_f32_16x16x32_bf16 v[100:103], v[166:169], v[0:3], v[100:103]
	v_mfma_f32_16x16x32_bf16 v[52:55], v[166:169], v[4:7], v[52:55]
	v_mfma_f32_16x16x32_bf16 v[124:127], v[166:169], v[8:11], v[124:127]
	v_mfma_f32_16x16x32_bf16 v[144:147], v[166:169], v[12:15], v[144:147]
	v_mfma_f32_16x16x32_bf16 v[60:63], v[170:173], v[0:3], v[60:63]
	v_mfma_f32_16x16x32_bf16 v[36:39], v[170:173], v[4:7], v[36:39]
	v_mfma_f32_16x16x32_bf16 v[80:83], v[170:173], v[8:11], v[80:83]
	v_mfma_f32_16x16x32_bf16 v[96:99], v[170:173], v[12:15], v[96:99]
	v_mfma_f32_16x16x32_bf16 v[48:51], v[174:177], v[0:3], v[48:51]
	v_mfma_f32_16x16x32_bf16 v[32:35], v[174:177], v[4:7], v[32:35]
	v_mfma_f32_16x16x32_bf16 v[88:91], v[174:177], v[8:11], v[88:91]
	v_mfma_f32_16x16x32_bf16 v[84:87], v[174:177], v[12:15], v[84:87]
	v_mfma_f32_16x16x32_bf16 v[44:47], v[178:181], v[0:3], v[44:47]
	v_mfma_f32_16x16x32_bf16 v[28:31], v[178:181], v[4:7], v[28:31]
	v_mfma_f32_16x16x32_bf16 v[92:95], v[178:181], v[8:11], v[92:95]
	v_mfma_f32_16x16x32_bf16 v[72:75], v[178:181], v[12:15], v[72:75]
	v_mfma_f32_16x16x32_bf16 v[40:43], v[182:185], v[0:3], v[40:43]
	v_mfma_f32_16x16x32_bf16 v[24:27], v[182:185], v[4:7], v[24:27]
	v_mfma_f32_16x16x32_bf16 v[76:79], v[182:185], v[8:11], v[76:79]
	v_mfma_f32_16x16x32_bf16 v[148:151], v[182:185], v[12:15], v[148:151]
	s_waitcnt vmcnt(0)
	s_waitcnt lgkmcnt(0)
	s_barrier
	ds_read_b128 v[156:159], v160 offset:8192
	ds_read_b128 v[162:165], v160 offset:9216
	ds_read_b128 v[166:169], v155
	ds_read_b128 v[170:173], v155 offset:1024
	ds_read_b128 v[174:177], v160 offset:10240
	s_waitcnt lgkmcnt(2)
	v_mfma_f32_16x16x32_bf16 v[178:181], v[162:165], v[166:169], v[120:123]
	s_nop 2
	ds_read_b128 v[120:123], v160 offset:11264
	ds_read_b128 v[182:185], v155 offset:2048
	ds_read_b128 v[186:189], v155 offset:3072
	s_waitcnt lgkmcnt(1)
	v_mfma_f32_16x16x32_bf16 v[190:193], v[156:159], v[182:185], v[108:111]
	s_nop 2
	ds_read_b128 v[108:111], v160 offset:12288
	v_mfma_f32_16x16x32_bf16 v[100:103], v[120:123], v[166:169], v[100:103]
	v_mfma_f32_16x16x32_bf16 v[52:55], v[120:123], v[170:173], v[52:55]
	v_mfma_f32_16x16x32_bf16 v[194:197], v[162:165], v[182:185], v[112:115]
	v_mfma_f32_16x16x32_bf16 v[208:211], v[174:177], v[182:185], v[116:119]
	s_nop 1
	ds_read_b128 v[112:115], v160 offset:13312
	v_mfma_f32_16x16x32_bf16 v[212:215], v[120:123], v[182:185], v[124:127]
	ds_read_b128 v[116:119], v160 offset:14336
	s_waitcnt lgkmcnt(3)
	v_mfma_f32_16x16x32_bf16 v[144:147], v[120:123], v[186:189], v[144:147]
	ds_read_b128 v[120:123], v160 offset:15360
	s_waitcnt vmcnt(4)
	s_waitcnt vmcnt(3)
	s_waitcnt vmcnt(2)
	s_waitcnt vmcnt(1)
	s_waitcnt vmcnt(0)
	s_waitcnt lgkmcnt(0)
	s_barrier
	ds_read_b128 v[0:3], v160 offset:32768
	v_mfma_f32_16x16x32_bf16 v[128:131], v[156:159], v[166:169], v[128:131]
	ds_read_b128 v[4:7], v160 offset:33792
	ds_read_b128 v[8:11], v155 offset:24576
	ds_read_b128 v[16:19], v155 offset:25600
	ds_read_b128 v[20:23], v160 offset:34816
	v_mfma_f32_16x16x32_bf16 v[68:71], v[156:159], v[170:173], v[68:71]
	v_mfma_f32_16x16x32_bf16 v[64:67], v[162:165], v[170:173], v[64:67]
	v_mfma_f32_16x16x32_bf16 v[56:59], v[174:177], v[170:173], v[56:59]
	v_mfma_f32_16x16x32_bf16 v[40:43], v[120:123], v[166:169], v[40:43]
	v_mfma_f32_16x16x32_bf16 v[36:39], v[108:111], v[170:173], v[36:39]
	v_mfma_f32_16x16x32_bf16 v[32:35], v[112:115], v[170:173], v[32:35]
	v_mfma_f32_16x16x32_bf16 v[28:31], v[116:119], v[170:173], v[28:31]
	v_mfma_f32_16x16x32_bf16 v[24:27], v[120:123], v[170:173], v[24:27]
	v_mfma_f32_16x16x32_bf16 v[170:173], v[120:123], v[182:185], v[76:79]
	v_mfma_f32_16x16x32_bf16 v[12:15], v[120:123], v[186:189], v[148:151]
	s_waitcnt lgkmcnt(2)
	v_mfma_f32_16x16x32_bf16 v[120:123], v[0:3], v[8:11], v[128:131]
	s_nop 2
	ds_read_b128 v[128:131], v160 offset:35840
	v_mfma_f32_16x16x32_bf16 v[124:127], v[4:7], v[8:11], v[178:181]
	ds_read_b128 v[148:151], v155 offset:26624
	s_nop 1
	ds_read_b128 v[178:181], v155 offset:27648
	v_mfma_f32_16x16x32_bf16 v[104:107], v[174:177], v[166:169], v[104:107]
	v_mfma_f32_16x16x32_bf16 v[132:135], v[156:159], v[186:189], v[132:135]
	v_mfma_f32_16x16x32_bf16 v[136:139], v[162:165], v[186:189], v[136:139]
	v_mfma_f32_16x16x32_bf16 v[140:143], v[174:177], v[186:189], v[140:143]
	v_mfma_f32_16x16x32_bf16 v[60:63], v[108:111], v[166:169], v[60:63]
	v_mfma_f32_16x16x32_bf16 v[48:51], v[112:115], v[166:169], v[48:51]
	v_mfma_f32_16x16x32_bf16 v[44:47], v[116:119], v[166:169], v[44:47]
	v_mfma_f32_16x16x32_bf16 v[156:159], v[108:111], v[182:185], v[80:83]
	v_mfma_f32_16x16x32_bf16 v[162:165], v[112:115], v[182:185], v[88:91]
	v_mfma_f32_16x16x32_bf16 v[166:169], v[116:119], v[182:185], v[92:95]
	v_mfma_f32_16x16x32_bf16 v[174:177], v[108:111], v[186:189], v[96:99]
	v_mfma_f32_16x16x32_bf16 v[182:185], v[112:115], v[186:189], v[84:87]
	v_mfma_f32_16x16x32_bf16 v[216:219], v[116:119], v[186:189], v[72:75]
	s_waitcnt lgkmcnt(3)
	v_mfma_f32_16x16x32_bf16 v[116:119], v[20:23], v[8:11], v[104:107]
	s_waitcnt lgkmcnt(2)
	v_mfma_f32_16x16x32_bf16 v[112:115], v[128:131], v[8:11], v[100:103]
	v_mfma_f32_16x16x32_bf16 v[108:111], v[0:3], v[16:19], v[68:71]
	v_mfma_f32_16x16x32_bf16 v[104:107], v[4:7], v[16:19], v[64:67]
	v_mfma_f32_16x16x32_bf16 v[96:99], v[128:131], v[16:19], v[52:55]
	s_waitcnt lgkmcnt(1)
	v_mfma_f32_16x16x32_bf16 v[92:95], v[0:3], v[148:151], v[190:193]
	v_mfma_f32_16x16x32_bf16 v[88:91], v[4:7], v[148:151], v[194:197]
	v_mfma_f32_16x16x32_bf16 v[80:83], v[128:131], v[148:151], v[212:215]
	s_waitcnt lgkmcnt(0)
	v_mfma_f32_16x16x32_bf16 v[76:79], v[0:3], v[178:181], v[132:135]
	ds_read_b128 v[0:3], v160 offset:36864
	v_mfma_f32_16x16x32_bf16 v[72:75], v[4:7], v[178:181], v[136:139]
	ds_read_b128 v[4:7], v160 offset:37888
	v_mfma_f32_16x16x32_bf16 v[68:71], v[128:131], v[178:181], v[144:147]
	ds_read_b128 v[130:133], v160 offset:38912
	ds_read_b128 v[134:137], v160 offset:39936
	s_waitcnt lgkmcnt(0)
	v_mfma_f32_16x16x32_bf16 v[100:103], v[20:23], v[16:19], v[56:59]
	s_barrier
	v_mov_b32 v128, v198
	v_mfma_f32_16x16x32_bf16 v[52:55], v[0:3], v[8:11], v[60:63]
	v_and_b32_e32 v129, 63, v128
	v_mfma_f32_16x16x32_bf16 v[56:59], v[4:7], v[8:11], v[48:51]
	v_mfma_f32_16x16x32_bf16 v[60:63], v[130:133], v[8:11], v[44:47]
	v_mfma_f32_16x16x32_bf16 v[48:51], v[134:137], v[8:11], v[40:43]
	v_lshrrev_b32_e32 v8, 1, v128
	v_mfma_f32_16x16x32_bf16 v[84:87], v[20:23], v[148:151], v[208:211]
	v_mfma_f32_16x16x32_bf16 v[64:67], v[20:23], v[178:181], v[140:143]
	v_mfma_f32_16x16x32_bf16 v[44:47], v[0:3], v[16:19], v[36:39]
	v_mfma_f32_16x16x32_bf16 v[40:43], v[4:7], v[16:19], v[32:35]
	v_mfma_f32_16x16x32_bf16 v[36:39], v[130:133], v[16:19], v[28:31]
	v_mfma_f32_16x16x32_bf16 v[32:35], v[134:137], v[16:19], v[24:27]
	v_mfma_f32_16x16x32_bf16 v[28:31], v[0:3], v[148:151], v[156:159]
	v_mfma_f32_16x16x32_bf16 v[20:23], v[4:7], v[148:151], v[162:165]
	v_mfma_f32_16x16x32_bf16 v[16:19], v[130:133], v[148:151], v[166:169]
	v_mfma_f32_16x16x32_bf16 v[24:27], v[134:137], v[148:151], v[170:173]
	v_and_or_b32 v148, v8, 64, s4
	v_lshlrev_b32_e32 v8, 1, v128
	v_and_b32_e32 v8, 0x80, v8
	v_mfma_f32_16x16x32_bf16 v[0:3], v[0:3], v[178:181], v[174:177]
	v_or_b32_e32 v151, s17, v8
	v_lshrrev_b32_e32 v150, 6, v151
	s_movk_i32 s4, 0xc01
	v_mfma_f32_16x16x32_bf16 v[4:7], v[4:7], v[178:181], v[182:185]
	v_and_b32_e32 v149, 15, v128
	v_cmp_gt_u32_e32 vcc, s4, v151
	v_and_b32_e32 v156, 60, v150
	v_mfma_f32_16x16x32_bf16 v[8:11], v[130:133], v[178:181], v[216:219]
	v_mfma_f32_16x16x32_bf16 v[12:15], v[134:137], v[178:181], v[12:15]
	s_and_saveexec_b64 s[20:21], vcc
	s_cbranch_execz .LBB0_591
	v_cmp_ne_u32_e32 vcc, 8, v156
	s_and_saveexec_b64 s[6:7], vcc
	s_xor_b64 s[6:7], exec, s[6:7]
	s_cbranch_execz .LBB0_485
	s_and_b32 s4, s17, 0xe00
	s_cmpk_eq_i32 s4, 0x400
	s_cbranch_scc1 .LBB0_616
	v_cmp_lt_i32_e32 vcc, 31, v150
	s_mov_b64 s[34:35], 0
	s_mov_b64 s[28:29], 0
	s_and_saveexec_b64 s[4:5], vcc
	s_xor_b64 s[4:5], exec, s[4:5]
	s_cbranch_execz .LBB0_462
	v_cmp_lt_i32_e32 vcc, 33, v150
	s_mov_b64 s[22:23], 0
	s_mov_b64 s[24:25], 0
	s_and_saveexec_b64 s[26:27], vcc
	s_xor_b64 s[26:27], exec, s[26:27]
	s_cbranch_execz .LBB0_459
	v_cmp_eq_u32_e32 vcc, 34, v150
	s_mov_b64 s[24:25], -1
	s_and_saveexec_b64 s[28:29], vcc
	s_xor_b64 s[24:25], exec, -1
	s_or_b64 exec, exec, s[28:29]
	s_and_b64 s[24:25], s[24:25], exec

	.amdhsa_kernel _Z10fwd_kernel6Paramsii
		.amdhsa_group_segment_fixed_size 73984
		.amdhsa_private_segment_fixed_size 0
		.amdhsa_kernarg_size 416
		.amdhsa_user_sgpr_count 2
		.amdhsa_user_sgpr_dispatch_ptr 0
		.amdhsa_user_sgpr_queue_ptr 0
		.amdhsa_user_sgpr_kernarg_segment_ptr 1
		.amdhsa_user_sgpr_dispatch_id 0
		.amdhsa_user_sgpr_kernarg_preload_length 0
		.amdhsa_user_sgpr_kernarg_preload_offset 0
		.amdhsa_user_sgpr_private_segment_size 0
		.amdhsa_uses_dynamic_stack 0
		.amdhsa_enable_private_segment 0
		.amdhsa_system_sgpr_workgroup_id_x 1
		.amdhsa_system_sgpr_workgroup_id_y 0
		.amdhsa_system_sgpr_workgroup_id_z 0
		.amdhsa_system_sgpr_workgroup_info 0
		.amdhsa_system_vgpr_workitem_id 2
		.amdhsa_next_free_vgpr 254
		.amdhsa_next_free_sgpr 100
		.amdhsa_accum_offset 256
		.amdhsa_reserve_vcc 1
		.amdhsa_float_round_mode_32 0
		.amdhsa_float_round_mode_16_64 0
		.amdhsa_float_denorm_mode_32 3
		.amdhsa_float_denorm_mode_16_64 3
		.amdhsa_dx10_clamp 1
		.amdhsa_ieee_mode 1
		.amdhsa_fp16_overflow 0
		.amdhsa_tg_split 0
		.amdhsa_exception_fp_ieee_invalid_op 0
		.amdhsa_exception_fp_denorm_src 0
		.amdhsa_exception_fp_ieee_div_zero 0
		.amdhsa_exception_fp_ieee_overflow 0
		.amdhsa_exception_fp_ieee_underflow 0
		.amdhsa_exception_fp_ieee_inexact 0
		.amdhsa_exception_int_div_zero 0
	.end_amdhsa_kernel

amdhsa.kernels:
  - .agpr_count:     0
    .args:
      - .offset:         0
        .size:           152
        .value_kind:     by_value
      - .offset:         152
        .size:           4
        .value_kind:     by_value
      - .offset:         156
        .size:           4
        .value_kind:     by_value
      - .offset:         160
        .size:           4
        .value_kind:     hidden_block_count_x
      - .offset:         164
        .size:           4
        .value_kind:     hidden_block_count_y
      - .offset:         168
        .size:           4
        .value_kind:     hidden_block_count_z
      - .offset:         172
        .size:           2
        .value_kind:     hidden_group_size_x
      - .offset:         174
        .size:           2
        .value_kind:     hidden_group_size_y
      - .offset:         176
        .size:           2
        .value_kind:     hidden_group_size_z
      - .offset:         178
        .size:           2
        .value_kind:     hidden_remainder_x
      - .offset:         180
        .size:           2
        .value_kind:     hidden_remainder_y
      - .offset:         182
        .size:           2
        .value_kind:     hidden_remainder_z
      - .offset:         200
        .size:           8
        .value_kind:     hidden_global_offset_x
      - .offset:         208
        .size:           8
        .value_kind:     hidden_global_offset_y
      - .offset:         216
        .size:           8
        .value_kind:     hidden_global_offset_z
      - .offset:         224
        .size:           2
        .value_kind:     hidden_grid_dims
      - .offset:         248
        .size:           8
        .value_kind:     hidden_multigrid_sync_arg
    .group_segment_fixed_size: 73984
    .kernarg_segment_align: 8
    .kernarg_segment_size: 416
    .language:       OpenCL C
    .language_version:
      - 2
      - 0
    .max_flat_workgroup_size: 256
    .name:           _Z10fwd_kernel6Paramsii
    .private_segment_fixed_size: 0
    .sgpr_count:     106
    .sgpr_spill_count: 111
    .symbol:         _Z10fwd_kernel6Paramsii.kd
    .uniform_work_group_size: 1
    .uses_dynamic_stack: false
    .vgpr_count:     254
    .vgpr_spill_count: 0
    .wavefront_size: 64
